# in-proj: last unit's epilogue (all four variants) duplicated with write-through stores, on top of loop-edge + v_mov_b64 stack
# speedup vs baseline: 1.0064x; 1.0064x over previous
.LBB0_568:
	s_and_b64 vcc, exec, s[42:43]
	s_cbranch_vccz .Llast_inp
	v_lshl_add_u32 v208, s27, 8, v192
	s_cmp_gt_i32 s26, 7
	s_mov_b64 s[6:7], -1
	s_mov_b64 s[56:57], 0x40000
	s_mov_b32 s58, 0x20000
	s_cbranch_scc0 .LBB0_578
	s_cmp_gt_u32 s26, 19
	s_cbranch_scc0 .LBB0_571
	v_mul_f32_e32 v134, 0xbfb8aa3b, v120
	v_exp_f32_e32 v134, v134
	v_mul_f32_e32 v138, 0xbfb8aa3b, v121
	v_mul_f32_e32 v132, 0xbfb8aa3b, v128
	v_exp_f32_e32 v138, v138
	v_add_f32_e32 v134, 1.0, v134
	v_rcp_f32_e32 v134, v134
	v_exp_f32_e32 v132, v132
	v_mul_f32_e32 v142, 0xbfb8aa3b, v122
	v_add_f32_e32 v138, 1.0, v138
	v_max_f32_e32 v136, 0x29e12e13, v134
	v_mul_f32_e32 v134, 0xbfb8aa3b, v116
	v_exp_f32_e32 v134, v134
	v_exp_f32_e32 v142, v142
	v_add_f32_e32 v132, 1.0, v132
	v_rcp_f32_e32 v138, v138
	v_add_f32_e32 v134, 1.0, v134
	v_rcp_f32_e32 v134, v134
	v_rcp_f32_e32 v132, v132
	v_rcp_f32_e32 v148, v136
	v_mul_f32_e32 v146, 0xbfb8aa3b, v123
	v_max_f32_e32 v137, 0x29e12e13, v134
	v_mul_f32_e32 v134, 0xbfb8aa3b, v129
	v_exp_f32_e32 v134, v134
	v_mul_f32_e32 v140, 0xbfb8aa3b, v130
	v_add_f32_e32 v142, 1.0, v142
	v_exp_f32_e32 v146, v146
	v_add_f32_e32 v134, 1.0, v134
	v_max_f32_e32 v138, 0x29e12e13, v138
	v_exp_f32_e32 v140, v140
	v_rcp_f32_e32 v142, v142
	v_rcp_f32_e32 v134, v134
	v_mul_f32_e32 v132, v148, v132
	v_rcp_f32_e32 v148, v138
	v_mul_f32_e32 v144, 0xbfb8aa3b, v131
	v_add_f32_e32 v146, 1.0, v146
	v_add_f32_e32 v140, 1.0, v140
	v_max_f32_e32 v142, 0x29e12e13, v142
	v_exp_f32_e32 v144, v144
	v_rcp_f32_e32 v146, v146
	v_rcp_f32_e32 v140, v140
	v_mul_f32_e32 v134, v148, v134
	v_rcp_f32_e32 v148, v142
	v_mul_f32_e32 v139, 0xbfb8aa3b, v117
	v_mul_f32_e32 v133, 0xbfb8aa3b, v124
	v_exp_f32_e32 v139, v139
	v_exp_f32_e32 v133, v133
	v_add_f32_e32 v144, 1.0, v144
	v_max_f32_e32 v146, 0x29e12e13, v146
	v_rcp_f32_e32 v144, v144
	v_mul_f32_e32 v140, v148, v140
	v_rcp_f32_e32 v148, v146
	v_mul_f32_e32 v143, 0xbfb8aa3b, v118
	v_mul_f32_e32 v135, 0xbfb8aa3b, v125
	v_add_f32_e32 v139, 1.0, v139
	v_exp_f32_e32 v143, v143
	v_add_f32_e32 v133, 1.0, v133
	v_exp_f32_e32 v135, v135
	v_rcp_f32_e32 v139, v139
	v_rcp_f32_e32 v133, v133
	v_mul_f32_e32 v144, v148, v144
	v_rcp_f32_e32 v148, v137
	v_mul_f32_e32 v147, 0xbfb8aa3b, v119
	v_mul_f32_e32 v141, 0xbfb8aa3b, v126
	v_add_f32_e32 v143, 1.0, v143
	v_exp_f32_e32 v147, v147
	v_add_f32_e32 v135, 1.0, v135
	v_max_f32_e32 v139, 0x29e12e13, v139
	v_exp_f32_e32 v141, v141
	v_rcp_f32_e32 v143, v143
	v_rcp_f32_e32 v135, v135
	v_mul_f32_e32 v148, v148, v133
	v_rcp_f32_e32 v133, v139
	v_mul_f32_e32 v145, 0xbfb8aa3b, v127
	v_add_f32_e32 v147, 1.0, v147
	v_add_f32_e32 v141, 1.0, v141
	v_max_f32_e32 v143, 0x29e12e13, v143
	v_exp_f32_e32 v145, v145
	v_rcp_f32_e32 v147, v147
	v_rcp_f32_e32 v141, v141
	v_mul_f32_e32 v135, v133, v135
	v_rcp_f32_e32 v133, v143
	v_add_f32_e32 v145, 1.0, v145
	v_max_f32_e32 v147, 0x29e12e13, v147
	v_rcp_f32_e32 v145, v145
	v_mul_f32_e32 v141, v133, v141
	v_rcp_f32_e32 v133, v147
	v_lshlrev_b32_e32 v2, 12, v208
	s_lshl_b32 s6, s26, 8
	v_readlane_b32 s2, v250, 63
	v_add3_u32 v2, v199, s6, v2
	v_mul_f32_e32 v145, v133, v145
	v_cvt_pk_bf16_f32 v132, v132, v134
	v_cvt_pk_bf16_f32 v133, v140, v144
	v_cvt_pk_bf16_f32 v134, v148, v135
	v_readlane_b32 s3, v251, 0
	v_readlane_b32 s6, v251, 1
	v_cvt_pk_bf16_f32 v135, v141, v145
	v_readlane_b32 s7, v251, 2
	v_mul_f32_e32 v140, 0xbfb8aa3b, v114
	v_exp_f32_e32 v140, v140
	s_nop 0
	global_store_dwordx4 v2, v[132:135], s[2:3]
	v_mul_f32_e32 v144, 0xbfb8aa3b, v115
	v_exp_f32_e32 v144, v144
	v_cvt_pk_bf16_f32 v132, v136, v138
	v_cvt_pk_bf16_f32 v133, v142, v146
	v_cvt_pk_bf16_f32 v134, v137, v139
	v_cvt_pk_bf16_f32 v135, v143, v147
	global_store_dwordx4 v2, v[132:135], s[6:7]
	v_mul_f32_e32 v138, 0xbfb8aa3b, v105
	v_exp_f32_e32 v138, v138
	v_mul_f32_e32 v134, 0xbfb8aa3b, v104
	v_exp_f32_e32 v134, v134
	v_mul_f32_e32 v132, 0xbfb8aa3b, v112
	v_exp_f32_e32 v132, v132
	v_mul_f32_e32 v142, 0xbfb8aa3b, v106
	v_add_f32_e32 v134, 1.0, v134
	v_rcp_f32_e32 v134, v134
	v_add_f32_e32 v138, 1.0, v138
	v_exp_f32_e32 v142, v142
	v_add_f32_e32 v132, 1.0, v132
	v_max_f32_e32 v136, 0x29e12e13, v134
	v_mul_f32_e32 v134, 0xbfb8aa3b, v100
	v_exp_f32_e32 v134, v134
	v_rcp_f32_e32 v138, v138
	v_rcp_f32_e32 v132, v132
	v_rcp_f32_e32 v148, v136
	v_add_f32_e32 v134, 1.0, v134
	v_rcp_f32_e32 v134, v134
	v_mul_f32_e32 v146, 0xbfb8aa3b, v107
	v_add_f32_e32 v142, 1.0, v142
	v_exp_f32_e32 v146, v146
	v_max_f32_e32 v137, 0x29e12e13, v134
	v_mul_f32_e32 v134, 0xbfb8aa3b, v113
	v_exp_f32_e32 v134, v134
	v_max_f32_e32 v138, 0x29e12e13, v138
	v_rcp_f32_e32 v142, v142
	v_mul_f32_e32 v132, v148, v132
	v_add_f32_e32 v134, 1.0, v134
	v_rcp_f32_e32 v134, v134
	v_rcp_f32_e32 v148, v138
	v_add_f32_e32 v146, 1.0, v146
	v_add_f32_e32 v140, 1.0, v140
	v_max_f32_e32 v142, 0x29e12e13, v142
	v_rcp_f32_e32 v146, v146
	v_rcp_f32_e32 v140, v140
	v_mul_f32_e32 v134, v148, v134
	v_rcp_f32_e32 v148, v142
	v_mul_f32_e32 v139, 0xbfb8aa3b, v101
	v_mul_f32_e32 v133, 0xbfb8aa3b, v108
	v_exp_f32_e32 v139, v139
	v_exp_f32_e32 v133, v133
	v_add_f32_e32 v144, 1.0, v144
	v_max_f32_e32 v146, 0x29e12e13, v146
	v_rcp_f32_e32 v144, v144
	v_mul_f32_e32 v140, v148, v140
	v_rcp_f32_e32 v148, v146
	v_mul_f32_e32 v143, 0xbfb8aa3b, v102
	v_mul_f32_e32 v135, 0xbfb8aa3b, v109
	v_add_f32_e32 v139, 1.0, v139
	v_exp_f32_e32 v143, v143
	v_add_f32_e32 v133, 1.0, v133
	v_exp_f32_e32 v135, v135
	v_rcp_f32_e32 v139, v139
	v_rcp_f32_e32 v133, v133
	v_mul_f32_e32 v144, v148, v144
	v_rcp_f32_e32 v148, v137
	v_mul_f32_e32 v147, 0xbfb8aa3b, v103
	v_mul_f32_e32 v141, 0xbfb8aa3b, v110
	v_add_f32_e32 v143, 1.0, v143
	v_exp_f32_e32 v147, v147
	v_add_f32_e32 v135, 1.0, v135
	v_max_f32_e32 v139, 0x29e12e13, v139
	v_exp_f32_e32 v141, v141
	v_rcp_f32_e32 v143, v143
	v_rcp_f32_e32 v135, v135
	v_mul_f32_e32 v148, v148, v133
	v_rcp_f32_e32 v133, v139
	v_mul_f32_e32 v145, 0xbfb8aa3b, v111
	v_add_f32_e32 v147, 1.0, v147
	v_add_f32_e32 v141, 1.0, v141
	v_max_f32_e32 v143, 0x29e12e13, v143
	v_exp_f32_e32 v145, v145
	v_rcp_f32_e32 v147, v147
	v_rcp_f32_e32 v141, v141
	v_mul_f32_e32 v135, v133, v135
	v_rcp_f32_e32 v133, v143
	v_add_f32_e32 v145, 1.0, v145
	v_max_f32_e32 v147, 0x29e12e13, v147
	v_rcp_f32_e32 v145, v145
	v_mul_f32_e32 v141, v133, v141
	v_rcp_f32_e32 v133, v147
	v_cvt_pk_bf16_f32 v132, v132, v134
	s_nop 0
	v_mul_f32_e32 v145, v133, v145
	v_cvt_pk_bf16_f32 v133, v140, v144
	v_cvt_pk_bf16_f32 v134, v148, v135
	v_add_u32_e32 v140, 0x10000, v2
	v_cvt_pk_bf16_f32 v135, v141, v145
	global_store_dwordx4 v140, v[132:135], s[2:3]
	v_mul_f32_e32 v144, 0xbfb8aa3b, v99
	v_exp_f32_e32 v144, v144
	v_cvt_pk_bf16_f32 v132, v136, v138
	v_cvt_pk_bf16_f32 v133, v142, v146
	v_cvt_pk_bf16_f32 v134, v137, v139
	v_cvt_pk_bf16_f32 v135, v143, v147
	global_store_dwordx4 v140, v[132:135], s[6:7]
	v_mul_f32_e32 v138, 0xbfb8aa3b, v89
	v_exp_f32_e32 v138, v138
	v_mul_f32_e32 v134, 0xbfb8aa3b, v88
	v_exp_f32_e32 v134, v134
	v_mul_f32_e32 v132, 0xbfb8aa3b, v96
	v_exp_f32_e32 v132, v132
	v_mul_f32_e32 v142, 0xbfb8aa3b, v90
	v_add_f32_e32 v134, 1.0, v134
	v_rcp_f32_e32 v134, v134
	v_add_f32_e32 v138, 1.0, v138
	v_exp_f32_e32 v142, v142
	v_add_f32_e32 v132, 1.0, v132
	v_max_f32_e32 v136, 0x29e12e13, v134
	v_mul_f32_e32 v134, 0xbfb8aa3b, v84
	v_exp_f32_e32 v134, v134
	v_rcp_f32_e32 v138, v138
	v_rcp_f32_e32 v132, v132
	v_rcp_f32_e32 v148, v136
	v_add_f32_e32 v134, 1.0, v134
	v_rcp_f32_e32 v134, v134
	v_mul_f32_e32 v146, 0xbfb8aa3b, v91
	v_mul_f32_e32 v140, 0xbfb8aa3b, v98
	v_add_f32_e32 v142, 1.0, v142
	v_max_f32_e32 v137, 0x29e12e13, v134
	v_mul_f32_e32 v134, 0xbfb8aa3b, v97
	v_exp_f32_e32 v134, v134
	v_exp_f32_e32 v146, v146
	v_max_f32_e32 v138, 0x29e12e13, v138
	v_exp_f32_e32 v140, v140
	v_add_f32_e32 v134, 1.0, v134
	v_rcp_f32_e32 v142, v142
	v_rcp_f32_e32 v134, v134
	v_mul_f32_e32 v132, v148, v132
	v_rcp_f32_e32 v148, v138
	v_add_f32_e32 v146, 1.0, v146
	v_add_f32_e32 v140, 1.0, v140
	v_max_f32_e32 v142, 0x29e12e13, v142
	v_rcp_f32_e32 v146, v146
	v_rcp_f32_e32 v140, v140
	v_mul_f32_e32 v134, v148, v134
	v_rcp_f32_e32 v148, v142
	v_mul_f32_e32 v139, 0xbfb8aa3b, v85
	v_mul_f32_e32 v133, 0xbfb8aa3b, v92
	v_exp_f32_e32 v139, v139
	v_exp_f32_e32 v133, v133
	v_add_f32_e32 v144, 1.0, v144
	v_max_f32_e32 v146, 0x29e12e13, v146
	v_rcp_f32_e32 v144, v144
	v_mul_f32_e32 v140, v148, v140
	v_rcp_f32_e32 v148, v146
	v_mul_f32_e32 v143, 0xbfb8aa3b, v86
	v_mul_f32_e32 v135, 0xbfb8aa3b, v93
	v_add_f32_e32 v139, 1.0, v139
	v_exp_f32_e32 v143, v143
	v_add_f32_e32 v133, 1.0, v133
	v_exp_f32_e32 v135, v135
	v_rcp_f32_e32 v139, v139
	v_rcp_f32_e32 v133, v133
	v_mul_f32_e32 v144, v148, v144
	v_rcp_f32_e32 v148, v137
	v_mul_f32_e32 v147, 0xbfb8aa3b, v87
	v_mul_f32_e32 v141, 0xbfb8aa3b, v94
	v_add_f32_e32 v143, 1.0, v143
	v_exp_f32_e32 v147, v147
	v_add_f32_e32 v135, 1.0, v135
	v_max_f32_e32 v139, 0x29e12e13, v139
	v_exp_f32_e32 v141, v141
	v_rcp_f32_e32 v143, v143
	v_rcp_f32_e32 v135, v135
	v_mul_f32_e32 v148, v148, v133
	v_rcp_f32_e32 v133, v139
	v_mul_f32_e32 v145, 0xbfb8aa3b, v95
	v_add_f32_e32 v147, 1.0, v147
	v_add_f32_e32 v141, 1.0, v141
	v_max_f32_e32 v143, 0x29e12e13, v143
	v_exp_f32_e32 v145, v145
	v_rcp_f32_e32 v147, v147
	v_rcp_f32_e32 v141, v141
	v_mul_f32_e32 v135, v133, v135
	v_rcp_f32_e32 v133, v143
	v_add_f32_e32 v145, 1.0, v145
	v_max_f32_e32 v147, 0x29e12e13, v147
	v_rcp_f32_e32 v145, v145
	v_mul_f32_e32 v141, v133, v141
	v_rcp_f32_e32 v133, v147
	v_cvt_pk_bf16_f32 v132, v132, v134
	s_nop 0
	v_mul_f32_e32 v145, v133, v145
	v_cvt_pk_bf16_f32 v133, v140, v144
	v_cvt_pk_bf16_f32 v134, v148, v135
	v_add_u32_e32 v140, 0x20000, v2
	v_cvt_pk_bf16_f32 v135, v141, v145
	global_store_dwordx4 v140, v[132:135], s[2:3]
	v_mul_f32_e32 v144, 0xbfb8aa3b, v83
	v_exp_f32_e32 v144, v144
	v_cvt_pk_bf16_f32 v132, v136, v138
	v_cvt_pk_bf16_f32 v133, v142, v146
	v_cvt_pk_bf16_f32 v134, v137, v139
	v_cvt_pk_bf16_f32 v135, v143, v147
	global_store_dwordx4 v140, v[132:135], s[6:7]
	v_mul_f32_e32 v138, 0xbfb8aa3b, v73
	v_exp_f32_e32 v138, v138
	v_mul_f32_e32 v134, 0xbfb8aa3b, v72
	v_exp_f32_e32 v134, v134
	v_mul_f32_e32 v132, 0xbfb8aa3b, v80
	v_exp_f32_e32 v132, v132
	v_mul_f32_e32 v142, 0xbfb8aa3b, v74
	v_add_f32_e32 v134, 1.0, v134
	v_rcp_f32_e32 v134, v134
	v_add_f32_e32 v138, 1.0, v138
	v_exp_f32_e32 v142, v142
	v_add_f32_e32 v132, 1.0, v132
	v_max_f32_e32 v136, 0x29e12e13, v134
	v_mul_f32_e32 v134, 0xbfb8aa3b, v68
	v_exp_f32_e32 v134, v134
	v_rcp_f32_e32 v138, v138
	v_rcp_f32_e32 v132, v132
	v_rcp_f32_e32 v148, v136
	v_add_f32_e32 v134, 1.0, v134
	v_rcp_f32_e32 v134, v134
	v_mul_f32_e32 v146, 0xbfb8aa3b, v75
	v_mul_f32_e32 v140, 0xbfb8aa3b, v82
	v_add_f32_e32 v142, 1.0, v142
	v_max_f32_e32 v137, 0x29e12e13, v134
	v_mul_f32_e32 v134, 0xbfb8aa3b, v81
	v_exp_f32_e32 v134, v134
	v_exp_f32_e32 v146, v146
	v_max_f32_e32 v138, 0x29e12e13, v138
	v_exp_f32_e32 v140, v140
	v_add_f32_e32 v134, 1.0, v134
	v_rcp_f32_e32 v142, v142
	v_rcp_f32_e32 v134, v134
	v_mul_f32_e32 v132, v148, v132
	v_rcp_f32_e32 v148, v138
	v_add_f32_e32 v146, 1.0, v146
	v_add_f32_e32 v140, 1.0, v140
	v_max_f32_e32 v142, 0x29e12e13, v142
	v_rcp_f32_e32 v146, v146
	v_rcp_f32_e32 v140, v140
	v_mul_f32_e32 v134, v148, v134
	v_rcp_f32_e32 v148, v142
	v_mul_f32_e32 v139, 0xbfb8aa3b, v69
	v_mul_f32_e32 v133, 0xbfb8aa3b, v76
	v_exp_f32_e32 v139, v139
	v_exp_f32_e32 v133, v133
	v_add_f32_e32 v144, 1.0, v144
	v_max_f32_e32 v146, 0x29e12e13, v146
	v_rcp_f32_e32 v144, v144
	v_mul_f32_e32 v140, v148, v140
	v_rcp_f32_e32 v148, v146
	v_mul_f32_e32 v143, 0xbfb8aa3b, v70
	v_mul_f32_e32 v135, 0xbfb8aa3b, v77
	v_add_f32_e32 v139, 1.0, v139
	v_exp_f32_e32 v143, v143
	v_add_f32_e32 v133, 1.0, v133
	v_exp_f32_e32 v135, v135
	v_rcp_f32_e32 v139, v139
	v_rcp_f32_e32 v133, v133
	v_mul_f32_e32 v144, v148, v144
	v_rcp_f32_e32 v148, v137
	v_mul_f32_e32 v147, 0xbfb8aa3b, v71
	v_mul_f32_e32 v141, 0xbfb8aa3b, v78
	v_add_f32_e32 v143, 1.0, v143
	v_exp_f32_e32 v147, v147
	v_add_f32_e32 v135, 1.0, v135
	v_max_f32_e32 v139, 0x29e12e13, v139
	v_exp_f32_e32 v141, v141
	v_rcp_f32_e32 v143, v143
	v_rcp_f32_e32 v135, v135
	v_mul_f32_e32 v148, v148, v133
	v_rcp_f32_e32 v133, v139
	v_mul_f32_e32 v145, 0xbfb8aa3b, v79
	v_add_f32_e32 v147, 1.0, v147
	v_add_f32_e32 v141, 1.0, v141
	v_max_f32_e32 v143, 0x29e12e13, v143
	v_exp_f32_e32 v145, v145
	v_rcp_f32_e32 v147, v147
	v_rcp_f32_e32 v141, v141
	v_mul_f32_e32 v135, v133, v135
	v_rcp_f32_e32 v133, v143
	v_add_f32_e32 v145, 1.0, v145
	v_max_f32_e32 v147, 0x29e12e13, v147
	v_rcp_f32_e32 v145, v145
	v_mul_f32_e32 v141, v133, v141
	v_rcp_f32_e32 v133, v147
	v_cvt_pk_bf16_f32 v132, v132, v134
	s_nop 0
	v_mul_f32_e32 v145, v133, v145
	v_cvt_pk_bf16_f32 v133, v140, v144
	v_cvt_pk_bf16_f32 v134, v148, v135
	v_add_u32_e32 v140, 0x30000, v2
	v_cvt_pk_bf16_f32 v135, v141, v145
	global_store_dwordx4 v140, v[132:135], s[2:3]
	v_mul_f32_e32 v141, 0xbfb8aa3b, v66
	v_exp_f32_e32 v141, v141
	v_cvt_pk_bf16_f32 v132, v136, v138
	v_cvt_pk_bf16_f32 v133, v142, v146
	v_cvt_pk_bf16_f32 v134, v137, v139
	v_cvt_pk_bf16_f32 v135, v143, v147
	global_store_dwordx4 v140, v[132:135], s[6:7]
	v_mul_f32_e32 v139, 0xbfb8aa3b, v57
	v_exp_f32_e32 v139, v139
	v_mul_f32_e32 v134, 0xbfb8aa3b, v56
	v_exp_f32_e32 v134, v134
	v_mul_f32_e32 v132, 0xbfb8aa3b, v64
	v_exp_f32_e32 v132, v132
	v_mul_f32_e32 v143, 0xbfb8aa3b, v58
	v_add_f32_e32 v134, 1.0, v134
	v_rcp_f32_e32 v134, v134
	v_add_f32_e32 v139, 1.0, v139
	v_exp_f32_e32 v143, v143
	v_add_f32_e32 v132, 1.0, v132
	v_max_f32_e32 v137, 0x29e12e13, v134
	v_mul_f32_e32 v134, 0xbfb8aa3b, v52
	v_exp_f32_e32 v134, v134
	v_rcp_f32_e32 v139, v139
	v_rcp_f32_e32 v132, v132
	v_rcp_f32_e32 v149, v137
	v_add_f32_e32 v134, 1.0, v134
	v_rcp_f32_e32 v134, v134
	v_mul_f32_e32 v147, 0xbfb8aa3b, v59
	v_add_f32_e32 v143, 1.0, v143
	v_exp_f32_e32 v147, v147
	v_max_f32_e32 v138, 0x29e12e13, v134
	v_mul_f32_e32 v134, 0xbfb8aa3b, v65
	v_exp_f32_e32 v134, v134
	v_max_f32_e32 v139, 0x29e12e13, v139
	v_rcp_f32_e32 v143, v143
	v_mul_f32_e32 v132, v149, v132
	v_add_f32_e32 v134, 1.0, v134
	v_rcp_f32_e32 v134, v134
	v_rcp_f32_e32 v149, v139
	v_mul_f32_e32 v145, 0xbfb8aa3b, v67
	v_add_f32_e32 v147, 1.0, v147
	v_add_f32_e32 v141, 1.0, v141
	v_max_f32_e32 v143, 0x29e12e13, v143
	v_exp_f32_e32 v145, v145
	v_rcp_f32_e32 v147, v147
	v_rcp_f32_e32 v141, v141
	v_mul_f32_e32 v134, v149, v134
	v_rcp_f32_e32 v149, v143
	v_mul_f32_e32 v140, 0xbfb8aa3b, v53
	v_mul_f32_e32 v133, 0xbfb8aa3b, v60
	v_exp_f32_e32 v140, v140
	v_exp_f32_e32 v133, v133
	v_add_f32_e32 v145, 1.0, v145
	v_max_f32_e32 v147, 0x29e12e13, v147
	v_rcp_f32_e32 v145, v145
	v_mul_f32_e32 v141, v149, v141
	v_rcp_f32_e32 v149, v147
	v_mul_f32_e32 v144, 0xbfb8aa3b, v54
	v_mul_f32_e32 v135, 0xbfb8aa3b, v61
	v_add_f32_e32 v140, 1.0, v140
	v_exp_f32_e32 v144, v144
	v_add_f32_e32 v133, 1.0, v133
	v_exp_f32_e32 v135, v135
	v_rcp_f32_e32 v140, v140
	v_rcp_f32_e32 v133, v133
	v_mul_f32_e32 v145, v149, v145
	v_rcp_f32_e32 v149, v138
	v_mul_f32_e32 v148, 0xbfb8aa3b, v55
	v_mul_f32_e32 v142, 0xbfb8aa3b, v62
	v_add_f32_e32 v144, 1.0, v144
	v_exp_f32_e32 v148, v148
	v_add_f32_e32 v135, 1.0, v135
	v_max_f32_e32 v140, 0x29e12e13, v140
	v_exp_f32_e32 v142, v142
	v_rcp_f32_e32 v144, v144
	v_rcp_f32_e32 v135, v135
	v_mul_f32_e32 v149, v149, v133
	v_rcp_f32_e32 v133, v140
	v_mul_f32_e32 v146, 0xbfb8aa3b, v63
	v_add_f32_e32 v148, 1.0, v148
	v_add_f32_e32 v142, 1.0, v142
	v_max_f32_e32 v144, 0x29e12e13, v144
	v_exp_f32_e32 v146, v146
	v_rcp_f32_e32 v148, v148
	v_rcp_f32_e32 v142, v142
	v_mul_f32_e32 v135, v133, v135
	v_rcp_f32_e32 v133, v144
	v_add_f32_e32 v146, 1.0, v146
	v_max_f32_e32 v148, 0x29e12e13, v148
	v_rcp_f32_e32 v146, v146
	v_mul_f32_e32 v142, v133, v142
	v_rcp_f32_e32 v133, v148
	v_add_u32_e32 v136, 0x80000, v2
	v_cvt_pk_bf16_f32 v132, v132, v134
	v_mul_f32_e32 v146, v133, v146
	v_cvt_pk_bf16_f32 v133, v141, v145
	v_cvt_pk_bf16_f32 v134, v149, v135
	v_cvt_pk_bf16_f32 v135, v142, v146
	global_store_dwordx4 v136, v[132:135], s[2:3]
	v_mul_f32_e32 v142, 0xbfb8aa3b, v42
	v_exp_f32_e32 v142, v142
	v_cvt_pk_bf16_f32 v132, v137, v139
	v_cvt_pk_bf16_f32 v133, v143, v147
	v_cvt_pk_bf16_f32 v134, v138, v140
	v_cvt_pk_bf16_f32 v135, v144, v148
	global_store_dwordx4 v136, v[132:135], s[6:7]
	v_mul_f32_e32 v138, 0xbfb8aa3b, v41
	v_exp_f32_e32 v138, v138
	v_mul_f32_e32 v134, 0xbfb8aa3b, v40
	v_exp_f32_e32 v134, v134
	v_mul_f32_e32 v132, 0xbfb8aa3b, v48
	v_exp_f32_e32 v132, v132
	v_add_f32_e32 v138, 1.0, v138
	v_add_f32_e32 v134, 1.0, v134
	v_rcp_f32_e32 v134, v134
	v_add_f32_e32 v132, 1.0, v132
	v_rcp_f32_e32 v138, v138
	v_rcp_f32_e32 v132, v132
	v_max_f32_e32 v136, 0x29e12e13, v134
	v_mul_f32_e32 v134, 0xbfb8aa3b, v36
	v_exp_f32_e32 v134, v134
	v_rcp_f32_e32 v148, v136
	v_mul_f32_e32 v146, 0xbfb8aa3b, v43
	v_mul_f32_e32 v140, 0xbfb8aa3b, v50
	v_add_f32_e32 v134, 1.0, v134
	v_rcp_f32_e32 v134, v134
	v_add_f32_e32 v142, 1.0, v142
	v_exp_f32_e32 v146, v146
	v_max_f32_e32 v138, 0x29e12e13, v138
	v_max_f32_e32 v137, 0x29e12e13, v134
	v_mul_f32_e32 v134, 0xbfb8aa3b, v49
	v_exp_f32_e32 v134, v134
	v_exp_f32_e32 v140, v140
	v_rcp_f32_e32 v142, v142
	v_mul_f32_e32 v132, v148, v132
	v_add_f32_e32 v134, 1.0, v134
	v_rcp_f32_e32 v134, v134
	v_rcp_f32_e32 v148, v138
	v_mul_f32_e32 v144, 0xbfb8aa3b, v51
	v_add_f32_e32 v146, 1.0, v146
	v_add_f32_e32 v140, 1.0, v140
	v_max_f32_e32 v142, 0x29e12e13, v142
	v_exp_f32_e32 v144, v144
	v_rcp_f32_e32 v146, v146
	v_rcp_f32_e32 v140, v140
	v_mul_f32_e32 v134, v148, v134
	v_rcp_f32_e32 v148, v142
	v_mul_f32_e32 v139, 0xbfb8aa3b, v37
	v_mul_f32_e32 v133, 0xbfb8aa3b, v44
	v_exp_f32_e32 v139, v139
	v_exp_f32_e32 v133, v133
	v_add_f32_e32 v144, 1.0, v144
	v_max_f32_e32 v146, 0x29e12e13, v146
	v_rcp_f32_e32 v144, v144
	v_mul_f32_e32 v140, v148, v140
	v_rcp_f32_e32 v148, v146
	v_mul_f32_e32 v143, 0xbfb8aa3b, v38
	v_mul_f32_e32 v135, 0xbfb8aa3b, v45
	v_add_f32_e32 v139, 1.0, v139
	v_exp_f32_e32 v143, v143
	v_add_f32_e32 v133, 1.0, v133
	v_exp_f32_e32 v135, v135
	v_rcp_f32_e32 v139, v139
	v_rcp_f32_e32 v133, v133
	v_mul_f32_e32 v144, v148, v144
	v_rcp_f32_e32 v148, v137
	v_mul_f32_e32 v147, 0xbfb8aa3b, v39
	v_mul_f32_e32 v141, 0xbfb8aa3b, v46
	v_add_f32_e32 v143, 1.0, v143
	v_exp_f32_e32 v147, v147
	v_add_f32_e32 v135, 1.0, v135
	v_max_f32_e32 v139, 0x29e12e13, v139
	v_exp_f32_e32 v141, v141
	v_rcp_f32_e32 v143, v143
	v_rcp_f32_e32 v135, v135
	v_mul_f32_e32 v148, v148, v133
	v_rcp_f32_e32 v133, v139
	v_mul_f32_e32 v145, 0xbfb8aa3b, v47
	v_add_f32_e32 v147, 1.0, v147
	v_add_f32_e32 v141, 1.0, v141
	v_max_f32_e32 v143, 0x29e12e13, v143
	v_exp_f32_e32 v145, v145
	v_rcp_f32_e32 v147, v147
	v_rcp_f32_e32 v141, v141
	v_mul_f32_e32 v135, v133, v135
	v_rcp_f32_e32 v133, v143
	v_add_f32_e32 v145, 1.0, v145
	v_max_f32_e32 v147, 0x29e12e13, v147
	v_rcp_f32_e32 v145, v145
	v_mul_f32_e32 v141, v133, v141
	v_rcp_f32_e32 v133, v147
	v_cvt_pk_bf16_f32 v132, v132, v134
	s_nop 0
	v_mul_f32_e32 v145, v133, v145
	v_cvt_pk_bf16_f32 v133, v140, v144
	v_cvt_pk_bf16_f32 v134, v148, v135
	v_add_u32_e32 v140, 0x90000, v2
	v_cvt_pk_bf16_f32 v135, v141, v145
	global_store_dwordx4 v140, v[132:135], s[2:3]
	v_mul_f32_e32 v144, 0xbfb8aa3b, v35
	v_exp_f32_e32 v144, v144
	v_cvt_pk_bf16_f32 v132, v136, v138
	v_cvt_pk_bf16_f32 v133, v142, v146
	v_cvt_pk_bf16_f32 v134, v137, v139
	v_cvt_pk_bf16_f32 v135, v143, v147
	global_store_dwordx4 v140, v[132:135], s[6:7]
	v_mul_f32_e32 v138, 0xbfb8aa3b, v25
	v_exp_f32_e32 v138, v138
	v_mul_f32_e32 v134, 0xbfb8aa3b, v24
	v_exp_f32_e32 v134, v134
	v_mul_f32_e32 v132, 0xbfb8aa3b, v32
	v_exp_f32_e32 v132, v132
	v_mul_f32_e32 v142, 0xbfb8aa3b, v26
	v_add_f32_e32 v134, 1.0, v134
	v_rcp_f32_e32 v134, v134
	v_add_f32_e32 v138, 1.0, v138
	v_exp_f32_e32 v142, v142
	v_add_f32_e32 v132, 1.0, v132
	v_max_f32_e32 v136, 0x29e12e13, v134
	v_mul_f32_e32 v134, 0xbfb8aa3b, v20
	v_exp_f32_e32 v134, v134
	v_rcp_f32_e32 v138, v138
	v_rcp_f32_e32 v132, v132
	v_rcp_f32_e32 v148, v136
	v_add_f32_e32 v134, 1.0, v134
	v_rcp_f32_e32 v134, v134
	v_mul_f32_e32 v146, 0xbfb8aa3b, v27
	v_mul_f32_e32 v140, 0xbfb8aa3b, v34
	v_add_f32_e32 v142, 1.0, v142
	v_max_f32_e32 v137, 0x29e12e13, v134
	v_mul_f32_e32 v134, 0xbfb8aa3b, v33
	v_exp_f32_e32 v134, v134
	v_exp_f32_e32 v146, v146
	v_max_f32_e32 v138, 0x29e12e13, v138
	v_exp_f32_e32 v140, v140
	v_add_f32_e32 v134, 1.0, v134
	v_rcp_f32_e32 v142, v142
	v_rcp_f32_e32 v134, v134
	v_mul_f32_e32 v132, v148, v132
	v_rcp_f32_e32 v148, v138
	v_add_f32_e32 v146, 1.0, v146
	v_add_f32_e32 v140, 1.0, v140
	v_max_f32_e32 v142, 0x29e12e13, v142
	v_rcp_f32_e32 v146, v146
	v_rcp_f32_e32 v140, v140
	v_mul_f32_e32 v134, v148, v134
	v_rcp_f32_e32 v148, v142
	v_mul_f32_e32 v139, 0xbfb8aa3b, v21
	v_mul_f32_e32 v133, 0xbfb8aa3b, v28
	v_exp_f32_e32 v139, v139
	v_exp_f32_e32 v133, v133
	v_add_f32_e32 v144, 1.0, v144
	v_max_f32_e32 v146, 0x29e12e13, v146
	v_rcp_f32_e32 v144, v144
	v_mul_f32_e32 v140, v148, v140
	v_rcp_f32_e32 v148, v146
	v_mul_f32_e32 v143, 0xbfb8aa3b, v22
	v_mul_f32_e32 v135, 0xbfb8aa3b, v29
	v_add_f32_e32 v139, 1.0, v139
	v_exp_f32_e32 v143, v143
	v_add_f32_e32 v133, 1.0, v133
	v_exp_f32_e32 v135, v135
	v_rcp_f32_e32 v139, v139
	v_rcp_f32_e32 v133, v133
	v_mul_f32_e32 v144, v148, v144
	v_rcp_f32_e32 v148, v137
	v_mul_f32_e32 v147, 0xbfb8aa3b, v23
	v_mul_f32_e32 v141, 0xbfb8aa3b, v30
	v_add_f32_e32 v143, 1.0, v143
	v_exp_f32_e32 v147, v147
	v_add_f32_e32 v135, 1.0, v135
	v_max_f32_e32 v139, 0x29e12e13, v139
	v_exp_f32_e32 v141, v141
	v_rcp_f32_e32 v143, v143
	v_rcp_f32_e32 v135, v135
	v_mul_f32_e32 v148, v148, v133
	v_rcp_f32_e32 v133, v139
	v_mul_f32_e32 v145, 0xbfb8aa3b, v31
	v_add_f32_e32 v147, 1.0, v147
	v_add_f32_e32 v141, 1.0, v141
	v_max_f32_e32 v143, 0x29e12e13, v143
	v_exp_f32_e32 v145, v145
	v_rcp_f32_e32 v147, v147
	v_rcp_f32_e32 v141, v141
	v_mul_f32_e32 v135, v133, v135
	v_rcp_f32_e32 v133, v143
	v_add_f32_e32 v145, 1.0, v145
	v_max_f32_e32 v147, 0x29e12e13, v147
	v_rcp_f32_e32 v145, v145
	v_mul_f32_e32 v141, v133, v141
	v_rcp_f32_e32 v133, v147
	v_cvt_pk_bf16_f32 v132, v132, v134
	s_nop 0
	v_mul_f32_e32 v145, v133, v145
	v_cvt_pk_bf16_f32 v133, v140, v144
	v_cvt_pk_bf16_f32 v134, v148, v135
	v_add_u32_e32 v140, 0xa0000, v2
	v_cvt_pk_bf16_f32 v135, v141, v145
	global_store_dwordx4 v140, v[132:135], s[2:3]
	v_mul_f32_e32 v144, 0xbfb8aa3b, v19
	v_exp_f32_e32 v144, v144
	v_cvt_pk_bf16_f32 v132, v136, v138
	v_cvt_pk_bf16_f32 v133, v142, v146
	v_cvt_pk_bf16_f32 v134, v137, v139
	v_cvt_pk_bf16_f32 v135, v143, v147
	global_store_dwordx4 v140, v[132:135], s[6:7]
	v_mul_f32_e32 v138, 0xbfb8aa3b, v9
	v_exp_f32_e32 v138, v138
	v_mul_f32_e32 v134, 0xbfb8aa3b, v8
	v_exp_f32_e32 v134, v134
	v_mul_f32_e32 v132, 0xbfb8aa3b, v16
	v_exp_f32_e32 v132, v132
	v_mul_f32_e32 v142, 0xbfb8aa3b, v10
	v_add_f32_e32 v134, 1.0, v134
	v_rcp_f32_e32 v134, v134
	v_add_f32_e32 v138, 1.0, v138
	v_exp_f32_e32 v142, v142
	v_add_f32_e32 v132, 1.0, v132
	v_max_f32_e32 v136, 0x29e12e13, v134
	v_mul_f32_e32 v134, 0xbfb8aa3b, v4
	v_exp_f32_e32 v134, v134
	v_rcp_f32_e32 v138, v138
	v_rcp_f32_e32 v132, v132
	v_rcp_f32_e32 v148, v136
	v_add_f32_e32 v134, 1.0, v134
	v_rcp_f32_e32 v134, v134
	v_mul_f32_e32 v146, 0xbfb8aa3b, v11
	v_mul_f32_e32 v140, 0xbfb8aa3b, v18
	v_add_f32_e32 v142, 1.0, v142
	v_max_f32_e32 v137, 0x29e12e13, v134
	v_mul_f32_e32 v134, 0xbfb8aa3b, v17
	v_exp_f32_e32 v134, v134
	v_exp_f32_e32 v146, v146
	v_max_f32_e32 v138, 0x29e12e13, v138
	v_exp_f32_e32 v140, v140
	v_add_f32_e32 v134, 1.0, v134
	v_rcp_f32_e32 v142, v142
	v_rcp_f32_e32 v134, v134
	v_mul_f32_e32 v132, v148, v132
	v_rcp_f32_e32 v148, v138
	v_add_f32_e32 v146, 1.0, v146
	v_add_f32_e32 v140, 1.0, v140
	v_max_f32_e32 v142, 0x29e12e13, v142
	v_rcp_f32_e32 v146, v146
	v_rcp_f32_e32 v140, v140
	v_mul_f32_e32 v134, v148, v134
	v_rcp_f32_e32 v148, v142
	v_mul_f32_e32 v139, 0xbfb8aa3b, v5
	v_mul_f32_e32 v133, 0xbfb8aa3b, v12
	v_exp_f32_e32 v139, v139
	v_exp_f32_e32 v133, v133
	v_add_f32_e32 v144, 1.0, v144
	v_max_f32_e32 v146, 0x29e12e13, v146
	v_rcp_f32_e32 v144, v144
	v_mul_f32_e32 v140, v148, v140
	v_rcp_f32_e32 v148, v146
	v_mul_f32_e32 v143, 0xbfb8aa3b, v6
	v_mul_f32_e32 v135, 0xbfb8aa3b, v13
	v_add_f32_e32 v139, 1.0, v139
	v_exp_f32_e32 v143, v143
	v_add_f32_e32 v133, 1.0, v133
	v_exp_f32_e32 v135, v135
	v_rcp_f32_e32 v139, v139
	v_rcp_f32_e32 v133, v133
	v_mul_f32_e32 v144, v148, v144
	v_rcp_f32_e32 v148, v137
	v_mul_f32_e32 v147, 0xbfb8aa3b, v7
	v_mul_f32_e32 v141, 0xbfb8aa3b, v14
	v_add_f32_e32 v143, 1.0, v143
	v_exp_f32_e32 v147, v147
	v_add_f32_e32 v135, 1.0, v135
	v_max_f32_e32 v139, 0x29e12e13, v139
	v_exp_f32_e32 v141, v141
	v_rcp_f32_e32 v143, v143
	v_rcp_f32_e32 v135, v135
	v_mul_f32_e32 v148, v148, v133
	v_rcp_f32_e32 v133, v139
	v_mul_f32_e32 v145, 0xbfb8aa3b, v15
	v_add_f32_e32 v147, 1.0, v147
	v_add_f32_e32 v141, 1.0, v141
	v_max_f32_e32 v143, 0x29e12e13, v143
	v_exp_f32_e32 v145, v145
	v_rcp_f32_e32 v147, v147
	v_rcp_f32_e32 v141, v141
	v_mul_f32_e32 v135, v133, v135
	v_rcp_f32_e32 v133, v143
	v_add_f32_e32 v145, 1.0, v145
	v_max_f32_e32 v147, 0x29e12e13, v147
	v_rcp_f32_e32 v145, v145
	v_mul_f32_e32 v141, v133, v141
	v_rcp_f32_e32 v133, v147
	v_cvt_pk_bf16_f32 v132, v132, v134
	v_add_u32_e32 v2, 0xb0000, v2
	v_mul_f32_e32 v145, v133, v145
	v_cvt_pk_bf16_f32 v133, v140, v144
	v_cvt_pk_bf16_f32 v134, v148, v135
	v_cvt_pk_bf16_f32 v135, v141, v145
	global_store_dwordx4 v2, v[132:135], s[2:3]
	s_nop 1
	v_cvt_pk_bf16_f32 v132, v136, v138
	v_cvt_pk_bf16_f32 v133, v142, v146
	v_cvt_pk_bf16_f32 v134, v137, v139
	v_cvt_pk_bf16_f32 v135, v143, v147
	global_store_dwordx4 v2, v[132:135], s[6:7]
	s_mov_b64 s[6:7], 0

.Llast_inp:
	v_lshl_add_u32 v208, s27, 8, v192
	s_cmp_gt_i32 s26, 7
	s_mov_b64 s[6:7], -1
	s_mov_b64 s[56:57], 0x40000
	s_mov_b32 s58, 0x20000
	s_cbranch_scc0 .Lwt_BB0_578
	s_cmp_gt_u32 s26, 19
	s_cbranch_scc0 .Lwt_BB0_571
	v_mul_f32_e32 v134, 0xbfb8aa3b, v120
	v_exp_f32_e32 v134, v134
	v_mul_f32_e32 v138, 0xbfb8aa3b, v121
	v_mul_f32_e32 v132, 0xbfb8aa3b, v128
	v_exp_f32_e32 v138, v138
	v_add_f32_e32 v134, 1.0, v134
	v_rcp_f32_e32 v134, v134
	v_exp_f32_e32 v132, v132
	v_mul_f32_e32 v142, 0xbfb8aa3b, v122
	v_add_f32_e32 v138, 1.0, v138
	v_max_f32_e32 v136, 0x29e12e13, v134
	v_mul_f32_e32 v134, 0xbfb8aa3b, v116
	v_exp_f32_e32 v134, v134
	v_exp_f32_e32 v142, v142
	v_add_f32_e32 v132, 1.0, v132
	v_rcp_f32_e32 v138, v138
	v_add_f32_e32 v134, 1.0, v134
	v_rcp_f32_e32 v134, v134
	v_rcp_f32_e32 v132, v132
	v_rcp_f32_e32 v148, v136
	v_mul_f32_e32 v146, 0xbfb8aa3b, v123
	v_max_f32_e32 v137, 0x29e12e13, v134
	v_mul_f32_e32 v134, 0xbfb8aa3b, v129
	v_exp_f32_e32 v134, v134
	v_mul_f32_e32 v140, 0xbfb8aa3b, v130
	v_add_f32_e32 v142, 1.0, v142
	v_exp_f32_e32 v146, v146
	v_add_f32_e32 v134, 1.0, v134
	v_max_f32_e32 v138, 0x29e12e13, v138
	v_exp_f32_e32 v140, v140
	v_rcp_f32_e32 v142, v142
	v_rcp_f32_e32 v134, v134
	v_mul_f32_e32 v132, v148, v132
	v_rcp_f32_e32 v148, v138
	v_mul_f32_e32 v144, 0xbfb8aa3b, v131
	v_add_f32_e32 v146, 1.0, v146
	v_add_f32_e32 v140, 1.0, v140
	v_max_f32_e32 v142, 0x29e12e13, v142
	v_exp_f32_e32 v144, v144
	v_rcp_f32_e32 v146, v146
	v_rcp_f32_e32 v140, v140
	v_mul_f32_e32 v134, v148, v134
	v_rcp_f32_e32 v148, v142
	v_mul_f32_e32 v139, 0xbfb8aa3b, v117
	v_mul_f32_e32 v133, 0xbfb8aa3b, v124
	v_exp_f32_e32 v139, v139
	v_exp_f32_e32 v133, v133
	v_add_f32_e32 v144, 1.0, v144
	v_max_f32_e32 v146, 0x29e12e13, v146
	v_rcp_f32_e32 v144, v144
	v_mul_f32_e32 v140, v148, v140
	v_rcp_f32_e32 v148, v146
	v_mul_f32_e32 v143, 0xbfb8aa3b, v118
	v_mul_f32_e32 v135, 0xbfb8aa3b, v125
	v_add_f32_e32 v139, 1.0, v139
	v_exp_f32_e32 v143, v143
	v_add_f32_e32 v133, 1.0, v133
	v_exp_f32_e32 v135, v135
	v_rcp_f32_e32 v139, v139
	v_rcp_f32_e32 v133, v133
	v_mul_f32_e32 v144, v148, v144
	v_rcp_f32_e32 v148, v137
	v_mul_f32_e32 v147, 0xbfb8aa3b, v119
	v_mul_f32_e32 v141, 0xbfb8aa3b, v126
	v_add_f32_e32 v143, 1.0, v143
	v_exp_f32_e32 v147, v147
	v_add_f32_e32 v135, 1.0, v135
	v_max_f32_e32 v139, 0x29e12e13, v139
	v_exp_f32_e32 v141, v141
	v_rcp_f32_e32 v143, v143
	v_rcp_f32_e32 v135, v135
	v_mul_f32_e32 v148, v148, v133
	v_rcp_f32_e32 v133, v139
	v_mul_f32_e32 v145, 0xbfb8aa3b, v127
	v_add_f32_e32 v147, 1.0, v147
	v_add_f32_e32 v141, 1.0, v141
	v_max_f32_e32 v143, 0x29e12e13, v143
	v_exp_f32_e32 v145, v145
	v_rcp_f32_e32 v147, v147
	v_rcp_f32_e32 v141, v141
	v_mul_f32_e32 v135, v133, v135
	v_rcp_f32_e32 v133, v143
	v_add_f32_e32 v145, 1.0, v145
	v_max_f32_e32 v147, 0x29e12e13, v147
	v_rcp_f32_e32 v145, v145
	v_mul_f32_e32 v141, v133, v141
	v_rcp_f32_e32 v133, v147
	v_lshlrev_b32_e32 v2, 12, v208
	s_lshl_b32 s6, s26, 8
	v_readlane_b32 s2, v250, 63
	v_add3_u32 v2, v199, s6, v2
	v_mul_f32_e32 v145, v133, v145
	v_cvt_pk_bf16_f32 v132, v132, v134
	v_cvt_pk_bf16_f32 v133, v140, v144
	v_cvt_pk_bf16_f32 v134, v148, v135
	v_readlane_b32 s3, v251, 0
	v_readlane_b32 s6, v251, 1
	v_cvt_pk_bf16_f32 v135, v141, v145
	v_readlane_b32 s7, v251, 2
	v_mul_f32_e32 v140, 0xbfb8aa3b, v114
	v_exp_f32_e32 v140, v140
	s_nop 0
	global_store_dwordx4 v2, v[132:135], s[2:3] sc0 sc1
	v_mul_f32_e32 v144, 0xbfb8aa3b, v115
	v_exp_f32_e32 v144, v144
	v_cvt_pk_bf16_f32 v132, v136, v138
	v_cvt_pk_bf16_f32 v133, v142, v146
	v_cvt_pk_bf16_f32 v134, v137, v139
	v_cvt_pk_bf16_f32 v135, v143, v147
	global_store_dwordx4 v2, v[132:135], s[6:7] sc0 sc1
	v_mul_f32_e32 v138, 0xbfb8aa3b, v105
	v_exp_f32_e32 v138, v138
	v_mul_f32_e32 v134, 0xbfb8aa3b, v104
	v_exp_f32_e32 v134, v134
	v_mul_f32_e32 v132, 0xbfb8aa3b, v112
	v_exp_f32_e32 v132, v132
	v_mul_f32_e32 v142, 0xbfb8aa3b, v106
	v_add_f32_e32 v134, 1.0, v134
	v_rcp_f32_e32 v134, v134
	v_add_f32_e32 v138, 1.0, v138
	v_exp_f32_e32 v142, v142
	v_add_f32_e32 v132, 1.0, v132
	v_max_f32_e32 v136, 0x29e12e13, v134
	v_mul_f32_e32 v134, 0xbfb8aa3b, v100
	v_exp_f32_e32 v134, v134
	v_rcp_f32_e32 v138, v138
	v_rcp_f32_e32 v132, v132
	v_rcp_f32_e32 v148, v136
	v_add_f32_e32 v134, 1.0, v134
	v_rcp_f32_e32 v134, v134
	v_mul_f32_e32 v146, 0xbfb8aa3b, v107
	v_add_f32_e32 v142, 1.0, v142
	v_exp_f32_e32 v146, v146
	v_max_f32_e32 v137, 0x29e12e13, v134
	v_mul_f32_e32 v134, 0xbfb8aa3b, v113
	v_exp_f32_e32 v134, v134
	v_max_f32_e32 v138, 0x29e12e13, v138
	v_rcp_f32_e32 v142, v142
	v_mul_f32_e32 v132, v148, v132
	v_add_f32_e32 v134, 1.0, v134
	v_rcp_f32_e32 v134, v134
	v_rcp_f32_e32 v148, v138
	v_add_f32_e32 v146, 1.0, v146
	v_add_f32_e32 v140, 1.0, v140
	v_max_f32_e32 v142, 0x29e12e13, v142
	v_rcp_f32_e32 v146, v146
	v_rcp_f32_e32 v140, v140
	v_mul_f32_e32 v134, v148, v134
	v_rcp_f32_e32 v148, v142
	v_mul_f32_e32 v139, 0xbfb8aa3b, v101
	v_mul_f32_e32 v133, 0xbfb8aa3b, v108
	v_exp_f32_e32 v139, v139
	v_exp_f32_e32 v133, v133
	v_add_f32_e32 v144, 1.0, v144
	v_max_f32_e32 v146, 0x29e12e13, v146
	v_rcp_f32_e32 v144, v144
	v_mul_f32_e32 v140, v148, v140
	v_rcp_f32_e32 v148, v146
	v_mul_f32_e32 v143, 0xbfb8aa3b, v102
	v_mul_f32_e32 v135, 0xbfb8aa3b, v109
	v_add_f32_e32 v139, 1.0, v139
	v_exp_f32_e32 v143, v143
	v_add_f32_e32 v133, 1.0, v133
	v_exp_f32_e32 v135, v135
	v_rcp_f32_e32 v139, v139
	v_rcp_f32_e32 v133, v133
	v_mul_f32_e32 v144, v148, v144
	v_rcp_f32_e32 v148, v137
	v_mul_f32_e32 v147, 0xbfb8aa3b, v103
	v_mul_f32_e32 v141, 0xbfb8aa3b, v110
	v_add_f32_e32 v143, 1.0, v143
	v_exp_f32_e32 v147, v147
	v_add_f32_e32 v135, 1.0, v135
	v_max_f32_e32 v139, 0x29e12e13, v139
	v_exp_f32_e32 v141, v141
	v_rcp_f32_e32 v143, v143
	v_rcp_f32_e32 v135, v135
	v_mul_f32_e32 v148, v148, v133
	v_rcp_f32_e32 v133, v139
	v_mul_f32_e32 v145, 0xbfb8aa3b, v111
	v_add_f32_e32 v147, 1.0, v147
	v_add_f32_e32 v141, 1.0, v141
	v_max_f32_e32 v143, 0x29e12e13, v143
	v_exp_f32_e32 v145, v145
	v_rcp_f32_e32 v147, v147
	v_rcp_f32_e32 v141, v141
	v_mul_f32_e32 v135, v133, v135
	v_rcp_f32_e32 v133, v143
	v_add_f32_e32 v145, 1.0, v145
	v_max_f32_e32 v147, 0x29e12e13, v147
	v_rcp_f32_e32 v145, v145
	v_mul_f32_e32 v141, v133, v141
	v_rcp_f32_e32 v133, v147
	v_cvt_pk_bf16_f32 v132, v132, v134
	s_nop 0
	v_mul_f32_e32 v145, v133, v145
	v_cvt_pk_bf16_f32 v133, v140, v144
	v_cvt_pk_bf16_f32 v134, v148, v135
	v_add_u32_e32 v140, 0x10000, v2
	v_cvt_pk_bf16_f32 v135, v141, v145
	global_store_dwordx4 v140, v[132:135], s[2:3] sc0 sc1
	v_mul_f32_e32 v144, 0xbfb8aa3b, v99
	v_exp_f32_e32 v144, v144
	v_cvt_pk_bf16_f32 v132, v136, v138
	v_cvt_pk_bf16_f32 v133, v142, v146
	v_cvt_pk_bf16_f32 v134, v137, v139
	v_cvt_pk_bf16_f32 v135, v143, v147
	global_store_dwordx4 v140, v[132:135], s[6:7] sc0 sc1
	v_mul_f32_e32 v138, 0xbfb8aa3b, v89
	v_exp_f32_e32 v138, v138
	v_mul_f32_e32 v134, 0xbfb8aa3b, v88
	v_exp_f32_e32 v134, v134
	v_mul_f32_e32 v132, 0xbfb8aa3b, v96
	v_exp_f32_e32 v132, v132
	v_mul_f32_e32 v142, 0xbfb8aa3b, v90
	v_add_f32_e32 v134, 1.0, v134
	v_rcp_f32_e32 v134, v134
	v_add_f32_e32 v138, 1.0, v138
	v_exp_f32_e32 v142, v142
	v_add_f32_e32 v132, 1.0, v132
	v_max_f32_e32 v136, 0x29e12e13, v134
	v_mul_f32_e32 v134, 0xbfb8aa3b, v84
	v_exp_f32_e32 v134, v134
	v_rcp_f32_e32 v138, v138
	v_rcp_f32_e32 v132, v132
	v_rcp_f32_e32 v148, v136
	v_add_f32_e32 v134, 1.0, v134
	v_rcp_f32_e32 v134, v134
	v_mul_f32_e32 v146, 0xbfb8aa3b, v91
	v_mul_f32_e32 v140, 0xbfb8aa3b, v98
	v_add_f32_e32 v142, 1.0, v142
	v_max_f32_e32 v137, 0x29e12e13, v134
	v_mul_f32_e32 v134, 0xbfb8aa3b, v97
	v_exp_f32_e32 v134, v134
	v_exp_f32_e32 v146, v146
	v_max_f32_e32 v138, 0x29e12e13, v138
	v_exp_f32_e32 v140, v140
	v_add_f32_e32 v134, 1.0, v134
	v_rcp_f32_e32 v142, v142
	v_rcp_f32_e32 v134, v134
	v_mul_f32_e32 v132, v148, v132
	v_rcp_f32_e32 v148, v138
	v_add_f32_e32 v146, 1.0, v146
	v_add_f32_e32 v140, 1.0, v140
	v_max_f32_e32 v142, 0x29e12e13, v142
	v_rcp_f32_e32 v146, v146
	v_rcp_f32_e32 v140, v140
	v_mul_f32_e32 v134, v148, v134
	v_rcp_f32_e32 v148, v142
	v_mul_f32_e32 v139, 0xbfb8aa3b, v85
	v_mul_f32_e32 v133, 0xbfb8aa3b, v92
	v_exp_f32_e32 v139, v139
	v_exp_f32_e32 v133, v133
	v_add_f32_e32 v144, 1.0, v144
	v_max_f32_e32 v146, 0x29e12e13, v146
	v_rcp_f32_e32 v144, v144
	v_mul_f32_e32 v140, v148, v140
	v_rcp_f32_e32 v148, v146
	v_mul_f32_e32 v143, 0xbfb8aa3b, v86
	v_mul_f32_e32 v135, 0xbfb8aa3b, v93
	v_add_f32_e32 v139, 1.0, v139
	v_exp_f32_e32 v143, v143
	v_add_f32_e32 v133, 1.0, v133
	v_exp_f32_e32 v135, v135
	v_rcp_f32_e32 v139, v139
	v_rcp_f32_e32 v133, v133
	v_mul_f32_e32 v144, v148, v144
	v_rcp_f32_e32 v148, v137
	v_mul_f32_e32 v147, 0xbfb8aa3b, v87
	v_mul_f32_e32 v141, 0xbfb8aa3b, v94
	v_add_f32_e32 v143, 1.0, v143
	v_exp_f32_e32 v147, v147
	v_add_f32_e32 v135, 1.0, v135
	v_max_f32_e32 v139, 0x29e12e13, v139
	v_exp_f32_e32 v141, v141
	v_rcp_f32_e32 v143, v143
	v_rcp_f32_e32 v135, v135
	v_mul_f32_e32 v148, v148, v133
	v_rcp_f32_e32 v133, v139
	v_mul_f32_e32 v145, 0xbfb8aa3b, v95
	v_add_f32_e32 v147, 1.0, v147
	v_add_f32_e32 v141, 1.0, v141
	v_max_f32_e32 v143, 0x29e12e13, v143
	v_exp_f32_e32 v145, v145
	v_rcp_f32_e32 v147, v147
	v_rcp_f32_e32 v141, v141
	v_mul_f32_e32 v135, v133, v135
	v_rcp_f32_e32 v133, v143
	v_add_f32_e32 v145, 1.0, v145
	v_max_f32_e32 v147, 0x29e12e13, v147
	v_rcp_f32_e32 v145, v145
	v_mul_f32_e32 v141, v133, v141
	v_rcp_f32_e32 v133, v147
	v_cvt_pk_bf16_f32 v132, v132, v134
	s_nop 0
	v_mul_f32_e32 v145, v133, v145
	v_cvt_pk_bf16_f32 v133, v140, v144
	v_cvt_pk_bf16_f32 v134, v148, v135
	v_add_u32_e32 v140, 0x20000, v2
	v_cvt_pk_bf16_f32 v135, v141, v145
	global_store_dwordx4 v140, v[132:135], s[2:3] sc0 sc1
	v_mul_f32_e32 v144, 0xbfb8aa3b, v83
	v_exp_f32_e32 v144, v144
	v_cvt_pk_bf16_f32 v132, v136, v138
	v_cvt_pk_bf16_f32 v133, v142, v146
	v_cvt_pk_bf16_f32 v134, v137, v139
	v_cvt_pk_bf16_f32 v135, v143, v147
	global_store_dwordx4 v140, v[132:135], s[6:7] sc0 sc1
	v_mul_f32_e32 v138, 0xbfb8aa3b, v73
	v_exp_f32_e32 v138, v138
	v_mul_f32_e32 v134, 0xbfb8aa3b, v72
	v_exp_f32_e32 v134, v134
	v_mul_f32_e32 v132, 0xbfb8aa3b, v80
	v_exp_f32_e32 v132, v132
	v_mul_f32_e32 v142, 0xbfb8aa3b, v74
	v_add_f32_e32 v134, 1.0, v134
	v_rcp_f32_e32 v134, v134
	v_add_f32_e32 v138, 1.0, v138
	v_exp_f32_e32 v142, v142
	v_add_f32_e32 v132, 1.0, v132
	v_max_f32_e32 v136, 0x29e12e13, v134
	v_mul_f32_e32 v134, 0xbfb8aa3b, v68
	v_exp_f32_e32 v134, v134
	v_rcp_f32_e32 v138, v138
	v_rcp_f32_e32 v132, v132
	v_rcp_f32_e32 v148, v136
	v_add_f32_e32 v134, 1.0, v134
	v_rcp_f32_e32 v134, v134
	v_mul_f32_e32 v146, 0xbfb8aa3b, v75
	v_mul_f32_e32 v140, 0xbfb8aa3b, v82
	v_add_f32_e32 v142, 1.0, v142
	v_max_f32_e32 v137, 0x29e12e13, v134
	v_mul_f32_e32 v134, 0xbfb8aa3b, v81
	v_exp_f32_e32 v134, v134
	v_exp_f32_e32 v146, v146
	v_max_f32_e32 v138, 0x29e12e13, v138
	v_exp_f32_e32 v140, v140
	v_add_f32_e32 v134, 1.0, v134
	v_rcp_f32_e32 v142, v142
	v_rcp_f32_e32 v134, v134
	v_mul_f32_e32 v132, v148, v132
	v_rcp_f32_e32 v148, v138
	v_add_f32_e32 v146, 1.0, v146
	v_add_f32_e32 v140, 1.0, v140
	v_max_f32_e32 v142, 0x29e12e13, v142
	v_rcp_f32_e32 v146, v146
	v_rcp_f32_e32 v140, v140
	v_mul_f32_e32 v134, v148, v134
	v_rcp_f32_e32 v148, v142
	v_mul_f32_e32 v139, 0xbfb8aa3b, v69
	v_mul_f32_e32 v133, 0xbfb8aa3b, v76
	v_exp_f32_e32 v139, v139
	v_exp_f32_e32 v133, v133
	v_add_f32_e32 v144, 1.0, v144
	v_max_f32_e32 v146, 0x29e12e13, v146
	v_rcp_f32_e32 v144, v144
	v_mul_f32_e32 v140, v148, v140
	v_rcp_f32_e32 v148, v146
	v_mul_f32_e32 v143, 0xbfb8aa3b, v70
	v_mul_f32_e32 v135, 0xbfb8aa3b, v77
	v_add_f32_e32 v139, 1.0, v139
	v_exp_f32_e32 v143, v143
	v_add_f32_e32 v133, 1.0, v133
	v_exp_f32_e32 v135, v135
	v_rcp_f32_e32 v139, v139
	v_rcp_f32_e32 v133, v133
	v_mul_f32_e32 v144, v148, v144
	v_rcp_f32_e32 v148, v137
	v_mul_f32_e32 v147, 0xbfb8aa3b, v71
	v_mul_f32_e32 v141, 0xbfb8aa3b, v78
	v_add_f32_e32 v143, 1.0, v143
	v_exp_f32_e32 v147, v147
	v_add_f32_e32 v135, 1.0, v135
	v_max_f32_e32 v139, 0x29e12e13, v139
	v_exp_f32_e32 v141, v141
	v_rcp_f32_e32 v143, v143
	v_rcp_f32_e32 v135, v135
	v_mul_f32_e32 v148, v148, v133
	v_rcp_f32_e32 v133, v139
	v_mul_f32_e32 v145, 0xbfb8aa3b, v79
	v_add_f32_e32 v147, 1.0, v147
	v_add_f32_e32 v141, 1.0, v141
	v_max_f32_e32 v143, 0x29e12e13, v143
	v_exp_f32_e32 v145, v145
	v_rcp_f32_e32 v147, v147
	v_rcp_f32_e32 v141, v141
	v_mul_f32_e32 v135, v133, v135
	v_rcp_f32_e32 v133, v143
	v_add_f32_e32 v145, 1.0, v145
	v_max_f32_e32 v147, 0x29e12e13, v147
	v_rcp_f32_e32 v145, v145
	v_mul_f32_e32 v141, v133, v141
	v_rcp_f32_e32 v133, v147
	v_cvt_pk_bf16_f32 v132, v132, v134
	s_nop 0
	v_mul_f32_e32 v145, v133, v145
	v_cvt_pk_bf16_f32 v133, v140, v144
	v_cvt_pk_bf16_f32 v134, v148, v135
	v_add_u32_e32 v140, 0x30000, v2
	v_cvt_pk_bf16_f32 v135, v141, v145
	global_store_dwordx4 v140, v[132:135], s[2:3] sc0 sc1
	v_mul_f32_e32 v141, 0xbfb8aa3b, v66
	v_exp_f32_e32 v141, v141
	v_cvt_pk_bf16_f32 v132, v136, v138
	v_cvt_pk_bf16_f32 v133, v142, v146
	v_cvt_pk_bf16_f32 v134, v137, v139
	v_cvt_pk_bf16_f32 v135, v143, v147
	global_store_dwordx4 v140, v[132:135], s[6:7] sc0 sc1
	v_mul_f32_e32 v139, 0xbfb8aa3b, v57
	v_exp_f32_e32 v139, v139
	v_mul_f32_e32 v134, 0xbfb8aa3b, v56
	v_exp_f32_e32 v134, v134
	v_mul_f32_e32 v132, 0xbfb8aa3b, v64
	v_exp_f32_e32 v132, v132
	v_mul_f32_e32 v143, 0xbfb8aa3b, v58
	v_add_f32_e32 v134, 1.0, v134
	v_rcp_f32_e32 v134, v134
	v_add_f32_e32 v139, 1.0, v139
	v_exp_f32_e32 v143, v143
	v_add_f32_e32 v132, 1.0, v132
	v_max_f32_e32 v137, 0x29e12e13, v134
	v_mul_f32_e32 v134, 0xbfb8aa3b, v52
	v_exp_f32_e32 v134, v134
	v_rcp_f32_e32 v139, v139
	v_rcp_f32_e32 v132, v132
	v_rcp_f32_e32 v149, v137
	v_add_f32_e32 v134, 1.0, v134
	v_rcp_f32_e32 v134, v134
	v_mul_f32_e32 v147, 0xbfb8aa3b, v59
	v_add_f32_e32 v143, 1.0, v143
	v_exp_f32_e32 v147, v147
	v_max_f32_e32 v138, 0x29e12e13, v134
	v_mul_f32_e32 v134, 0xbfb8aa3b, v65
	v_exp_f32_e32 v134, v134
	v_max_f32_e32 v139, 0x29e12e13, v139
	v_rcp_f32_e32 v143, v143
	v_mul_f32_e32 v132, v149, v132
	v_add_f32_e32 v134, 1.0, v134
	v_rcp_f32_e32 v134, v134
	v_rcp_f32_e32 v149, v139
	v_mul_f32_e32 v145, 0xbfb8aa3b, v67
	v_add_f32_e32 v147, 1.0, v147
	v_add_f32_e32 v141, 1.0, v141
	v_max_f32_e32 v143, 0x29e12e13, v143
	v_exp_f32_e32 v145, v145
	v_rcp_f32_e32 v147, v147
	v_rcp_f32_e32 v141, v141
	v_mul_f32_e32 v134, v149, v134
	v_rcp_f32_e32 v149, v143
	v_mul_f32_e32 v140, 0xbfb8aa3b, v53
	v_mul_f32_e32 v133, 0xbfb8aa3b, v60
	v_exp_f32_e32 v140, v140
	v_exp_f32_e32 v133, v133
	v_add_f32_e32 v145, 1.0, v145
	v_max_f32_e32 v147, 0x29e12e13, v147
	v_rcp_f32_e32 v145, v145
	v_mul_f32_e32 v141, v149, v141
	v_rcp_f32_e32 v149, v147
	v_mul_f32_e32 v144, 0xbfb8aa3b, v54
	v_mul_f32_e32 v135, 0xbfb8aa3b, v61
	v_add_f32_e32 v140, 1.0, v140
	v_exp_f32_e32 v144, v144
	v_add_f32_e32 v133, 1.0, v133
	v_exp_f32_e32 v135, v135
	v_rcp_f32_e32 v140, v140
	v_rcp_f32_e32 v133, v133
	v_mul_f32_e32 v145, v149, v145
	v_rcp_f32_e32 v149, v138
	v_mul_f32_e32 v148, 0xbfb8aa3b, v55
	v_mul_f32_e32 v142, 0xbfb8aa3b, v62
	v_add_f32_e32 v144, 1.0, v144
	v_exp_f32_e32 v148, v148
	v_add_f32_e32 v135, 1.0, v135
	v_max_f32_e32 v140, 0x29e12e13, v140
	v_exp_f32_e32 v142, v142
	v_rcp_f32_e32 v144, v144
	v_rcp_f32_e32 v135, v135
	v_mul_f32_e32 v149, v149, v133
	v_rcp_f32_e32 v133, v140
	v_mul_f32_e32 v146, 0xbfb8aa3b, v63
	v_add_f32_e32 v148, 1.0, v148
	v_add_f32_e32 v142, 1.0, v142
	v_max_f32_e32 v144, 0x29e12e13, v144
	v_exp_f32_e32 v146, v146
	v_rcp_f32_e32 v148, v148
	v_rcp_f32_e32 v142, v142
	v_mul_f32_e32 v135, v133, v135
	v_rcp_f32_e32 v133, v144
	v_add_f32_e32 v146, 1.0, v146
	v_max_f32_e32 v148, 0x29e12e13, v148
	v_rcp_f32_e32 v146, v146
	v_mul_f32_e32 v142, v133, v142
	v_rcp_f32_e32 v133, v148
	v_add_u32_e32 v136, 0x80000, v2
	v_cvt_pk_bf16_f32 v132, v132, v134
	v_mul_f32_e32 v146, v133, v146
	v_cvt_pk_bf16_f32 v133, v141, v145
	v_cvt_pk_bf16_f32 v134, v149, v135
	v_cvt_pk_bf16_f32 v135, v142, v146
	global_store_dwordx4 v136, v[132:135], s[2:3] sc0 sc1
	v_mul_f32_e32 v142, 0xbfb8aa3b, v42
	v_exp_f32_e32 v142, v142
	v_cvt_pk_bf16_f32 v132, v137, v139
	v_cvt_pk_bf16_f32 v133, v143, v147
	v_cvt_pk_bf16_f32 v134, v138, v140
	v_cvt_pk_bf16_f32 v135, v144, v148
	global_store_dwordx4 v136, v[132:135], s[6:7] sc0 sc1
	v_mul_f32_e32 v138, 0xbfb8aa3b, v41
	v_exp_f32_e32 v138, v138
	v_mul_f32_e32 v134, 0xbfb8aa3b, v40
	v_exp_f32_e32 v134, v134
	v_mul_f32_e32 v132, 0xbfb8aa3b, v48
	v_exp_f32_e32 v132, v132
	v_add_f32_e32 v138, 1.0, v138
	v_add_f32_e32 v134, 1.0, v134
	v_rcp_f32_e32 v134, v134
	v_add_f32_e32 v132, 1.0, v132
	v_rcp_f32_e32 v138, v138
	v_rcp_f32_e32 v132, v132
	v_max_f32_e32 v136, 0x29e12e13, v134
	v_mul_f32_e32 v134, 0xbfb8aa3b, v36
	v_exp_f32_e32 v134, v134
	v_rcp_f32_e32 v148, v136
	v_mul_f32_e32 v146, 0xbfb8aa3b, v43
	v_mul_f32_e32 v140, 0xbfb8aa3b, v50
	v_add_f32_e32 v134, 1.0, v134
	v_rcp_f32_e32 v134, v134
	v_add_f32_e32 v142, 1.0, v142
	v_exp_f32_e32 v146, v146
	v_max_f32_e32 v138, 0x29e12e13, v138
	v_max_f32_e32 v137, 0x29e12e13, v134
	v_mul_f32_e32 v134, 0xbfb8aa3b, v49
	v_exp_f32_e32 v134, v134
	v_exp_f32_e32 v140, v140
	v_rcp_f32_e32 v142, v142
	v_mul_f32_e32 v132, v148, v132
	v_add_f32_e32 v134, 1.0, v134
	v_rcp_f32_e32 v134, v134
	v_rcp_f32_e32 v148, v138
	v_mul_f32_e32 v144, 0xbfb8aa3b, v51
	v_add_f32_e32 v146, 1.0, v146
	v_add_f32_e32 v140, 1.0, v140
	v_max_f32_e32 v142, 0x29e12e13, v142
	v_exp_f32_e32 v144, v144
	v_rcp_f32_e32 v146, v146
	v_rcp_f32_e32 v140, v140
	v_mul_f32_e32 v134, v148, v134
	v_rcp_f32_e32 v148, v142
	v_mul_f32_e32 v139, 0xbfb8aa3b, v37
	v_mul_f32_e32 v133, 0xbfb8aa3b, v44
	v_exp_f32_e32 v139, v139
	v_exp_f32_e32 v133, v133
	v_add_f32_e32 v144, 1.0, v144
	v_max_f32_e32 v146, 0x29e12e13, v146
	v_rcp_f32_e32 v144, v144
	v_mul_f32_e32 v140, v148, v140
	v_rcp_f32_e32 v148, v146
	v_mul_f32_e32 v143, 0xbfb8aa3b, v38
	v_mul_f32_e32 v135, 0xbfb8aa3b, v45
	v_add_f32_e32 v139, 1.0, v139
	v_exp_f32_e32 v143, v143
	v_add_f32_e32 v133, 1.0, v133
	v_exp_f32_e32 v135, v135
	v_rcp_f32_e32 v139, v139
	v_rcp_f32_e32 v133, v133
	v_mul_f32_e32 v144, v148, v144
	v_rcp_f32_e32 v148, v137
	v_mul_f32_e32 v147, 0xbfb8aa3b, v39
	v_mul_f32_e32 v141, 0xbfb8aa3b, v46
	v_add_f32_e32 v143, 1.0, v143
	v_exp_f32_e32 v147, v147
	v_add_f32_e32 v135, 1.0, v135
	v_max_f32_e32 v139, 0x29e12e13, v139
	v_exp_f32_e32 v141, v141
	v_rcp_f32_e32 v143, v143
	v_rcp_f32_e32 v135, v135
	v_mul_f32_e32 v148, v148, v133
	v_rcp_f32_e32 v133, v139
	v_mul_f32_e32 v145, 0xbfb8aa3b, v47
	v_add_f32_e32 v147, 1.0, v147
	v_add_f32_e32 v141, 1.0, v141
	v_max_f32_e32 v143, 0x29e12e13, v143
	v_exp_f32_e32 v145, v145
	v_rcp_f32_e32 v147, v147
	v_rcp_f32_e32 v141, v141
	v_mul_f32_e32 v135, v133, v135
	v_rcp_f32_e32 v133, v143
	v_add_f32_e32 v145, 1.0, v145
	v_max_f32_e32 v147, 0x29e12e13, v147
	v_rcp_f32_e32 v145, v145
	v_mul_f32_e32 v141, v133, v141
	v_rcp_f32_e32 v133, v147
	v_cvt_pk_bf16_f32 v132, v132, v134
	s_nop 0
	v_mul_f32_e32 v145, v133, v145
	v_cvt_pk_bf16_f32 v133, v140, v144
	v_cvt_pk_bf16_f32 v134, v148, v135
	v_add_u32_e32 v140, 0x90000, v2
	v_cvt_pk_bf16_f32 v135, v141, v145
	global_store_dwordx4 v140, v[132:135], s[2:3] sc0 sc1
	v_mul_f32_e32 v144, 0xbfb8aa3b, v35
	v_exp_f32_e32 v144, v144
	v_cvt_pk_bf16_f32 v132, v136, v138
	v_cvt_pk_bf16_f32 v133, v142, v146
	v_cvt_pk_bf16_f32 v134, v137, v139
	v_cvt_pk_bf16_f32 v135, v143, v147
	global_store_dwordx4 v140, v[132:135], s[6:7] sc0 sc1
	v_mul_f32_e32 v138, 0xbfb8aa3b, v25
	v_exp_f32_e32 v138, v138
	v_mul_f32_e32 v134, 0xbfb8aa3b, v24
	v_exp_f32_e32 v134, v134
	v_mul_f32_e32 v132, 0xbfb8aa3b, v32
	v_exp_f32_e32 v132, v132
	v_mul_f32_e32 v142, 0xbfb8aa3b, v26
	v_add_f32_e32 v134, 1.0, v134
	v_rcp_f32_e32 v134, v134
	v_add_f32_e32 v138, 1.0, v138
	v_exp_f32_e32 v142, v142
	v_add_f32_e32 v132, 1.0, v132
	v_max_f32_e32 v136, 0x29e12e13, v134
	v_mul_f32_e32 v134, 0xbfb8aa3b, v20
	v_exp_f32_e32 v134, v134
	v_rcp_f32_e32 v138, v138
	v_rcp_f32_e32 v132, v132
	v_rcp_f32_e32 v148, v136
	v_add_f32_e32 v134, 1.0, v134
	v_rcp_f32_e32 v134, v134
	v_mul_f32_e32 v146, 0xbfb8aa3b, v27
	v_mul_f32_e32 v140, 0xbfb8aa3b, v34
	v_add_f32_e32 v142, 1.0, v142
	v_max_f32_e32 v137, 0x29e12e13, v134
	v_mul_f32_e32 v134, 0xbfb8aa3b, v33
	v_exp_f32_e32 v134, v134
	v_exp_f32_e32 v146, v146
	v_max_f32_e32 v138, 0x29e12e13, v138
	v_exp_f32_e32 v140, v140
	v_add_f32_e32 v134, 1.0, v134
	v_rcp_f32_e32 v142, v142
	v_rcp_f32_e32 v134, v134
	v_mul_f32_e32 v132, v148, v132
	v_rcp_f32_e32 v148, v138
	v_add_f32_e32 v146, 1.0, v146
	v_add_f32_e32 v140, 1.0, v140
	v_max_f32_e32 v142, 0x29e12e13, v142
	v_rcp_f32_e32 v146, v146
	v_rcp_f32_e32 v140, v140
	v_mul_f32_e32 v134, v148, v134
	v_rcp_f32_e32 v148, v142
	v_mul_f32_e32 v139, 0xbfb8aa3b, v21
	v_mul_f32_e32 v133, 0xbfb8aa3b, v28
	v_exp_f32_e32 v139, v139
	v_exp_f32_e32 v133, v133
	v_add_f32_e32 v144, 1.0, v144
	v_max_f32_e32 v146, 0x29e12e13, v146
	v_rcp_f32_e32 v144, v144
	v_mul_f32_e32 v140, v148, v140
	v_rcp_f32_e32 v148, v146
	v_mul_f32_e32 v143, 0xbfb8aa3b, v22
	v_mul_f32_e32 v135, 0xbfb8aa3b, v29
	v_add_f32_e32 v139, 1.0, v139
	v_exp_f32_e32 v143, v143
	v_add_f32_e32 v133, 1.0, v133
	v_exp_f32_e32 v135, v135
	v_rcp_f32_e32 v139, v139
	v_rcp_f32_e32 v133, v133
	v_mul_f32_e32 v144, v148, v144
	v_rcp_f32_e32 v148, v137
	v_mul_f32_e32 v147, 0xbfb8aa3b, v23
	v_mul_f32_e32 v141, 0xbfb8aa3b, v30
	v_add_f32_e32 v143, 1.0, v143
	v_exp_f32_e32 v147, v147
	v_add_f32_e32 v135, 1.0, v135
	v_max_f32_e32 v139, 0x29e12e13, v139
	v_exp_f32_e32 v141, v141
	v_rcp_f32_e32 v143, v143
	v_rcp_f32_e32 v135, v135
	v_mul_f32_e32 v148, v148, v133
	v_rcp_f32_e32 v133, v139
	v_mul_f32_e32 v145, 0xbfb8aa3b, v31
	v_add_f32_e32 v147, 1.0, v147
	v_add_f32_e32 v141, 1.0, v141
	v_max_f32_e32 v143, 0x29e12e13, v143
	v_exp_f32_e32 v145, v145
	v_rcp_f32_e32 v147, v147
	v_rcp_f32_e32 v141, v141
	v_mul_f32_e32 v135, v133, v135
	v_rcp_f32_e32 v133, v143
	v_add_f32_e32 v145, 1.0, v145
	v_max_f32_e32 v147, 0x29e12e13, v147
	v_rcp_f32_e32 v145, v145
	v_mul_f32_e32 v141, v133, v141
	v_rcp_f32_e32 v133, v147
	v_cvt_pk_bf16_f32 v132, v132, v134
	s_nop 0
	v_mul_f32_e32 v145, v133, v145
	v_cvt_pk_bf16_f32 v133, v140, v144
	v_cvt_pk_bf16_f32 v134, v148, v135
	v_add_u32_e32 v140, 0xa0000, v2
	v_cvt_pk_bf16_f32 v135, v141, v145
	global_store_dwordx4 v140, v[132:135], s[2:3] sc0 sc1
	v_mul_f32_e32 v144, 0xbfb8aa3b, v19
	v_exp_f32_e32 v144, v144
	v_cvt_pk_bf16_f32 v132, v136, v138
	v_cvt_pk_bf16_f32 v133, v142, v146
	v_cvt_pk_bf16_f32 v134, v137, v139
	v_cvt_pk_bf16_f32 v135, v143, v147
	global_store_dwordx4 v140, v[132:135], s[6:7] sc0 sc1
	v_mul_f32_e32 v138, 0xbfb8aa3b, v9
	v_exp_f32_e32 v138, v138
	v_mul_f32_e32 v134, 0xbfb8aa3b, v8
	v_exp_f32_e32 v134, v134
	v_mul_f32_e32 v132, 0xbfb8aa3b, v16
	v_exp_f32_e32 v132, v132
	v_mul_f32_e32 v142, 0xbfb8aa3b, v10
	v_add_f32_e32 v134, 1.0, v134
	v_rcp_f32_e32 v134, v134
	v_add_f32_e32 v138, 1.0, v138
	v_exp_f32_e32 v142, v142
	v_add_f32_e32 v132, 1.0, v132
	v_max_f32_e32 v136, 0x29e12e13, v134
	v_mul_f32_e32 v134, 0xbfb8aa3b, v4
	v_exp_f32_e32 v134, v134
	v_rcp_f32_e32 v138, v138
	v_rcp_f32_e32 v132, v132
	v_rcp_f32_e32 v148, v136
	v_add_f32_e32 v134, 1.0, v134
	v_rcp_f32_e32 v134, v134
	v_mul_f32_e32 v146, 0xbfb8aa3b, v11
	v_mul_f32_e32 v140, 0xbfb8aa3b, v18
	v_add_f32_e32 v142, 1.0, v142
	v_max_f32_e32 v137, 0x29e12e13, v134
	v_mul_f32_e32 v134, 0xbfb8aa3b, v17
	v_exp_f32_e32 v134, v134
	v_exp_f32_e32 v146, v146
	v_max_f32_e32 v138, 0x29e12e13, v138
	v_exp_f32_e32 v140, v140
	v_add_f32_e32 v134, 1.0, v134
	v_rcp_f32_e32 v142, v142
	v_rcp_f32_e32 v134, v134
	v_mul_f32_e32 v132, v148, v132
	v_rcp_f32_e32 v148, v138
	v_add_f32_e32 v146, 1.0, v146
	v_add_f32_e32 v140, 1.0, v140
	v_max_f32_e32 v142, 0x29e12e13, v142
	v_rcp_f32_e32 v146, v146
	v_rcp_f32_e32 v140, v140
	v_mul_f32_e32 v134, v148, v134
	v_rcp_f32_e32 v148, v142
	v_mul_f32_e32 v139, 0xbfb8aa3b, v5
	v_mul_f32_e32 v133, 0xbfb8aa3b, v12
	v_exp_f32_e32 v139, v139
	v_exp_f32_e32 v133, v133
	v_add_f32_e32 v144, 1.0, v144
	v_max_f32_e32 v146, 0x29e12e13, v146
	v_rcp_f32_e32 v144, v144
	v_mul_f32_e32 v140, v148, v140
	v_rcp_f32_e32 v148, v146
	v_mul_f32_e32 v143, 0xbfb8aa3b, v6
	v_mul_f32_e32 v135, 0xbfb8aa3b, v13
	v_add_f32_e32 v139, 1.0, v139
	v_exp_f32_e32 v143, v143
	v_add_f32_e32 v133, 1.0, v133
	v_exp_f32_e32 v135, v135
	v_rcp_f32_e32 v139, v139
	v_rcp_f32_e32 v133, v133
	v_mul_f32_e32 v144, v148, v144
	v_rcp_f32_e32 v148, v137
	v_mul_f32_e32 v147, 0xbfb8aa3b, v7
	v_mul_f32_e32 v141, 0xbfb8aa3b, v14
	v_add_f32_e32 v143, 1.0, v143
	v_exp_f32_e32 v147, v147
	v_add_f32_e32 v135, 1.0, v135
	v_max_f32_e32 v139, 0x29e12e13, v139
	v_exp_f32_e32 v141, v141
	v_rcp_f32_e32 v143, v143
	v_rcp_f32_e32 v135, v135
	v_mul_f32_e32 v148, v148, v133
	v_rcp_f32_e32 v133, v139
	v_mul_f32_e32 v145, 0xbfb8aa3b, v15
	v_add_f32_e32 v147, 1.0, v147
	v_add_f32_e32 v141, 1.0, v141
	v_max_f32_e32 v143, 0x29e12e13, v143
	v_exp_f32_e32 v145, v145
	v_rcp_f32_e32 v147, v147
	v_rcp_f32_e32 v141, v141
	v_mul_f32_e32 v135, v133, v135
	v_rcp_f32_e32 v133, v143
	v_add_f32_e32 v145, 1.0, v145
	v_max_f32_e32 v147, 0x29e12e13, v147
	v_rcp_f32_e32 v145, v145
	v_mul_f32_e32 v141, v133, v141
	v_rcp_f32_e32 v133, v147
	v_cvt_pk_bf16_f32 v132, v132, v134
	v_add_u32_e32 v2, 0xb0000, v2
	v_mul_f32_e32 v145, v133, v145
	v_cvt_pk_bf16_f32 v133, v140, v144
	v_cvt_pk_bf16_f32 v134, v148, v135
	v_cvt_pk_bf16_f32 v135, v141, v145
	global_store_dwordx4 v2, v[132:135], s[2:3] sc0 sc1
	s_nop 1
	v_cvt_pk_bf16_f32 v132, v136, v138
	v_cvt_pk_bf16_f32 v133, v142, v146
	v_cvt_pk_bf16_f32 v134, v137, v139
	v_cvt_pk_bf16_f32 v135, v143, v147
	global_store_dwordx4 v2, v[132:135], s[6:7] sc0 sc1
	s_mov_b64 s[6:7], 0
.Lwt_BB0_571:
	s_andn2_b64 vcc, exec, s[6:7]
	s_cbranch_vccnz .Lwt_BB0_576
	s_add_i32 s10, s26, -8
	s_lshr_b32 s6, s10, 2
	s_mul_hi_u32 s7, s6, 0x1400000
	s_mul_i32 s6, s6, 0x1400000
	v_readlane_b32 s2, v250, 13
	v_readlane_b32 s3, v250, 14
	s_add_u32 s6, s2, s6
	s_addc_u32 s7, s3, s7
	s_lshl_b32 s8, s26, 9
	s_and_b32 s8, s8, 0x600
	s_add_u32 s6, s6, s8
	s_addc_u32 s7, s7, 0
	s_cmp_gt_i32 s27, 31
	s_cselect_b64 s[8:9], -1, 0
	s_cmp_lt_u32 s10, 8
	s_cselect_b64 s[10:11], -1, 0
	v_lshl_or_b32 v220, v208, 11, v194
	s_and_b64 s[10:11], s[8:9], s[10:11]
	s_mov_b64 s[8:9], -1
	s_and_b64 vcc, exec, s[10:11]
	v_or_b32_e32 v218, 0x8000, v220
	v_or_b32_e32 v217, 0x8100, v220
	v_or_b32_e32 v167, 0x10000, v220
	v_or_b32_e32 v166, 0x10100, v220
	v_or_b32_e32 v165, 0x18000, v220
	v_or_b32_e32 v164, 0x18100, v220
	v_add_u32_e32 v216, 0x40000, v220
	v_add_u32_e32 v215, 0x40100, v220
	v_add_u32_e32 v214, 0x48000, v220
	v_add_u32_e32 v213, 0x48100, v220
	v_add_u32_e32 v212, 0x50000, v220
	v_add_u32_e32 v211, 0x50100, v220
	v_add_u32_e32 v209, 0x58000, v220
	v_add_u32_e32 v2, 0x58100, v220
	s_cbranch_vccnz .Lwt_BB0_574
	v_cvt_pk_bf16_f32 v132, v128, v129
	v_cvt_pk_bf16_f32 v133, v130, v131
	v_cvt_pk_bf16_f32 v134, v124, v125
	v_cvt_pk_bf16_f32 v135, v126, v127
	global_store_dwordx4 v220, v[132:135], s[6:7] sc0 sc1
	s_mov_b64 s[8:9], 0
	s_nop 0
	v_cvt_pk_bf16_f32 v132, v120, v121
	v_cvt_pk_bf16_f32 v133, v122, v123
	v_cvt_pk_bf16_f32 v134, v116, v117
	v_cvt_pk_bf16_f32 v135, v118, v119
	global_store_dwordx4 v220, v[132:135], s[6:7] offset:256 sc0 sc1
	s_nop 1
	v_cvt_pk_bf16_f32 v132, v112, v113
	v_cvt_pk_bf16_f32 v133, v114, v115
	v_cvt_pk_bf16_f32 v134, v108, v109
	v_cvt_pk_bf16_f32 v135, v110, v111
	global_store_dwordx4 v218, v[132:135], s[6:7] sc0 sc1
	s_nop 1
	v_cvt_pk_bf16_f32 v132, v104, v105
	v_cvt_pk_bf16_f32 v133, v106, v107
	v_cvt_pk_bf16_f32 v134, v100, v101
	v_cvt_pk_bf16_f32 v135, v102, v103
	global_store_dwordx4 v217, v[132:135], s[6:7] sc0 sc1
	s_nop 1
	v_cvt_pk_bf16_f32 v132, v96, v97
	v_cvt_pk_bf16_f32 v133, v98, v99
	v_cvt_pk_bf16_f32 v134, v92, v93
	v_cvt_pk_bf16_f32 v135, v94, v95
	global_store_dwordx4 v167, v[132:135], s[6:7] sc0 sc1
	s_nop 1
	v_cvt_pk_bf16_f32 v132, v88, v89
	v_cvt_pk_bf16_f32 v133, v90, v91
	v_cvt_pk_bf16_f32 v134, v84, v85
	v_cvt_pk_bf16_f32 v135, v86, v87
	global_store_dwordx4 v166, v[132:135], s[6:7] sc0 sc1
	s_nop 1
	v_cvt_pk_bf16_f32 v132, v80, v81
	v_cvt_pk_bf16_f32 v133, v82, v83
	v_cvt_pk_bf16_f32 v134, v76, v77
	v_cvt_pk_bf16_f32 v135, v78, v79
	global_store_dwordx4 v165, v[132:135], s[6:7] sc0 sc1
	s_nop 1
	v_cvt_pk_bf16_f32 v132, v72, v73
	v_cvt_pk_bf16_f32 v133, v74, v75
	v_cvt_pk_bf16_f32 v134, v68, v69
	v_cvt_pk_bf16_f32 v135, v70, v71
	global_store_dwordx4 v164, v[132:135], s[6:7] sc0 sc1
	s_nop 1
	v_cvt_pk_bf16_f32 v132, v64, v65
	v_cvt_pk_bf16_f32 v133, v66, v67
	v_cvt_pk_bf16_f32 v134, v60, v61
	v_cvt_pk_bf16_f32 v135, v62, v63
	global_store_dwordx4 v216, v[132:135], s[6:7] sc0 sc1
	s_nop 1
	v_cvt_pk_bf16_f32 v132, v56, v57
	v_cvt_pk_bf16_f32 v133, v58, v59
	v_cvt_pk_bf16_f32 v134, v52, v53
	v_cvt_pk_bf16_f32 v135, v54, v55
	global_store_dwordx4 v215, v[132:135], s[6:7] sc0 sc1
	s_nop 1
	v_cvt_pk_bf16_f32 v132, v48, v49
	v_cvt_pk_bf16_f32 v133, v50, v51
	v_cvt_pk_bf16_f32 v134, v44, v45
	v_cvt_pk_bf16_f32 v135, v46, v47
	global_store_dwordx4 v214, v[132:135], s[6:7] sc0 sc1
	s_nop 1
	v_cvt_pk_bf16_f32 v132, v40, v41
	v_cvt_pk_bf16_f32 v133, v42, v43
	v_cvt_pk_bf16_f32 v134, v36, v37
	v_cvt_pk_bf16_f32 v135, v38, v39
	global_store_dwordx4 v213, v[132:135], s[6:7] sc0 sc1
	s_nop 1
	v_cvt_pk_bf16_f32 v132, v32, v33
	v_cvt_pk_bf16_f32 v133, v34, v35
	v_cvt_pk_bf16_f32 v134, v28, v29
	v_cvt_pk_bf16_f32 v135, v30, v31
	global_store_dwordx4 v212, v[132:135], s[6:7] sc0 sc1
	s_nop 1
	v_cvt_pk_bf16_f32 v132, v24, v25
	v_cvt_pk_bf16_f32 v133, v26, v27
	v_cvt_pk_bf16_f32 v134, v20, v21
	v_cvt_pk_bf16_f32 v135, v22, v23
	global_store_dwordx4 v211, v[132:135], s[6:7] sc0 sc1
	s_nop 1
	v_cvt_pk_bf16_f32 v132, v16, v17
	v_cvt_pk_bf16_f32 v133, v18, v19
	v_cvt_pk_bf16_f32 v134, v12, v13
	v_cvt_pk_bf16_f32 v135, v14, v15
	global_store_dwordx4 v209, v[132:135], s[6:7] sc0 sc1
	s_nop 1
	v_cvt_pk_bf16_f32 v132, v8, v9
	v_cvt_pk_bf16_f32 v133, v10, v11
	v_cvt_pk_bf16_f32 v134, v4, v5
	v_cvt_pk_bf16_f32 v135, v6, v7
	global_store_dwordx4 v2, v[132:135], s[6:7] sc0 sc1
.Lwt_BB0_574:
	s_andn2_b64 vcc, exec, s[8:9]
	s_cbranch_vccnz .Lwt_BB0_576
	v_and_b32_e32 v133, 64, v204
	s_lshl_b32 s8, s27, 2
	v_xor_b32_e32 v132, 32, v204
	v_add_u32_e32 v133, 64, v133
	s_and_b32 s8, s8, 12
	v_cmp_lt_i32_e32 vcc, v132, v133
	s_add_i32 s8, s8, s14
	v_mov_b32_e32 v219, s8
	v_cndmask_b32_e32 v132, v204, v132, vcc
	v_lshlrev_b32_e32 v210, 2, v132
	v_cndmask_b32_e64 v132, v1, v219, s[38:39]
	v_readlane_b32 s2, v252, 3
	v_lshl_or_b32 v132, v132, 7, v195
	v_readlane_b32 s3, v252, 4
	s_nop 4
	global_load_dwordx4 v[136:139], v132, s[2:3] offset:48
	global_load_dwordx4 v[144:147], v132, s[2:3] offset:32
	global_load_dwordx4 v[152:155], v132, s[2:3] offset:16
	global_load_dwordx4 v[160:163], v132, s[2:3]
	v_cndmask_b32_e64 v132, v196, v219, s[38:39]
	v_lshl_or_b32 v156, v132, 7, v195
	global_load_dwordx4 v[132:135], v156, s[2:3] offset:48
	global_load_dwordx4 v[140:143], v156, s[2:3] offset:32
	global_load_dwordx4 v[148:151], v156, s[2:3] offset:16
	s_nop 0
	global_load_dwordx4 v[156:159], v156, s[2:3]
	ds_bpermute_b32 v221, v210, v128
	ds_bpermute_b32 v222, v210, v129
	ds_bpermute_b32 v223, v210, v130
	ds_bpermute_b32 v224, v210, v131
	ds_bpermute_b32 v225, v210, v124
	ds_bpermute_b32 v226, v210, v125
	ds_bpermute_b32 v227, v210, v126
	ds_bpermute_b32 v228, v210, v127
	s_add_i32 s8, s8, 2
	s_waitcnt vmcnt(0) lgkmcnt(0)
	v_mul_f32_e32 v227, v137, v227
	v_mul_f32_e32 v225, v145, v225
	v_mul_f32_e32 v223, v153, v223
	v_mul_f32_e32 v221, v161, v221
	v_mul_f32_e32 v222, v163, v222
	v_cndmask_b32_e64 v221, -v221, v221, s[36:37]
	v_cndmask_b32_e64 v222, -v222, v222, s[36:37]
	v_fmac_f32_e32 v221, v128, v160
	v_fmac_f32_e32 v222, v129, v162
	v_cvt_pk_bf16_f32 v222, v221, v222
	ds_bpermute_b32 v221, v210, v120
	v_cndmask_b32_e64 v223, -v223, v223, s[36:37]
	v_fmac_f32_e32 v223, v130, v152
	v_mul_f32_e32 v224, v155, v224
	v_cndmask_b32_e64 v224, -v224, v224, s[36:37]
	s_waitcnt lgkmcnt(0)
	v_mul_f32_e32 v161, v161, v221
	v_cndmask_b32_e64 v161, -v161, v161, s[36:37]
	v_fmac_f32_e32 v161, v120, v160
	ds_bpermute_b32 v160, v210, v121
	v_fmac_f32_e32 v224, v131, v154
	v_cndmask_b32_e64 v225, -v225, v225, s[36:37]
	v_fmac_f32_e32 v225, v124, v144
	v_mul_f32_e32 v226, v147, v226
	s_waitcnt lgkmcnt(0)
	v_mul_f32_e32 v160, v163, v160
	v_cndmask_b32_e64 v160, -v160, v160, s[36:37]
	v_fmac_f32_e32 v160, v121, v162
	ds_bpermute_b32 v162, v210, v122
	v_cndmask_b32_e64 v226, -v226, v226, s[36:37]
	v_fmac_f32_e32 v226, v125, v146
	v_cndmask_b32_e64 v227, -v227, v227, s[36:37]
	v_fmac_f32_e32 v227, v126, v136
	s_waitcnt lgkmcnt(0)
	v_mul_f32_e32 v153, v153, v162
	v_cndmask_b32_e64 v153, -v153, v153, s[36:37]
	v_fmac_f32_e32 v153, v122, v152
	ds_bpermute_b32 v152, v210, v123
	v_mul_f32_e32 v228, v139, v228
	v_cndmask_b32_e64 v228, -v228, v228, s[36:37]
	v_cvt_pk_bf16_f32 v223, v223, v224
	v_fmac_f32_e32 v228, v127, v138
	s_waitcnt lgkmcnt(0)
	v_mul_f32_e32 v152, v155, v152
	v_cndmask_b32_e64 v152, -v152, v152, s[36:37]
	v_fmac_f32_e32 v152, v123, v154
	ds_bpermute_b32 v154, v210, v116
	v_cvt_pk_bf16_f32 v224, v225, v226
	v_cvt_pk_bf16_f32 v225, v227, v228
	global_store_dwordx4 v220, v[222:225], s[6:7] sc0 sc1
	ds_bpermute_b32 v221, v210, v113
	s_waitcnt lgkmcnt(1)
	v_mul_f32_e32 v145, v145, v154
	v_cndmask_b32_e64 v145, -v145, v145, s[36:37]
	v_fmac_f32_e32 v145, v116, v144
	ds_bpermute_b32 v144, v210, v117
	ds_bpermute_b32 v222, v210, v114
	ds_bpermute_b32 v223, v210, v115
	ds_bpermute_b32 v224, v210, v108
	ds_bpermute_b32 v225, v210, v109
	s_waitcnt lgkmcnt(4)
	v_mul_f32_e32 v144, v147, v144
	v_cndmask_b32_e64 v144, -v144, v144, s[36:37]
	v_fmac_f32_e32 v144, v117, v146
	ds_bpermute_b32 v146, v210, v118
	ds_bpermute_b32 v226, v210, v110
	ds_bpermute_b32 v227, v210, v111
	v_mul_f32_e32 v221, v159, v221
	s_waitcnt lgkmcnt(6)
	v_mul_f32_e32 v222, v149, v222
	s_waitcnt lgkmcnt(2)
	v_mul_f32_e32 v137, v137, v146
	v_cndmask_b32_e64 v146, -v137, v137, s[36:37]
	v_fmac_f32_e32 v146, v118, v136
	ds_bpermute_b32 v136, v210, v119
	v_mul_f32_e32 v223, v151, v223
	v_cndmask_b32_e64 v221, -v221, v221, s[36:37]
	v_cndmask_b32_e64 v222, -v222, v222, s[36:37]
	v_cndmask_b32_e64 v223, -v223, v223, s[36:37]
	s_waitcnt lgkmcnt(0)
	v_mul_f32_e32 v136, v139, v136
	v_cndmask_b32_e64 v139, -v136, v136, s[36:37]
	v_fmac_f32_e32 v139, v119, v138
	v_cvt_pk_bf16_f32 v136, v161, v160
	v_cvt_pk_bf16_f32 v137, v153, v152
	v_cvt_pk_bf16_f32 v138, v145, v144
	v_cvt_pk_bf16_f32 v139, v146, v139
	global_store_dwordx4 v220, v[136:139], s[6:7] offset:256 sc0 sc1
	ds_bpermute_b32 v220, v210, v112
	v_mul_f32_e32 v224, v141, v224
	v_cndmask_b32_e64 v136, v197, v219, s[38:39]
	v_mul_f32_e32 v225, v143, v225
	v_mul_f32_e32 v226, v133, v226
	s_waitcnt lgkmcnt(0)
	v_mul_f32_e32 v220, v157, v220
	v_cndmask_b32_e64 v220, -v220, v220, s[36:37]
	v_mul_f32_e32 v227, v135, v227
	v_lshl_or_b32 v160, v136, 7, v195
	v_fmac_f32_e32 v220, v112, v156
	v_fmac_f32_e32 v221, v113, v158
	v_fmac_f32_e32 v222, v114, v148
	v_fmac_f32_e32 v223, v115, v150
	v_cndmask_b32_e64 v224, -v224, v224, s[36:37]
	v_cndmask_b32_e64 v225, -v225, v225, s[36:37]
	v_cndmask_b32_e64 v226, -v226, v226, s[36:37]
	v_cndmask_b32_e64 v227, -v227, v227, s[36:37]
	global_load_dwordx4 v[136:139], v160, s[2:3] offset:48
	global_load_dwordx4 v[144:147], v160, s[2:3] offset:32
	global_load_dwordx4 v[152:155], v160, s[2:3] offset:16
	s_nop 0
	global_load_dwordx4 v[160:163], v160, s[2:3]
	v_fmac_f32_e32 v224, v108, v140
	v_fmac_f32_e32 v225, v109, v142
	v_fmac_f32_e32 v226, v110, v132
	v_fmac_f32_e32 v227, v111, v134
	v_cvt_pk_bf16_f32 v220, v220, v221
	v_cvt_pk_bf16_f32 v221, v222, v223
	v_cvt_pk_bf16_f32 v222, v224, v225
	v_cvt_pk_bf16_f32 v223, v226, v227
	global_store_dwordx4 v218, v[220:223], s[6:7] sc0 sc1
	ds_bpermute_b32 v218, v210, v104
	ds_bpermute_b32 v220, v210, v99
	ds_bpermute_b32 v221, v210, v92
	ds_bpermute_b32 v222, v210, v93
	ds_bpermute_b32 v223, v210, v94
	s_waitcnt lgkmcnt(4)
	v_mul_f32_e32 v157, v157, v218
	v_cndmask_b32_e64 v157, -v157, v157, s[36:37]
	v_fmac_f32_e32 v157, v104, v156
	ds_bpermute_b32 v156, v210, v105
	ds_bpermute_b32 v218, v210, v97
	ds_bpermute_b32 v224, v210, v95
	s_waitcnt lgkmcnt(2)
	v_mul_f32_e32 v156, v159, v156
	v_cndmask_b32_e64 v156, -v156, v156, s[36:37]
	v_fmac_f32_e32 v156, v105, v158
	ds_bpermute_b32 v158, v210, v106
	s_waitcnt lgkmcnt(0)
	v_mul_f32_e32 v149, v149, v158
	v_cndmask_b32_e64 v149, -v149, v149, s[36:37]
	v_fmac_f32_e32 v149, v106, v148
	ds_bpermute_b32 v148, v210, v107
	s_waitcnt lgkmcnt(0)
	v_mul_f32_e32 v148, v151, v148
	v_cndmask_b32_e64 v148, -v148, v148, s[36:37]
	v_fmac_f32_e32 v148, v107, v150
	ds_bpermute_b32 v150, v210, v100
	s_waitcnt lgkmcnt(0)
	v_mul_f32_e32 v141, v141, v150
	v_cndmask_b32_e64 v141, -v141, v141, s[36:37]
	v_fmac_f32_e32 v141, v100, v140
	ds_bpermute_b32 v140, v210, v101
	s_waitcnt lgkmcnt(0)
	v_mul_f32_e32 v140, v143, v140
	v_cndmask_b32_e64 v140, -v140, v140, s[36:37]
	v_fmac_f32_e32 v140, v101, v142
	ds_bpermute_b32 v142, v210, v102
	s_waitcnt lgkmcnt(0)
	v_mul_f32_e32 v133, v133, v142
	v_cndmask_b32_e64 v142, -v133, v133, s[36:37]
	v_fmac_f32_e32 v142, v102, v132
	ds_bpermute_b32 v132, v210, v103
	s_waitcnt lgkmcnt(0)
	v_mul_f32_e32 v132, v135, v132
	v_cndmask_b32_e64 v135, -v132, v132, s[36:37]
	v_fmac_f32_e32 v135, v103, v134
	v_cvt_pk_bf16_f32 v132, v157, v156
	v_cvt_pk_bf16_f32 v133, v149, v148
	v_cvt_pk_bf16_f32 v134, v141, v140
	v_cvt_pk_bf16_f32 v135, v142, v135
	global_store_dwordx4 v217, v[132:135], s[6:7] sc0 sc1
	ds_bpermute_b32 v217, v210, v96
	s_waitcnt vmcnt(2)
	v_mul_f32_e32 v218, v163, v218
	v_cndmask_b32_e64 v132, v198, v219, s[38:39]
	v_lshl_or_b32 v156, v132, 7, v195
	global_load_dwordx4 v[132:135], v156, s[2:3] offset:48
	global_load_dwordx4 v[140:143], v156, s[2:3] offset:32
	global_load_dwordx4 v[148:151], v156, s[2:3] offset:16
	s_nop 0
	global_load_dwordx4 v[156:159], v156, s[2:3]
	ds_bpermute_b32 v219, v210, v98
	v_mul_f32_e32 v220, v155, v220
	v_mul_f32_e32 v221, v145, v221
	s_waitcnt lgkmcnt(1)
	v_mul_f32_e32 v217, v161, v217
	v_cndmask_b32_e64 v218, -v218, v218, s[36:37]
	s_waitcnt lgkmcnt(0)
	v_mul_f32_e32 v219, v153, v219
	v_cndmask_b32_e64 v219, -v219, v219, s[36:37]
	v_cndmask_b32_e64 v220, -v220, v220, s[36:37]
	v_cndmask_b32_e64 v221, -v221, v221, s[36:37]
	v_mul_f32_e32 v222, v147, v222
	v_mul_f32_e32 v223, v137, v223
	v_mul_f32_e32 v224, v139, v224
	v_cndmask_b32_e64 v217, -v217, v217, s[36:37]
	v_fmac_f32_e32 v218, v97, v162
	v_fmac_f32_e32 v219, v98, v152
	v_fmac_f32_e32 v220, v99, v154
	v_fmac_f32_e32 v221, v92, v144
	v_cndmask_b32_e64 v222, -v222, v222, s[36:37]
	v_cndmask_b32_e64 v223, -v223, v223, s[36:37]
	v_cndmask_b32_e64 v224, -v224, v224, s[36:37]
	v_fmac_f32_e32 v217, v96, v160
	v_fmac_f32_e32 v222, v93, v146
	v_fmac_f32_e32 v223, v94, v136
	v_fmac_f32_e32 v224, v95, v138
	v_cvt_pk_bf16_f32 v218, v217, v218
	v_cvt_pk_bf16_f32 v219, v219, v220
	v_cvt_pk_bf16_f32 v220, v221, v222
	v_cvt_pk_bf16_f32 v221, v223, v224
	global_store_dwordx4 v167, v[218:221], s[6:7] sc0 sc1
	ds_bpermute_b32 v167, v210, v88
	ds_bpermute_b32 v218, v210, v82
	v_mov_b32_e32 v217, s8
	s_waitcnt lgkmcnt(1)
	v_mul_f32_e32 v161, v161, v167
	v_cndmask_b32_e64 v161, -v161, v161, s[36:37]
	v_fmac_f32_e32 v161, v88, v160
	ds_bpermute_b32 v160, v210, v89
	ds_bpermute_b32 v167, v210, v81
	s_waitcnt lgkmcnt(1)
	v_mul_f32_e32 v160, v163, v160
	v_cndmask_b32_e64 v160, -v160, v160, s[36:37]
	v_fmac_f32_e32 v160, v89, v162
	ds_bpermute_b32 v162, v210, v90
	s_waitcnt lgkmcnt(0)
	v_mul_f32_e32 v153, v153, v162
	v_cndmask_b32_e64 v153, -v153, v153, s[36:37]
	v_fmac_f32_e32 v153, v90, v152
	ds_bpermute_b32 v152, v210, v91
	s_waitcnt lgkmcnt(0)
	v_mul_f32_e32 v152, v155, v152
	v_cndmask_b32_e64 v152, -v152, v152, s[36:37]
	v_fmac_f32_e32 v152, v91, v154
	ds_bpermute_b32 v154, v210, v84
	s_waitcnt lgkmcnt(0)
	v_mul_f32_e32 v145, v145, v154
	v_cndmask_b32_e64 v145, -v145, v145, s[36:37]
	v_fmac_f32_e32 v145, v84, v144
	ds_bpermute_b32 v144, v210, v85
	s_waitcnt lgkmcnt(0)
	v_mul_f32_e32 v144, v147, v144
	v_cndmask_b32_e64 v144, -v144, v144, s[36:37]
	v_fmac_f32_e32 v144, v85, v146
	ds_bpermute_b32 v146, v210, v86
	s_waitcnt vmcnt(2)
	v_mul_f32_e32 v218, v149, v218
	v_cndmask_b32_e64 v219, -v218, v218, s[36:37]
	ds_bpermute_b32 v218, v210, v83
	s_waitcnt vmcnt(1)
	v_mul_f32_e32 v167, v159, v167
	s_waitcnt lgkmcnt(1)
	v_mul_f32_e32 v137, v137, v146
	v_cndmask_b32_e64 v146, -v137, v137, s[36:37]
	v_fmac_f32_e32 v146, v86, v136
	s_waitcnt lgkmcnt(0)
	v_mul_f32_e32 v218, v151, v218
	v_cndmask_b32_e64 v220, -v218, v218, s[36:37]
	ds_bpermute_b32 v218, v210, v76
	ds_bpermute_b32 v136, v210, v87
	v_cndmask_b32_e64 v167, -v167, v167, s[36:37]
	v_fmac_f32_e32 v219, v82, v148
	v_fmac_f32_e32 v220, v83, v150
	s_waitcnt lgkmcnt(1)
	v_mul_f32_e32 v218, v141, v218
	v_cndmask_b32_e64 v221, -v218, v218, s[36:37]
	ds_bpermute_b32 v218, v210, v77
	s_waitcnt lgkmcnt(1)
	v_mul_f32_e32 v136, v139, v136
	v_cndmask_b32_e64 v139, -v136, v136, s[36:37]
	v_fmac_f32_e32 v139, v87, v138
	v_cvt_pk_bf16_f32 v136, v161, v160
	s_waitcnt lgkmcnt(0)
	v_mul_f32_e32 v218, v143, v218
	v_cndmask_b32_e64 v222, -v218, v218, s[36:37]
	ds_bpermute_b32 v218, v210, v78
	v_cvt_pk_bf16_f32 v137, v153, v152
	v_cvt_pk_bf16_f32 v138, v145, v144
	v_cvt_pk_bf16_f32 v139, v146, v139
	global_store_dwordx4 v166, v[136:139], s[6:7] sc0 sc1
	s_waitcnt lgkmcnt(0)
	v_mul_f32_e32 v218, v133, v218
	ds_bpermute_b32 v166, v210, v80
	v_cndmask_b32_e64 v136, v1, v217, s[38:39]
	v_lshl_or_b32 v160, v136, 7, v195
	global_load_dwordx4 v[136:139], v160, s[2:3] offset:48
	global_load_dwordx4 v[144:147], v160, s[2:3] offset:32
	global_load_dwordx4 v[152:155], v160, s[2:3] offset:16
	s_nop 0
	global_load_dwordx4 v[160:163], v160, s[2:3]
	v_cndmask_b32_e64 v223, -v218, v218, s[36:37]
	ds_bpermute_b32 v218, v210, v79
	s_waitcnt lgkmcnt(1)
	v_mul_f32_e32 v166, v157, v166
	v_cndmask_b32_e64 v166, -v166, v166, s[36:37]
	v_fmac_f32_e32 v221, v76, v140
	v_fmac_f32_e32 v166, v80, v156
	s_waitcnt lgkmcnt(0)
	v_mul_f32_e32 v218, v135, v218
	v_cndmask_b32_e64 v224, -v218, v218, s[36:37]
	v_fmac_f32_e32 v167, v81, v158
	v_fmac_f32_e32 v222, v77, v142
	v_fmac_f32_e32 v223, v78, v132
	v_fmac_f32_e32 v224, v79, v134
	v_cvt_pk_bf16_f32 v218, v166, v167
	v_cvt_pk_bf16_f32 v219, v219, v220
	v_cvt_pk_bf16_f32 v220, v221, v222
	v_cvt_pk_bf16_f32 v221, v223, v224
	global_store_dwordx4 v165, v[218:221], s[6:7] sc0 sc1
	ds_bpermute_b32 v165, v210, v72
	ds_bpermute_b32 v218, v210, v60
	ds_bpermute_b32 v219, v210, v61
	ds_bpermute_b32 v220, v210, v62
	ds_bpermute_b32 v221, v210, v63
	s_waitcnt lgkmcnt(4)
	v_mul_f32_e32 v157, v157, v165
	v_cndmask_b32_e64 v157, -v157, v157, s[36:37]
	v_fmac_f32_e32 v157, v72, v156
	ds_bpermute_b32 v156, v210, v73
	s_waitcnt lgkmcnt(0)
	v_mul_f32_e32 v156, v159, v156
	v_cndmask_b32_e64 v156, -v156, v156, s[36:37]
	v_fmac_f32_e32 v156, v73, v158
	ds_bpermute_b32 v158, v210, v74
	s_waitcnt lgkmcnt(0)
	v_mul_f32_e32 v149, v149, v158
	v_cndmask_b32_e64 v149, -v149, v149, s[36:37]
	v_fmac_f32_e32 v149, v74, v148
	ds_bpermute_b32 v148, v210, v75
	s_waitcnt lgkmcnt(0)
	v_mul_f32_e32 v148, v151, v148
	v_cndmask_b32_e64 v148, -v148, v148, s[36:37]
	v_fmac_f32_e32 v148, v75, v150
	ds_bpermute_b32 v150, v210, v68
	s_waitcnt lgkmcnt(0)
	v_mul_f32_e32 v141, v141, v150
	v_cndmask_b32_e64 v141, -v141, v141, s[36:37]
	v_fmac_f32_e32 v141, v68, v140
	ds_bpermute_b32 v140, v210, v69
	s_waitcnt lgkmcnt(0)
	v_mul_f32_e32 v140, v143, v140
	v_cndmask_b32_e64 v140, -v140, v140, s[36:37]
	v_fmac_f32_e32 v140, v69, v142
	ds_bpermute_b32 v142, v210, v70
	s_waitcnt lgkmcnt(0)
	v_mul_f32_e32 v133, v133, v142
	v_cndmask_b32_e64 v142, -v133, v133, s[36:37]
	v_fmac_f32_e32 v142, v70, v132
	ds_bpermute_b32 v132, v210, v71
	s_waitcnt vmcnt(4)
	v_mul_f32_e32 v220, v137, v220
	s_waitcnt vmcnt(3)
	v_mul_f32_e32 v218, v145, v218
	s_waitcnt lgkmcnt(0)
	v_mul_f32_e32 v132, v135, v132
	v_cndmask_b32_e64 v135, -v132, v132, s[36:37]
	v_fmac_f32_e32 v135, v71, v134
	v_cvt_pk_bf16_f32 v132, v157, v156
	v_cvt_pk_bf16_f32 v133, v149, v148
	v_cvt_pk_bf16_f32 v134, v141, v140
	v_cvt_pk_bf16_f32 v135, v142, v135
	global_store_dwordx4 v164, v[132:135], s[6:7] sc0 sc1
	ds_bpermute_b32 v133, v210, v65
	ds_bpermute_b32 v134, v210, v66
	v_cndmask_b32_e64 v132, v196, v217, s[38:39]
	v_lshl_or_b32 v132, v132, 7, v195
	global_load_dwordx4 v[140:143], v132, s[2:3] offset:48
	global_load_dwordx4 v[148:151], v132, s[2:3] offset:32
	global_load_dwordx4 v[156:159], v132, s[2:3] offset:16
	global_load_dwordx4 v[164:167], v132, s[2:3]
	ds_bpermute_b32 v132, v210, v64
	ds_bpermute_b32 v135, v210, v67
	s_waitcnt vmcnt(6) lgkmcnt(3)
	v_mul_f32_e32 v133, v163, v133
	s_waitcnt lgkmcnt(2)
	v_mul_f32_e32 v134, v153, v134
	v_cndmask_b32_e64 v133, -v133, v133, s[36:37]
	s_waitcnt lgkmcnt(1)
	v_mul_f32_e32 v132, v161, v132
	v_cndmask_b32_e64 v132, -v132, v132, s[36:37]
	v_cndmask_b32_e64 v134, -v134, v134, s[36:37]
	s_waitcnt lgkmcnt(0)
	v_mul_f32_e32 v135, v155, v135
	v_mul_f32_e32 v219, v147, v219
	v_fmac_f32_e32 v132, v64, v160
	v_fmac_f32_e32 v133, v65, v162
	v_fmac_f32_e32 v134, v66, v152
	v_cndmask_b32_e64 v135, -v135, v135, s[36:37]
	v_cndmask_b32_e64 v218, -v218, v218, s[36:37]
	v_cndmask_b32_e64 v219, -v219, v219, s[36:37]
	v_mul_f32_e32 v221, v139, v221
	v_fmac_f32_e32 v135, v67, v154
	v_fmac_f32_e32 v218, v60, v144
	v_fmac_f32_e32 v219, v61, v146
	v_cndmask_b32_e64 v220, -v220, v220, s[36:37]
	v_cndmask_b32_e64 v221, -v221, v221, s[36:37]
	v_cvt_pk_bf16_f32 v132, v132, v133
	v_cvt_pk_bf16_f32 v133, v134, v135
	v_cvt_pk_bf16_f32 v134, v218, v219
	v_fmac_f32_e32 v220, v62, v136
	v_fmac_f32_e32 v221, v63, v138
	v_cvt_pk_bf16_f32 v135, v220, v221
	global_store_dwordx4 v216, v[132:135], s[6:7] sc0 sc1
	ds_bpermute_b32 v134, v210, v58
	ds_bpermute_b32 v132, v210, v56
	ds_bpermute_b32 v133, v210, v57
	ds_bpermute_b32 v135, v210, v59
	ds_bpermute_b32 v216, v210, v45
	s_waitcnt lgkmcnt(4)
	v_mul_f32_e32 v134, v153, v134
	v_cndmask_b32_e64 v134, -v134, v134, s[36:37]
	v_fmac_f32_e32 v134, v58, v152
	ds_bpermute_b32 v152, v210, v52
	s_waitcnt lgkmcnt(4)
	v_mul_f32_e32 v132, v161, v132
	v_cndmask_b32_e64 v132, -v132, v132, s[36:37]
	s_waitcnt lgkmcnt(3)
	v_mul_f32_e32 v133, v163, v133
	s_waitcnt lgkmcnt(2)
	v_mul_f32_e32 v135, v155, v135
	s_waitcnt lgkmcnt(0)
	v_mul_f32_e32 v145, v145, v152
	v_cndmask_b32_e64 v145, -v145, v145, s[36:37]
	v_fmac_f32_e32 v145, v52, v144
	ds_bpermute_b32 v144, v210, v53
	v_fmac_f32_e32 v132, v56, v160
	v_cndmask_b32_e64 v133, -v133, v133, s[36:37]
	v_cndmask_b32_e64 v135, -v135, v135, s[36:37]
	v_fmac_f32_e32 v133, v57, v162
	s_waitcnt lgkmcnt(0)
	v_mul_f32_e32 v144, v147, v144
	v_cndmask_b32_e64 v144, -v144, v144, s[36:37]
	v_fmac_f32_e32 v144, v53, v146
	ds_bpermute_b32 v146, v210, v54
	v_fmac_f32_e32 v135, v59, v154
	v_cvt_pk_bf16_f32 v132, v132, v133
	v_cvt_pk_bf16_f32 v133, v134, v135
	v_cvt_pk_bf16_f32 v134, v145, v144
	s_waitcnt lgkmcnt(0)
	v_mul_f32_e32 v137, v137, v146
	v_cndmask_b32_e64 v137, -v137, v137, s[36:37]
	v_fmac_f32_e32 v137, v54, v136
	ds_bpermute_b32 v136, v210, v55
	ds_bpermute_b32 v218, v210, v46
	ds_bpermute_b32 v219, v210, v47
	s_waitcnt lgkmcnt(2)
	v_mul_f32_e32 v136, v139, v136
	v_cndmask_b32_e64 v136, -v136, v136, s[36:37]
	v_fmac_f32_e32 v136, v55, v138
	v_cvt_pk_bf16_f32 v135, v137, v136
	global_store_dwordx4 v215, v[132:135], s[6:7] sc0 sc1
	ds_bpermute_b32 v137, v210, v49
	ds_bpermute_b32 v138, v210, v50
	v_cndmask_b32_e64 v132, v197, v217, s[38:39]
	v_lshl_or_b32 v136, v132, 7, v195
	global_load_dwordx4 v[132:135], v136, s[2:3] offset:48
	global_load_dwordx4 v[144:147], v136, s[2:3] offset:32
	global_load_dwordx4 v[152:155], v136, s[2:3] offset:16
	global_load_dwordx4 v[160:163], v136, s[2:3]
	ds_bpermute_b32 v136, v210, v48
	ds_bpermute_b32 v139, v210, v51
	ds_bpermute_b32 v215, v210, v44
	s_waitcnt vmcnt(6) lgkmcnt(4)
	v_mul_f32_e32 v137, v167, v137
	s_waitcnt lgkmcnt(3)
	v_mul_f32_e32 v138, v157, v138
	s_waitcnt lgkmcnt(2)
	v_mul_f32_e32 v136, v165, v136
	v_cndmask_b32_e64 v136, -v136, v136, s[36:37]
	v_cndmask_b32_e64 v137, -v137, v137, s[36:37]
	v_cndmask_b32_e64 v138, -v138, v138, s[36:37]
	s_waitcnt lgkmcnt(1)
	v_mul_f32_e32 v139, v159, v139
	s_waitcnt lgkmcnt(0)
	v_mul_f32_e32 v215, v149, v215
	v_mul_f32_e32 v216, v151, v216
	v_fmac_f32_e32 v136, v48, v164
	v_fmac_f32_e32 v137, v49, v166
	v_fmac_f32_e32 v138, v50, v156
	v_cndmask_b32_e64 v139, -v139, v139, s[36:37]
	v_cndmask_b32_e64 v215, -v215, v215, s[36:37]
	v_cndmask_b32_e64 v216, -v216, v216, s[36:37]
	v_mul_f32_e32 v218, v141, v218
	v_mul_f32_e32 v219, v143, v219
	v_fmac_f32_e32 v139, v51, v158
	v_fmac_f32_e32 v215, v44, v148
	v_fmac_f32_e32 v216, v45, v150
	v_cndmask_b32_e64 v218, -v218, v218, s[36:37]
	v_cndmask_b32_e64 v219, -v219, v219, s[36:37]
	v_cvt_pk_bf16_f32 v136, v136, v137
	v_cvt_pk_bf16_f32 v137, v138, v139
	v_cvt_pk_bf16_f32 v138, v215, v216
	v_fmac_f32_e32 v218, v46, v140
	v_fmac_f32_e32 v219, v47, v142
	v_cvt_pk_bf16_f32 v139, v218, v219
	global_store_dwordx4 v214, v[136:139], s[6:7] sc0 sc1
	ds_bpermute_b32 v138, v210, v42
	ds_bpermute_b32 v136, v210, v40
	ds_bpermute_b32 v137, v210, v41
	ds_bpermute_b32 v139, v210, v43
	ds_bpermute_b32 v214, v210, v29
	s_waitcnt lgkmcnt(4)
	v_mul_f32_e32 v138, v157, v138
	v_cndmask_b32_e64 v138, -v138, v138, s[36:37]
	v_fmac_f32_e32 v138, v42, v156
	ds_bpermute_b32 v156, v210, v36
	s_waitcnt lgkmcnt(4)
	v_mul_f32_e32 v136, v165, v136
	v_cndmask_b32_e64 v136, -v136, v136, s[36:37]
	s_waitcnt lgkmcnt(3)
	v_mul_f32_e32 v137, v167, v137
	s_waitcnt lgkmcnt(2)
	v_mul_f32_e32 v139, v159, v139
	s_waitcnt lgkmcnt(0)
	v_mul_f32_e32 v149, v149, v156
	v_cndmask_b32_e64 v149, -v149, v149, s[36:37]
	v_fmac_f32_e32 v149, v36, v148
	ds_bpermute_b32 v148, v210, v37
	v_fmac_f32_e32 v136, v40, v164
	v_cndmask_b32_e64 v137, -v137, v137, s[36:37]
	v_cndmask_b32_e64 v139, -v139, v139, s[36:37]
	v_fmac_f32_e32 v137, v41, v166
	s_waitcnt lgkmcnt(0)
	v_mul_f32_e32 v148, v151, v148
	v_cndmask_b32_e64 v148, -v148, v148, s[36:37]
	v_fmac_f32_e32 v148, v37, v150
	ds_bpermute_b32 v150, v210, v38
	v_fmac_f32_e32 v139, v43, v158
	v_cvt_pk_bf16_f32 v136, v136, v137
	v_cvt_pk_bf16_f32 v137, v138, v139
	v_cvt_pk_bf16_f32 v138, v149, v148
	s_waitcnt lgkmcnt(0)
	v_mul_f32_e32 v141, v141, v150
	v_cndmask_b32_e64 v141, -v141, v141, s[36:37]
	v_fmac_f32_e32 v141, v38, v140
	ds_bpermute_b32 v140, v210, v39
	ds_bpermute_b32 v164, v210, v32
	ds_bpermute_b32 v165, v210, v33
	ds_bpermute_b32 v166, v210, v34
	ds_bpermute_b32 v167, v210, v35
	s_waitcnt lgkmcnt(4)
	v_mul_f32_e32 v140, v143, v140
	v_cndmask_b32_e64 v140, -v140, v140, s[36:37]
	v_fmac_f32_e32 v140, v39, v142
	v_cvt_pk_bf16_f32 v139, v141, v140
	global_store_dwordx4 v213, v[136:139], s[6:7] sc0 sc1
	ds_bpermute_b32 v213, v210, v28
	ds_bpermute_b32 v215, v210, v30
	v_cndmask_b32_e64 v136, v198, v217, s[38:39]
	v_lshl_or_b32 v156, v136, 7, v195
	global_load_dwordx4 v[136:139], v156, s[2:3] offset:48
	global_load_dwordx4 v[140:143], v156, s[2:3] offset:32
	global_load_dwordx4 v[148:151], v156, s[2:3] offset:16
	s_nop 0
	global_load_dwordx4 v[156:159], v156, s[2:3]
	ds_bpermute_b32 v216, v210, v31
	s_waitcnt vmcnt(6) lgkmcnt(6)
	v_mul_f32_e32 v164, v161, v164
	v_cndmask_b32_e64 v164, -v164, v164, s[36:37]
	s_waitcnt lgkmcnt(5)
	v_mul_f32_e32 v165, v163, v165
	s_waitcnt lgkmcnt(4)
	v_mul_f32_e32 v166, v153, v166
	s_waitcnt lgkmcnt(3)
	v_mul_f32_e32 v167, v155, v167
	v_fmac_f32_e32 v164, v32, v160
	v_cndmask_b32_e64 v165, -v165, v165, s[36:37]
	v_cndmask_b32_e64 v166, -v166, v166, s[36:37]
	v_cndmask_b32_e64 v167, -v167, v167, s[36:37]
	s_waitcnt lgkmcnt(2)
	v_mul_f32_e32 v213, v145, v213
	v_mul_f32_e32 v214, v147, v214
	s_waitcnt lgkmcnt(1)
	v_mul_f32_e32 v215, v133, v215
	s_waitcnt lgkmcnt(0)
	v_mul_f32_e32 v216, v135, v216
	v_fmac_f32_e32 v165, v33, v162
	v_fmac_f32_e32 v166, v34, v152
	v_fmac_f32_e32 v167, v35, v154
	v_cndmask_b32_e64 v213, -v213, v213, s[36:37]
	v_cndmask_b32_e64 v214, -v214, v214, s[36:37]
	v_cndmask_b32_e64 v215, -v215, v215, s[36:37]
	v_cndmask_b32_e64 v216, -v216, v216, s[36:37]
	v_cvt_pk_bf16_f32 v164, v164, v165
	v_fmac_f32_e32 v213, v28, v144
	v_fmac_f32_e32 v214, v29, v146
	v_fmac_f32_e32 v215, v30, v132
	v_fmac_f32_e32 v216, v31, v134
	v_cvt_pk_bf16_f32 v165, v166, v167
	v_cvt_pk_bf16_f32 v166, v213, v214
	v_cvt_pk_bf16_f32 v167, v215, v216
	global_store_dwordx4 v212, v[164:167], s[6:7] sc0 sc1
	ds_bpermute_b32 v164, v210, v24
	s_waitcnt lgkmcnt(0)
	v_mul_f32_e32 v161, v161, v164
	v_cndmask_b32_e64 v161, -v161, v161, s[36:37]
	v_fmac_f32_e32 v161, v24, v160
	ds_bpermute_b32 v160, v210, v25
	s_waitcnt lgkmcnt(0)
	v_mul_f32_e32 v160, v163, v160
	v_cndmask_b32_e64 v160, -v160, v160, s[36:37]
	v_fmac_f32_e32 v160, v25, v162
	ds_bpermute_b32 v162, v210, v26
	s_waitcnt lgkmcnt(0)
	v_mul_f32_e32 v153, v153, v162
	v_cndmask_b32_e64 v153, -v153, v153, s[36:37]
	v_fmac_f32_e32 v153, v26, v152
	ds_bpermute_b32 v152, v210, v27
	s_waitcnt lgkmcnt(0)
	v_mul_f32_e32 v152, v155, v152
	v_cndmask_b32_e64 v152, -v152, v152, s[36:37]
	v_fmac_f32_e32 v152, v27, v154
	ds_bpermute_b32 v154, v210, v20
	s_waitcnt lgkmcnt(0)
	v_mul_f32_e32 v145, v145, v154
	v_cndmask_b32_e64 v145, -v145, v145, s[36:37]
	v_fmac_f32_e32 v145, v20, v144
	ds_bpermute_b32 v144, v210, v21
	s_waitcnt lgkmcnt(0)
	v_mul_f32_e32 v144, v147, v144
	v_cndmask_b32_e64 v144, -v144, v144, s[36:37]
	v_fmac_f32_e32 v144, v21, v146
	ds_bpermute_b32 v146, v210, v22
	ds_bpermute_b32 v147, v210, v15
	s_waitcnt lgkmcnt(1)
	v_mul_f32_e32 v133, v133, v146
	v_cndmask_b32_e64 v146, -v133, v133, s[36:37]
	v_fmac_f32_e32 v146, v22, v132
	ds_bpermute_b32 v132, v210, v23
	s_waitcnt vmcnt(4) lgkmcnt(1)
	v_mul_f32_e32 v147, v139, v147
	v_cndmask_b32_e64 v147, -v147, v147, s[36:37]
	v_fmac_f32_e32 v147, v15, v138
	s_waitcnt lgkmcnt(0)
	v_mul_f32_e32 v132, v135, v132
	v_cndmask_b32_e64 v135, -v132, v132, s[36:37]
	v_fmac_f32_e32 v135, v23, v134
	v_cvt_pk_bf16_f32 v132, v161, v160
	v_cvt_pk_bf16_f32 v133, v153, v152
	v_cvt_pk_bf16_f32 v134, v145, v144
	v_cvt_pk_bf16_f32 v135, v146, v135
	global_store_dwordx4 v211, v[132:135], s[6:7] sc0 sc1
	ds_bpermute_b32 v132, v210, v16
	ds_bpermute_b32 v133, v210, v17
	ds_bpermute_b32 v134, v210, v18
	ds_bpermute_b32 v144, v210, v12
	ds_bpermute_b32 v135, v210, v19
	ds_bpermute_b32 v145, v210, v13
	s_waitcnt vmcnt(2) lgkmcnt(5)
	v_mul_f32_e32 v132, v157, v132
	s_waitcnt lgkmcnt(4)
	v_mul_f32_e32 v133, v159, v133
	s_waitcnt lgkmcnt(3)
	v_mul_f32_e32 v134, v149, v134
	s_waitcnt lgkmcnt(2)
	v_mul_f32_e32 v144, v141, v144
	v_cndmask_b32_e64 v132, -v132, v132, s[36:37]
	v_cndmask_b32_e64 v133, -v133, v133, s[36:37]
	v_cndmask_b32_e64 v134, -v134, v134, s[36:37]
	s_waitcnt lgkmcnt(1)
	v_mul_f32_e32 v135, v151, v135
	v_cndmask_b32_e64 v144, -v144, v144, s[36:37]
	s_waitcnt lgkmcnt(0)
	v_mul_f32_e32 v145, v143, v145
	v_fmac_f32_e32 v132, v16, v156
	v_fmac_f32_e32 v133, v17, v158
	v_fmac_f32_e32 v134, v18, v148
	v_cndmask_b32_e64 v135, -v135, v135, s[36:37]
	v_fmac_f32_e32 v144, v12, v140
	v_cndmask_b32_e64 v145, -v145, v145, s[36:37]
	v_fmac_f32_e32 v135, v19, v150
	v_fmac_f32_e32 v145, v13, v142
	v_cvt_pk_bf16_f32 v132, v132, v133
	v_cvt_pk_bf16_f32 v133, v134, v135
	v_cvt_pk_bf16_f32 v134, v144, v145
	ds_bpermute_b32 v144, v210, v4
	ds_bpermute_b32 v146, v210, v14
	s_waitcnt lgkmcnt(1)
	v_mul_f32_e32 v141, v141, v144
	v_cndmask_b32_e64 v141, -v141, v141, s[36:37]
	v_fmac_f32_e32 v141, v4, v140
	ds_bpermute_b32 v140, v210, v5
	s_waitcnt lgkmcnt(1)
	v_mul_f32_e32 v146, v137, v146
	v_cndmask_b32_e64 v146, -v146, v146, s[36:37]
	v_fmac_f32_e32 v146, v14, v136
	v_cvt_pk_bf16_f32 v135, v146, v147
	s_waitcnt lgkmcnt(0)
	v_mul_f32_e32 v140, v143, v140
	v_cndmask_b32_e64 v140, -v140, v140, s[36:37]
	v_fmac_f32_e32 v140, v5, v142
	ds_bpermute_b32 v142, v210, v6
	global_store_dwordx4 v209, v[132:135], s[6:7] sc0 sc1
	ds_bpermute_b32 v132, v210, v8
	ds_bpermute_b32 v133, v210, v9
	ds_bpermute_b32 v134, v210, v10
	s_waitcnt lgkmcnt(3)
	v_mul_f32_e32 v137, v137, v142
	ds_bpermute_b32 v135, v210, v11
	v_cndmask_b32_e64 v137, -v137, v137, s[36:37]
	v_fmac_f32_e32 v137, v6, v136
	ds_bpermute_b32 v136, v210, v7
	s_waitcnt lgkmcnt(4)
	v_mul_f32_e32 v132, v157, v132
	s_waitcnt lgkmcnt(3)
	v_mul_f32_e32 v133, v159, v133
	s_waitcnt lgkmcnt(2)
	v_mul_f32_e32 v134, v149, v134
	s_waitcnt lgkmcnt(1)
	v_mul_f32_e32 v135, v151, v135
	v_cndmask_b32_e64 v132, -v132, v132, s[36:37]
	v_cndmask_b32_e64 v133, -v133, v133, s[36:37]
	v_cndmask_b32_e64 v134, -v134, v134, s[36:37]
	v_cndmask_b32_e64 v135, -v135, v135, s[36:37]
	s_waitcnt lgkmcnt(0)
	v_mul_f32_e32 v136, v139, v136
	v_fmac_f32_e32 v132, v8, v156
	v_fmac_f32_e32 v133, v9, v158
	v_fmac_f32_e32 v134, v10, v148
	v_fmac_f32_e32 v135, v11, v150
	v_cndmask_b32_e64 v136, -v136, v136, s[36:37]
	v_fmac_f32_e32 v136, v7, v138
	v_cvt_pk_bf16_f32 v132, v132, v133
	v_cvt_pk_bf16_f32 v133, v134, v135
	v_cvt_pk_bf16_f32 v134, v141, v140
	v_cvt_pk_bf16_f32 v135, v137, v136
	global_store_dwordx4 v2, v[132:135], s[6:7] sc0 sc1

.Lwt_BB0_579:
	s_nop 0
	v_mul_f32_e32 v133, v124, v124
	v_fmamk_f32 v133, v133, 0xbdd2d3e8, v201
	v_mul_f32_e32 v133, v124, v133
	v_exp_f32_e32 v133, v133
	v_mul_f32_e32 v132, v128, v128
	v_fmamk_f32 v132, v132, 0xbdd2d3e8, v201
	v_mul_f32_e32 v132, v128, v132
	v_add_f32_e32 v133, 1.0, v133
	v_rcp_f32_e32 v133, v133
	v_exp_f32_e32 v132, v132
	s_ashr_i32 s6, s26, 2
	s_mul_hi_i32 s7, s6, 0x1400000
	v_mul_f32_e32 v124, v124, v133
	v_mul_f32_e32 v133, v129, v129
	v_fmamk_f32 v133, v133, 0xbdd2d3e8, v201
	v_mul_f32_e32 v133, v129, v133
	v_exp_f32_e32 v133, v133
	v_add_f32_e32 v132, 1.0, v132
	v_rcp_f32_e32 v132, v132
	s_mul_i32 s6, s6, 0x1400000
	v_add_f32_e32 v133, 1.0, v133
	v_rcp_f32_e32 v133, v133
	s_add_u32 s6, s59, s6
	s_addc_u32 s7, s60, s7
	s_lshl_b32 s8, s26, 9
	v_pk_mul_f32 v[128:129], v[128:129], v[132:133]
	v_mul_f32_e32 v132, v125, v125
	v_fmamk_f32 v132, v132, 0xbdd2d3e8, v201
	v_mul_f32_e32 v132, v125, v132
	v_exp_f32_e32 v132, v132
	s_and_b32 s8, s8, 0x600
	s_add_u32 s6, s6, s8
	s_addc_u32 s7, s7, 0
	v_add_f32_e32 v132, 1.0, v132
	v_rcp_f32_e32 v132, v132
	v_lshl_or_b32 v146, v208, 11, v194
	v_cvt_pk_bf16_f32 v138, v128, v129
	s_lshl_b32 s8, s26, 5
	v_mul_f32_e32 v132, v125, v132
	v_mul_f32_e32 v125, v130, v130
	v_fmamk_f32 v125, v125, 0xbdd2d3e8, v201
	v_mul_f32_e32 v125, v130, v125
	v_exp_f32_e32 v125, v125
	s_add_i32 s8, s25, s8
	s_cmp_gt_i32 s26, 3
	v_lshl_add_u32 v2, v208, 7, s8
	v_add_f32_e32 v125, 1.0, v125
	v_rcp_f32_e32 v125, v125
	s_cselect_b64 s[8:9], -1, 0
	s_cmp_lt_i32 s26, 4
	v_mul_f32_e32 v130, v130, v125
	v_mul_f32_e32 v125, v126, v126
	v_fmamk_f32 v125, v125, 0xbdd2d3e8, v201
	v_mul_f32_e32 v125, v126, v125
	v_exp_f32_e32 v125, v125
	s_nop 0
	v_add_f32_e32 v125, 1.0, v125
	v_rcp_f32_e32 v125, v125
	s_nop 0
	v_mul_f32_e32 v126, v126, v125
	v_mul_f32_e32 v125, v131, v131
	v_fmamk_f32 v125, v125, 0xbdd2d3e8, v201
	v_mul_f32_e32 v125, v131, v125
	v_exp_f32_e32 v125, v125
	s_nop 0
	v_add_f32_e32 v125, 1.0, v125
	v_rcp_f32_e32 v125, v125
	s_nop 0
	v_mul_f32_e32 v134, v131, v125
	v_mul_f32_e32 v125, v127, v127
	v_fmamk_f32 v125, v125, 0xbdd2d3e8, v201
	v_mul_f32_e32 v125, v127, v125
	v_exp_f32_e32 v125, v125
	v_cvt_pk_bf16_f32 v139, v130, v134
	v_cvt_pk_bf16_f32 v140, v124, v132
	s_nop 0
	v_add_f32_e32 v125, 1.0, v125
	v_rcp_f32_e32 v125, v125
	s_nop 0
	v_mul_f32_e32 v136, v127, v125
	v_mul_f32_e32 v125, v120, v120
	v_fmamk_f32 v125, v125, 0xbdd2d3e8, v201
	v_mul_f32_e32 v125, v120, v125
	v_exp_f32_e32 v125, v125
	v_cvt_pk_bf16_f32 v141, v126, v136
	global_store_dwordx4 v146, v[138:141], s[6:7] sc0 sc1
	v_add_f32_e32 v125, 1.0, v125
	v_rcp_f32_e32 v125, v125
	s_nop 0
	v_mul_f32_e32 v120, v120, v125
	v_mul_f32_e32 v125, v116, v116
	v_fmamk_f32 v125, v125, 0xbdd2d3e8, v201
	v_mul_f32_e32 v125, v116, v125
	v_exp_f32_e32 v125, v125
	s_nop 0
	v_add_f32_e32 v125, 1.0, v125
	v_rcp_f32_e32 v125, v125
	s_nop 0
	v_mul_f32_e32 v116, v116, v125
	v_mul_f32_e32 v125, v121, v121
	v_fmamk_f32 v125, v125, 0xbdd2d3e8, v201
	v_mul_f32_e32 v125, v121, v125
	v_exp_f32_e32 v125, v125
	s_nop 0
	v_add_f32_e32 v125, 1.0, v125
	v_rcp_f32_e32 v125, v125
	s_nop 0
	v_mul_f32_e32 v138, v121, v125
	v_mul_f32_e32 v121, v117, v117
	v_fmamk_f32 v121, v121, 0xbdd2d3e8, v201
	v_mul_f32_e32 v121, v117, v121
	v_exp_f32_e32 v121, v121
	v_cvt_pk_bf16_f32 v148, v120, v138
	s_nop 0
	v_add_f32_e32 v121, 1.0, v121
	v_rcp_f32_e32 v121, v121
	s_nop 0
	v_mul_f32_e32 v140, v117, v121
	v_mul_f32_e32 v117, v122, v122
	v_fmamk_f32 v117, v117, 0xbdd2d3e8, v201
	v_mul_f32_e32 v117, v122, v117
	v_exp_f32_e32 v117, v117
	s_nop 0
	v_add_f32_e32 v117, 1.0, v117
	v_rcp_f32_e32 v117, v117
	s_nop 0
	v_mul_f32_e32 v122, v122, v117
	v_mul_f32_e32 v117, v118, v118
	v_fmamk_f32 v117, v117, 0xbdd2d3e8, v201
	v_mul_f32_e32 v117, v118, v117
	v_exp_f32_e32 v117, v117
	s_nop 0
	v_add_f32_e32 v117, 1.0, v117
	v_rcp_f32_e32 v117, v117
	s_nop 0
	v_mul_f32_e32 v118, v118, v117
	v_mul_f32_e32 v117, v123, v123
	v_fmamk_f32 v117, v117, 0xbdd2d3e8, v201
	v_mul_f32_e32 v117, v123, v117
	v_exp_f32_e32 v117, v117
	s_nop 0
	v_add_f32_e32 v117, 1.0, v117
	v_rcp_f32_e32 v117, v117
	s_nop 0
	v_mul_f32_e32 v142, v123, v117
	v_mul_f32_e32 v117, v119, v119
	v_fmamk_f32 v117, v117, 0xbdd2d3e8, v201
	v_mul_f32_e32 v117, v119, v117
	v_exp_f32_e32 v117, v117
	v_cvt_pk_bf16_f32 v149, v122, v142
	v_cvt_pk_bf16_f32 v150, v116, v140
	s_nop 0
	v_add_f32_e32 v117, 1.0, v117
	v_rcp_f32_e32 v117, v117
	s_nop 0
	v_mul_f32_e32 v144, v119, v117
	v_cvt_pk_bf16_f32 v151, v118, v144
	global_store_dwordx4 v146, v[148:151], s[6:7] offset:256 sc0 sc1
	s_cbranch_scc1 .Lwt_BB0_583
	s_nop 0
	v_mov_b32_e32 v150, v3
	v_mov_b32_e32 v151, v129
	v_pk_mul_f32 v[148:149], v[128:129], v[128:129]
	v_pk_add_f32 v[150:151], v[128:129], v[150:151]
	v_pk_mov_b32 v[128:129], v[128:129], v[148:149] op_sel:[1,0]
	v_mov_b32_e32 v151, v149
	v_mul_f32_e32 v131, v130, v130
	v_pk_add_f32 v[128:129], v[128:129], v[150:151]
	v_mul_f32_e32 v135, v134, v134
	v_pk_add_f32 v[128:129], v[130:131], v[128:129]
	v_mul_f32_e32 v125, v124, v124
	v_pk_add_f32 v[128:129], v[134:135], v[128:129]
	v_mul_f32_e32 v133, v132, v132
	v_pk_add_f32 v[124:125], v[124:125], v[128:129]
	v_mul_f32_e32 v127, v126, v126
	v_pk_add_f32 v[124:125], v[132:133], v[124:125]
	v_mul_f32_e32 v137, v136, v136
	v_pk_add_f32 v[124:125], v[126:127], v[124:125]
	v_mul_f32_e32 v121, v120, v120
	v_pk_add_f32 v[124:125], v[136:137], v[124:125]
	v_mul_f32_e32 v139, v138, v138
	v_pk_add_f32 v[120:121], v[120:121], v[124:125]
	v_mul_f32_e32 v123, v122, v122
	v_pk_add_f32 v[120:121], v[138:139], v[120:121]
	v_mul_f32_e32 v143, v142, v142
	v_pk_add_f32 v[120:121], v[122:123], v[120:121]
	v_mul_f32_e32 v117, v116, v116
	v_and_b32_e32 v127, 64, v204
	v_pk_add_f32 v[120:121], v[142:143], v[120:121]
	v_mul_f32_e32 v141, v140, v140
	v_xor_b32_e32 v126, 16, v204
	v_add_u32_e32 v127, 64, v127
	v_pk_add_f32 v[116:117], v[116:117], v[120:121]
	v_mul_f32_e32 v119, v118, v118
	v_cmp_lt_i32_e32 vcc, v126, v127
	v_pk_add_f32 v[116:117], v[140:141], v[116:117]
	v_mul_f32_e32 v145, v144, v144
	v_cndmask_b32_e32 v126, v204, v126, vcc
	v_pk_add_f32 v[116:117], v[118:119], v[116:117]
	v_lshlrev_b32_e32 v126, 2, v126
	v_pk_add_f32 v[116:117], v[144:145], v[116:117]
	ds_bpermute_b32 v118, v126, v116
	ds_bpermute_b32 v119, v126, v117
	v_xor_b32_e32 v120, 32, v204
	v_cmp_lt_i32_e32 vcc, v120, v127
	s_waitcnt lgkmcnt(0)
	v_pk_add_f32 v[116:117], v[116:117], v[118:119]
	v_cndmask_b32_e32 v120, v204, v120, vcc
	v_lshlrev_b32_e32 v120, 2, v120
	ds_bpermute_b32 v118, v120, v116
	ds_bpermute_b32 v119, v120, v117
	s_and_saveexec_b64 s[10:11], s[40:41]
	s_cbranch_execz .Lwt_BB0_582
	v_lshl_add_u64 v[120:121], s[66:67], 0, v[2:3]
	s_waitcnt lgkmcnt(0)
	v_pk_add_f32 v[116:117], v[116:117], v[118:119]
	global_store_dwordx2 v[120:121], v[116:117], off sc0 sc1

.Lwt_BB0_583:
	v_mul_f32_e32 v117, v108, v108
	v_fmamk_f32 v117, v117, 0xbdd2d3e8, v201
	v_mul_f32_e32 v117, v108, v117
	v_exp_f32_e32 v117, v117
	v_mul_f32_e32 v116, v112, v112
	v_fmamk_f32 v116, v116, 0xbdd2d3e8, v201
	v_mul_f32_e32 v116, v112, v116
	v_add_f32_e32 v117, 1.0, v117
	v_rcp_f32_e32 v117, v117
	v_exp_f32_e32 v116, v116
	s_waitcnt lgkmcnt(0)
	v_or_b32_e32 v119, 0x8000, v146
	v_mul_f32_e32 v108, v108, v117
	v_mul_f32_e32 v117, v113, v113
	v_fmamk_f32 v117, v117, 0xbdd2d3e8, v201
	v_mul_f32_e32 v117, v113, v117
	v_exp_f32_e32 v117, v117
	v_add_f32_e32 v116, 1.0, v116
	v_rcp_f32_e32 v116, v116
	s_andn2_b64 vcc, exec, s[8:9]
	v_add_f32_e32 v117, 1.0, v117
	v_rcp_f32_e32 v117, v117
	s_nop 0
	v_pk_mul_f32 v[112:113], v[112:113], v[116:117]
	v_mul_f32_e32 v116, v109, v109
	v_fmamk_f32 v116, v116, 0xbdd2d3e8, v201
	v_mul_f32_e32 v116, v109, v116
	v_exp_f32_e32 v116, v116
	v_cvt_pk_bf16_f32 v122, v112, v113
	s_nop 0
	v_add_f32_e32 v116, 1.0, v116
	v_rcp_f32_e32 v116, v116
	s_nop 0
	v_mul_f32_e32 v116, v109, v116
	v_mul_f32_e32 v109, v114, v114
	v_fmamk_f32 v109, v109, 0xbdd2d3e8, v201
	v_mul_f32_e32 v109, v114, v109
	v_exp_f32_e32 v109, v109
	s_nop 0
	v_add_f32_e32 v109, 1.0, v109
	v_rcp_f32_e32 v109, v109
	s_nop 0
	v_mul_f32_e32 v114, v114, v109
	v_mul_f32_e32 v109, v110, v110
	v_fmamk_f32 v109, v109, 0xbdd2d3e8, v201
	v_mul_f32_e32 v109, v110, v109
	v_exp_f32_e32 v109, v109
	s_nop 0
	v_add_f32_e32 v109, 1.0, v109
	v_rcp_f32_e32 v109, v109
	s_nop 0
	v_mul_f32_e32 v110, v110, v109
	v_mul_f32_e32 v109, v115, v115
	v_fmamk_f32 v109, v109, 0xbdd2d3e8, v201
	v_mul_f32_e32 v109, v115, v109
	v_exp_f32_e32 v109, v109
	s_nop 0
	v_add_f32_e32 v109, 1.0, v109
	v_rcp_f32_e32 v109, v109
	s_nop 0
	v_mul_f32_e32 v118, v115, v109
	v_mul_f32_e32 v109, v111, v111
	v_fmamk_f32 v109, v109, 0xbdd2d3e8, v201
	v_mul_f32_e32 v109, v111, v109
	v_exp_f32_e32 v109, v109
	v_cvt_pk_bf16_f32 v123, v114, v118
	v_cvt_pk_bf16_f32 v124, v108, v116
	s_nop 0
	v_add_f32_e32 v109, 1.0, v109
	v_rcp_f32_e32 v109, v109
	s_nop 0
	v_mul_f32_e32 v120, v111, v109
	v_mul_f32_e32 v109, v104, v104
	v_fmamk_f32 v109, v109, 0xbdd2d3e8, v201
	v_mul_f32_e32 v109, v104, v109
	v_exp_f32_e32 v109, v109
	v_cvt_pk_bf16_f32 v125, v110, v120
	global_store_dwordx4 v119, v[122:125], s[6:7] sc0 sc1
	v_add_f32_e32 v109, 1.0, v109
	v_rcp_f32_e32 v109, v109
	s_nop 0
	v_mul_f32_e32 v104, v104, v109
	v_mul_f32_e32 v109, v100, v100
	v_fmamk_f32 v109, v109, 0xbdd2d3e8, v201
	v_mul_f32_e32 v109, v100, v109
	v_exp_f32_e32 v109, v109
	s_nop 0
	v_add_f32_e32 v109, 1.0, v109
	v_rcp_f32_e32 v109, v109
	s_nop 0
	v_mul_f32_e32 v100, v100, v109
	v_mul_f32_e32 v109, v105, v105
	v_fmamk_f32 v109, v109, 0xbdd2d3e8, v201
	v_mul_f32_e32 v109, v105, v109
	v_exp_f32_e32 v109, v109
	s_nop 0
	v_add_f32_e32 v109, 1.0, v109
	v_rcp_f32_e32 v109, v109
	s_nop 0
	v_mul_f32_e32 v122, v105, v109
	v_mul_f32_e32 v105, v101, v101
	v_fmamk_f32 v105, v105, 0xbdd2d3e8, v201
	v_mul_f32_e32 v105, v101, v105
	v_exp_f32_e32 v105, v105
	v_cvt_pk_bf16_f32 v130, v104, v122
	s_nop 0
	v_add_f32_e32 v105, 1.0, v105
	v_rcp_f32_e32 v105, v105
	s_nop 0
	v_mul_f32_e32 v124, v101, v105
	v_mul_f32_e32 v101, v106, v106
	v_fmamk_f32 v101, v101, 0xbdd2d3e8, v201
	v_mul_f32_e32 v101, v106, v101
	v_exp_f32_e32 v101, v101
	s_nop 0
	v_add_f32_e32 v101, 1.0, v101
	v_rcp_f32_e32 v101, v101
	s_nop 0
	v_mul_f32_e32 v106, v106, v101
	v_mul_f32_e32 v101, v102, v102
	v_fmamk_f32 v101, v101, 0xbdd2d3e8, v201
	v_mul_f32_e32 v101, v102, v101
	v_exp_f32_e32 v101, v101
	s_nop 0
	v_add_f32_e32 v101, 1.0, v101
	v_rcp_f32_e32 v101, v101
	s_nop 0
	v_mul_f32_e32 v102, v102, v101
	v_mul_f32_e32 v101, v107, v107
	v_fmamk_f32 v101, v101, 0xbdd2d3e8, v201
	v_mul_f32_e32 v101, v107, v101
	v_exp_f32_e32 v101, v101
	s_nop 0
	v_add_f32_e32 v101, 1.0, v101
	v_rcp_f32_e32 v101, v101
	s_nop 0
	v_mul_f32_e32 v126, v107, v101
	v_mul_f32_e32 v101, v103, v103
	v_fmamk_f32 v101, v101, 0xbdd2d3e8, v201
	v_mul_f32_e32 v101, v103, v101
	v_exp_f32_e32 v101, v101
	v_cvt_pk_bf16_f32 v131, v106, v126
	v_cvt_pk_bf16_f32 v132, v100, v124
	s_nop 0
	v_add_f32_e32 v101, 1.0, v101
	v_rcp_f32_e32 v101, v101
	s_nop 0
	v_mul_f32_e32 v128, v103, v101
	v_or_b32_e32 v101, 0x8100, v146
	v_cvt_pk_bf16_f32 v133, v102, v128
	global_store_dwordx4 v101, v[130:133], s[6:7] sc0 sc1
	v_cndmask_b32_e64 v101, 0, 1, s[8:9]
	v_cmp_ne_u32_e64 s[44:45], 1, v101
	s_cbranch_vccnz .Lwt_BB0_587
	v_mov_b32_e32 v132, v3
	v_mov_b32_e32 v133, v113
	v_pk_mul_f32 v[130:131], v[112:113], v[112:113]
	v_pk_add_f32 v[132:133], v[112:113], v[132:133]
	v_pk_mov_b32 v[112:113], v[112:113], v[130:131] op_sel:[1,0]
	v_mov_b32_e32 v133, v131
	v_mul_f32_e32 v115, v114, v114
	v_pk_add_f32 v[112:113], v[112:113], v[132:133]
	v_mul_f32_e32 v119, v118, v118
	v_pk_add_f32 v[112:113], v[114:115], v[112:113]
	v_mul_f32_e32 v109, v108, v108
	v_pk_add_f32 v[112:113], v[118:119], v[112:113]
	v_mul_f32_e32 v117, v116, v116
	v_pk_add_f32 v[108:109], v[108:109], v[112:113]
	v_mul_f32_e32 v111, v110, v110
	v_pk_add_f32 v[108:109], v[116:117], v[108:109]
	v_mul_f32_e32 v121, v120, v120
	v_pk_add_f32 v[108:109], v[110:111], v[108:109]
	v_mul_f32_e32 v105, v104, v104
	v_pk_add_f32 v[108:109], v[120:121], v[108:109]
	v_mul_f32_e32 v123, v122, v122
	v_pk_add_f32 v[104:105], v[104:105], v[108:109]
	v_mul_f32_e32 v107, v106, v106
	v_pk_add_f32 v[104:105], v[122:123], v[104:105]
	v_mul_f32_e32 v127, v126, v126
	v_pk_add_f32 v[104:105], v[106:107], v[104:105]
	v_mul_f32_e32 v101, v100, v100
	v_and_b32_e32 v111, 64, v204
	v_pk_add_f32 v[104:105], v[126:127], v[104:105]
	v_mul_f32_e32 v125, v124, v124
	v_xor_b32_e32 v110, 16, v204
	v_add_u32_e32 v111, 64, v111
	v_pk_add_f32 v[100:101], v[100:101], v[104:105]
	v_mul_f32_e32 v103, v102, v102
	v_cmp_lt_i32_e32 vcc, v110, v111
	v_pk_add_f32 v[100:101], v[124:125], v[100:101]
	v_mul_f32_e32 v129, v128, v128
	v_cndmask_b32_e32 v110, v204, v110, vcc
	v_pk_add_f32 v[100:101], v[102:103], v[100:101]
	v_lshlrev_b32_e32 v110, 2, v110
	v_pk_add_f32 v[100:101], v[128:129], v[100:101]
	ds_bpermute_b32 v102, v110, v100
	ds_bpermute_b32 v103, v110, v101
	v_xor_b32_e32 v104, 32, v204
	v_cmp_lt_i32_e32 vcc, v104, v111
	s_waitcnt lgkmcnt(0)
	v_pk_add_f32 v[100:101], v[100:101], v[102:103]
	v_cndmask_b32_e32 v104, v204, v104, vcc
	v_lshlrev_b32_e32 v104, 2, v104
	ds_bpermute_b32 v102, v104, v100
	ds_bpermute_b32 v103, v104, v101
	s_and_saveexec_b64 s[8:9], s[40:41]
	s_cbranch_execz .Lwt_BB0_586
	v_lshl_add_u64 v[104:105], s[66:67], 0, v[2:3]
	s_waitcnt lgkmcnt(0)
	v_pk_add_f32 v[100:101], v[100:101], v[102:103]
	global_store_dwordx2 v[104:105], v[100:101], off offset:2048 sc0 sc1

.Lwt_BB0_587:
	v_mul_f32_e32 v101, v92, v92
	v_fmamk_f32 v101, v101, 0xbdd2d3e8, v201
	v_mul_f32_e32 v101, v92, v101
	v_exp_f32_e32 v101, v101
	v_mul_f32_e32 v100, v96, v96
	v_fmamk_f32 v100, v100, 0xbdd2d3e8, v201
	v_mul_f32_e32 v100, v96, v100
	v_add_f32_e32 v101, 1.0, v101
	v_rcp_f32_e32 v101, v101
	v_exp_f32_e32 v100, v100
	s_waitcnt lgkmcnt(0)
	v_or_b32_e32 v103, 0x10000, v146
	v_mul_f32_e32 v92, v92, v101
	v_mul_f32_e32 v101, v97, v97
	v_fmamk_f32 v101, v101, 0xbdd2d3e8, v201
	v_mul_f32_e32 v101, v97, v101
	v_exp_f32_e32 v101, v101
	v_add_f32_e32 v100, 1.0, v100
	v_rcp_f32_e32 v100, v100
	s_and_b64 vcc, exec, s[44:45]
	v_add_f32_e32 v101, 1.0, v101
	v_rcp_f32_e32 v101, v101
	s_nop 0
	v_pk_mul_f32 v[96:97], v[96:97], v[100:101]
	v_mul_f32_e32 v100, v93, v93
	v_fmamk_f32 v100, v100, 0xbdd2d3e8, v201
	v_mul_f32_e32 v100, v93, v100
	v_exp_f32_e32 v100, v100
	v_cvt_pk_bf16_f32 v106, v96, v97
	s_nop 0
	v_add_f32_e32 v100, 1.0, v100
	v_rcp_f32_e32 v100, v100
	s_nop 0
	v_mul_f32_e32 v100, v93, v100
	v_mul_f32_e32 v93, v98, v98
	v_fmamk_f32 v93, v93, 0xbdd2d3e8, v201
	v_mul_f32_e32 v93, v98, v93
	v_exp_f32_e32 v93, v93
	s_nop 0
	v_add_f32_e32 v93, 1.0, v93
	v_rcp_f32_e32 v93, v93
	s_nop 0
	v_mul_f32_e32 v98, v98, v93
	v_mul_f32_e32 v93, v94, v94
	v_fmamk_f32 v93, v93, 0xbdd2d3e8, v201
	v_mul_f32_e32 v93, v94, v93
	v_exp_f32_e32 v93, v93
	s_nop 0
	v_add_f32_e32 v93, 1.0, v93
	v_rcp_f32_e32 v93, v93
	s_nop 0
	v_mul_f32_e32 v94, v94, v93
	v_mul_f32_e32 v93, v99, v99
	v_fmamk_f32 v93, v93, 0xbdd2d3e8, v201
	v_mul_f32_e32 v93, v99, v93
	v_exp_f32_e32 v93, v93
	s_nop 0
	v_add_f32_e32 v93, 1.0, v93
	v_rcp_f32_e32 v93, v93
	s_nop 0
	v_mul_f32_e32 v102, v99, v93
	v_mul_f32_e32 v93, v95, v95
	v_fmamk_f32 v93, v93, 0xbdd2d3e8, v201
	v_mul_f32_e32 v93, v95, v93
	v_exp_f32_e32 v93, v93
	v_cvt_pk_bf16_f32 v107, v98, v102
	v_cvt_pk_bf16_f32 v108, v92, v100
	s_nop 0
	v_add_f32_e32 v93, 1.0, v93
	v_rcp_f32_e32 v93, v93
	s_nop 0
	v_mul_f32_e32 v104, v95, v93
	v_mul_f32_e32 v93, v88, v88
	v_fmamk_f32 v93, v93, 0xbdd2d3e8, v201
	v_mul_f32_e32 v93, v88, v93
	v_exp_f32_e32 v93, v93
	v_cvt_pk_bf16_f32 v109, v94, v104
	global_store_dwordx4 v103, v[106:109], s[6:7] sc0 sc1
	v_add_f32_e32 v93, 1.0, v93
	v_rcp_f32_e32 v93, v93
	s_nop 0
	v_mul_f32_e32 v88, v88, v93
	v_mul_f32_e32 v93, v84, v84
	v_fmamk_f32 v93, v93, 0xbdd2d3e8, v201
	v_mul_f32_e32 v93, v84, v93
	v_exp_f32_e32 v93, v93
	s_nop 0
	v_add_f32_e32 v93, 1.0, v93
	v_rcp_f32_e32 v93, v93
	s_nop 0
	v_mul_f32_e32 v84, v84, v93
	v_mul_f32_e32 v93, v89, v89
	v_fmamk_f32 v93, v93, 0xbdd2d3e8, v201
	v_mul_f32_e32 v93, v89, v93
	v_exp_f32_e32 v93, v93
	s_nop 0
	v_add_f32_e32 v93, 1.0, v93
	v_rcp_f32_e32 v93, v93
	s_nop 0
	v_mul_f32_e32 v106, v89, v93
	v_mul_f32_e32 v89, v85, v85
	v_fmamk_f32 v89, v89, 0xbdd2d3e8, v201
	v_mul_f32_e32 v89, v85, v89
	v_exp_f32_e32 v89, v89
	v_cvt_pk_bf16_f32 v114, v88, v106
	s_nop 0
	v_add_f32_e32 v89, 1.0, v89
	v_rcp_f32_e32 v89, v89
	s_nop 0
	v_mul_f32_e32 v108, v85, v89
	v_mul_f32_e32 v85, v90, v90
	v_fmamk_f32 v85, v85, 0xbdd2d3e8, v201
	v_mul_f32_e32 v85, v90, v85
	v_exp_f32_e32 v85, v85
	s_nop 0
	v_add_f32_e32 v85, 1.0, v85
	v_rcp_f32_e32 v85, v85
	s_nop 0
	v_mul_f32_e32 v90, v90, v85
	v_mul_f32_e32 v85, v86, v86
	v_fmamk_f32 v85, v85, 0xbdd2d3e8, v201
	v_mul_f32_e32 v85, v86, v85
	v_exp_f32_e32 v85, v85
	s_nop 0
	v_add_f32_e32 v85, 1.0, v85
	v_rcp_f32_e32 v85, v85
	s_nop 0
	v_mul_f32_e32 v86, v86, v85
	v_mul_f32_e32 v85, v91, v91
	v_fmamk_f32 v85, v85, 0xbdd2d3e8, v201
	v_mul_f32_e32 v85, v91, v85
	v_exp_f32_e32 v85, v85
	s_nop 0
	v_add_f32_e32 v85, 1.0, v85
	v_rcp_f32_e32 v85, v85
	s_nop 0
	v_mul_f32_e32 v110, v91, v85
	v_mul_f32_e32 v85, v87, v87
	v_fmamk_f32 v85, v85, 0xbdd2d3e8, v201
	v_mul_f32_e32 v85, v87, v85
	v_exp_f32_e32 v85, v85
	v_cvt_pk_bf16_f32 v115, v90, v110
	v_cvt_pk_bf16_f32 v116, v84, v108
	s_nop 0
	v_add_f32_e32 v85, 1.0, v85
	v_rcp_f32_e32 v85, v85
	s_nop 0
	v_mul_f32_e32 v112, v87, v85
	v_or_b32_e32 v85, 0x10100, v146
	v_cvt_pk_bf16_f32 v117, v86, v112
	global_store_dwordx4 v85, v[114:117], s[6:7] sc0 sc1
	s_cbranch_vccnz .Lwt_BB0_591
	s_nop 0
	v_mov_b32_e32 v116, v3
	v_mov_b32_e32 v117, v97
	v_pk_mul_f32 v[114:115], v[96:97], v[96:97]
	v_pk_add_f32 v[116:117], v[96:97], v[116:117]
	v_pk_mov_b32 v[96:97], v[96:97], v[114:115] op_sel:[1,0]
	v_mov_b32_e32 v117, v115
	v_mul_f32_e32 v99, v98, v98
	v_pk_add_f32 v[96:97], v[96:97], v[116:117]
	v_mul_f32_e32 v103, v102, v102
	v_pk_add_f32 v[96:97], v[98:99], v[96:97]
	v_mul_f32_e32 v93, v92, v92
	v_pk_add_f32 v[96:97], v[102:103], v[96:97]
	v_mul_f32_e32 v101, v100, v100
	v_pk_add_f32 v[92:93], v[92:93], v[96:97]
	v_mul_f32_e32 v95, v94, v94
	v_pk_add_f32 v[92:93], v[100:101], v[92:93]
	v_mul_f32_e32 v105, v104, v104
	v_pk_add_f32 v[92:93], v[94:95], v[92:93]
	v_mul_f32_e32 v89, v88, v88
	v_pk_add_f32 v[92:93], v[104:105], v[92:93]
	v_mul_f32_e32 v107, v106, v106
	v_pk_add_f32 v[88:89], v[88:89], v[92:93]
	v_mul_f32_e32 v91, v90, v90
	v_pk_add_f32 v[88:89], v[106:107], v[88:89]
	v_mul_f32_e32 v111, v110, v110
	v_pk_add_f32 v[88:89], v[90:91], v[88:89]
	v_mul_f32_e32 v85, v84, v84
	v_and_b32_e32 v95, 64, v204
	v_pk_add_f32 v[88:89], v[110:111], v[88:89]
	v_mul_f32_e32 v109, v108, v108
	v_xor_b32_e32 v94, 16, v204
	v_add_u32_e32 v95, 64, v95
	v_pk_add_f32 v[84:85], v[84:85], v[88:89]
	v_mul_f32_e32 v87, v86, v86
	v_cmp_lt_i32_e32 vcc, v94, v95
	v_pk_add_f32 v[84:85], v[108:109], v[84:85]
	v_mul_f32_e32 v113, v112, v112
	v_cndmask_b32_e32 v94, v204, v94, vcc
	v_pk_add_f32 v[84:85], v[86:87], v[84:85]
	v_lshlrev_b32_e32 v94, 2, v94
	v_pk_add_f32 v[84:85], v[112:113], v[84:85]
	ds_bpermute_b32 v86, v94, v84
	ds_bpermute_b32 v87, v94, v85
	v_xor_b32_e32 v88, 32, v204
	v_cmp_lt_i32_e32 vcc, v88, v95
	s_waitcnt lgkmcnt(0)
	v_pk_add_f32 v[84:85], v[84:85], v[86:87]
	v_cndmask_b32_e32 v88, v204, v88, vcc
	v_lshlrev_b32_e32 v88, 2, v88
	ds_bpermute_b32 v86, v88, v84
	ds_bpermute_b32 v87, v88, v85
	s_and_saveexec_b64 s[8:9], s[40:41]
	s_cbranch_execz .Lwt_BB0_590
	v_lshl_add_u64 v[88:89], s[66:67], 0, v[2:3]
	s_waitcnt lgkmcnt(0)
	v_pk_add_f32 v[84:85], v[84:85], v[86:87]
	v_add_co_u32_e32 v86, vcc, 0x1000, v88
	s_nop 1
	v_addc_co_u32_e32 v87, vcc, 0, v89, vcc
	global_store_dwordx2 v[86:87], v[84:85], off sc0 sc1

.Lwt_BB0_591:
	v_mul_f32_e32 v85, v76, v76
	v_fmamk_f32 v85, v85, 0xbdd2d3e8, v201
	v_mul_f32_e32 v85, v76, v85
	v_exp_f32_e32 v85, v85
	v_mul_f32_e32 v84, v80, v80
	v_fmamk_f32 v84, v84, 0xbdd2d3e8, v201
	v_mul_f32_e32 v84, v80, v84
	v_add_f32_e32 v85, 1.0, v85
	v_rcp_f32_e32 v85, v85
	v_exp_f32_e32 v84, v84
	s_waitcnt lgkmcnt(0)
	v_or_b32_e32 v87, 0x18000, v146
	v_mul_f32_e32 v76, v76, v85
	v_mul_f32_e32 v85, v81, v81
	v_fmamk_f32 v85, v85, 0xbdd2d3e8, v201
	v_mul_f32_e32 v85, v81, v85
	v_exp_f32_e32 v85, v85
	v_add_f32_e32 v84, 1.0, v84
	v_rcp_f32_e32 v84, v84
	s_and_b64 vcc, exec, s[44:45]
	v_add_f32_e32 v85, 1.0, v85
	v_rcp_f32_e32 v85, v85
	s_nop 0
	v_pk_mul_f32 v[80:81], v[80:81], v[84:85]
	v_mul_f32_e32 v84, v77, v77
	v_fmamk_f32 v84, v84, 0xbdd2d3e8, v201
	v_mul_f32_e32 v84, v77, v84
	v_exp_f32_e32 v84, v84
	v_cvt_pk_bf16_f32 v90, v80, v81
	s_nop 0
	v_add_f32_e32 v84, 1.0, v84
	v_rcp_f32_e32 v84, v84
	s_nop 0
	v_mul_f32_e32 v84, v77, v84
	v_mul_f32_e32 v77, v82, v82
	v_fmamk_f32 v77, v77, 0xbdd2d3e8, v201
	v_mul_f32_e32 v77, v82, v77
	v_exp_f32_e32 v77, v77
	s_nop 0
	v_add_f32_e32 v77, 1.0, v77
	v_rcp_f32_e32 v77, v77
	s_nop 0
	v_mul_f32_e32 v82, v82, v77
	v_mul_f32_e32 v77, v78, v78
	v_fmamk_f32 v77, v77, 0xbdd2d3e8, v201
	v_mul_f32_e32 v77, v78, v77
	v_exp_f32_e32 v77, v77
	s_nop 0
	v_add_f32_e32 v77, 1.0, v77
	v_rcp_f32_e32 v77, v77
	s_nop 0
	v_mul_f32_e32 v78, v78, v77
	v_mul_f32_e32 v77, v83, v83
	v_fmamk_f32 v77, v77, 0xbdd2d3e8, v201
	v_mul_f32_e32 v77, v83, v77
	v_exp_f32_e32 v77, v77
	s_nop 0
	v_add_f32_e32 v77, 1.0, v77
	v_rcp_f32_e32 v77, v77
	s_nop 0
	v_mul_f32_e32 v86, v83, v77
	v_mul_f32_e32 v77, v79, v79
	v_fmamk_f32 v77, v77, 0xbdd2d3e8, v201
	v_mul_f32_e32 v77, v79, v77
	v_exp_f32_e32 v77, v77
	v_cvt_pk_bf16_f32 v91, v82, v86
	v_cvt_pk_bf16_f32 v92, v76, v84
	s_nop 0
	v_add_f32_e32 v77, 1.0, v77
	v_rcp_f32_e32 v77, v77
	s_nop 0
	v_mul_f32_e32 v88, v79, v77
	v_mul_f32_e32 v77, v72, v72
	v_fmamk_f32 v77, v77, 0xbdd2d3e8, v201
	v_mul_f32_e32 v77, v72, v77
	v_exp_f32_e32 v77, v77
	v_cvt_pk_bf16_f32 v93, v78, v88
	global_store_dwordx4 v87, v[90:93], s[6:7] sc0 sc1
	v_add_f32_e32 v77, 1.0, v77
	v_rcp_f32_e32 v77, v77
	s_nop 0
	v_mul_f32_e32 v72, v72, v77
	v_mul_f32_e32 v77, v68, v68
	v_fmamk_f32 v77, v77, 0xbdd2d3e8, v201
	v_mul_f32_e32 v77, v68, v77
	v_exp_f32_e32 v77, v77
	s_nop 0
	v_add_f32_e32 v77, 1.0, v77
	v_rcp_f32_e32 v77, v77
	s_nop 0
	v_mul_f32_e32 v68, v68, v77
	v_mul_f32_e32 v77, v73, v73
	v_fmamk_f32 v77, v77, 0xbdd2d3e8, v201
	v_mul_f32_e32 v77, v73, v77
	v_exp_f32_e32 v77, v77
	s_nop 0
	v_add_f32_e32 v77, 1.0, v77
	v_rcp_f32_e32 v77, v77
	s_nop 0
	v_mul_f32_e32 v90, v73, v77
	v_mul_f32_e32 v73, v69, v69
	v_fmamk_f32 v73, v73, 0xbdd2d3e8, v201
	v_mul_f32_e32 v73, v69, v73
	v_exp_f32_e32 v73, v73
	v_cvt_pk_bf16_f32 v98, v72, v90
	s_nop 0
	v_add_f32_e32 v73, 1.0, v73
	v_rcp_f32_e32 v73, v73
	s_nop 0
	v_mul_f32_e32 v92, v69, v73
	v_mul_f32_e32 v69, v74, v74
	v_fmamk_f32 v69, v69, 0xbdd2d3e8, v201
	v_mul_f32_e32 v69, v74, v69
	v_exp_f32_e32 v69, v69
	s_nop 0
	v_add_f32_e32 v69, 1.0, v69
	v_rcp_f32_e32 v69, v69
	s_nop 0
	v_mul_f32_e32 v74, v74, v69
	v_mul_f32_e32 v69, v70, v70
	v_fmamk_f32 v69, v69, 0xbdd2d3e8, v201
	v_mul_f32_e32 v69, v70, v69
	v_exp_f32_e32 v69, v69
	s_nop 0
	v_add_f32_e32 v69, 1.0, v69
	v_rcp_f32_e32 v69, v69
	s_nop 0
	v_mul_f32_e32 v70, v70, v69
	v_mul_f32_e32 v69, v75, v75
	v_fmamk_f32 v69, v69, 0xbdd2d3e8, v201
	v_mul_f32_e32 v69, v75, v69
	v_exp_f32_e32 v69, v69
	s_nop 0
	v_add_f32_e32 v69, 1.0, v69
	v_rcp_f32_e32 v69, v69
	s_nop 0
	v_mul_f32_e32 v94, v75, v69
	v_mul_f32_e32 v69, v71, v71
	v_fmamk_f32 v69, v69, 0xbdd2d3e8, v201
	v_mul_f32_e32 v69, v71, v69
	v_exp_f32_e32 v69, v69
	v_cvt_pk_bf16_f32 v99, v74, v94
	v_cvt_pk_bf16_f32 v100, v68, v92
	s_nop 0
	v_add_f32_e32 v69, 1.0, v69
	v_rcp_f32_e32 v69, v69
	s_nop 0
	v_mul_f32_e32 v96, v71, v69
	v_or_b32_e32 v69, 0x18100, v146
	v_cvt_pk_bf16_f32 v101, v70, v96
	global_store_dwordx4 v69, v[98:101], s[6:7] sc0 sc1
	s_cbranch_vccnz .Lwt_BB0_595
	s_nop 0
	v_mov_b32_e32 v100, v3
	v_mov_b32_e32 v101, v81
	v_pk_mul_f32 v[98:99], v[80:81], v[80:81]
	v_pk_add_f32 v[100:101], v[80:81], v[100:101]
	v_pk_mov_b32 v[80:81], v[80:81], v[98:99] op_sel:[1,0]
	v_mov_b32_e32 v101, v99
	v_mul_f32_e32 v83, v82, v82
	v_pk_add_f32 v[80:81], v[80:81], v[100:101]
	v_mul_f32_e32 v87, v86, v86
	v_pk_add_f32 v[80:81], v[82:83], v[80:81]
	v_mul_f32_e32 v77, v76, v76
	v_pk_add_f32 v[80:81], v[86:87], v[80:81]
	v_mul_f32_e32 v85, v84, v84
	v_pk_add_f32 v[76:77], v[76:77], v[80:81]
	v_mul_f32_e32 v79, v78, v78
	v_pk_add_f32 v[76:77], v[84:85], v[76:77]
	v_mul_f32_e32 v89, v88, v88
	v_pk_add_f32 v[76:77], v[78:79], v[76:77]
	v_mul_f32_e32 v73, v72, v72
	v_pk_add_f32 v[76:77], v[88:89], v[76:77]
	v_mul_f32_e32 v91, v90, v90
	v_pk_add_f32 v[72:73], v[72:73], v[76:77]
	v_mul_f32_e32 v75, v74, v74
	v_pk_add_f32 v[72:73], v[90:91], v[72:73]
	v_mul_f32_e32 v95, v94, v94
	v_pk_add_f32 v[72:73], v[74:75], v[72:73]
	v_mul_f32_e32 v69, v68, v68
	v_and_b32_e32 v79, 64, v204
	v_pk_add_f32 v[72:73], v[94:95], v[72:73]
	v_mul_f32_e32 v93, v92, v92
	v_xor_b32_e32 v78, 16, v204
	v_add_u32_e32 v79, 64, v79
	v_pk_add_f32 v[68:69], v[68:69], v[72:73]
	v_mul_f32_e32 v71, v70, v70
	v_cmp_lt_i32_e32 vcc, v78, v79
	v_pk_add_f32 v[68:69], v[92:93], v[68:69]
	v_mul_f32_e32 v97, v96, v96
	v_cndmask_b32_e32 v78, v204, v78, vcc
	v_pk_add_f32 v[68:69], v[70:71], v[68:69]
	v_lshlrev_b32_e32 v78, 2, v78
	v_pk_add_f32 v[68:69], v[96:97], v[68:69]
	ds_bpermute_b32 v70, v78, v68
	ds_bpermute_b32 v71, v78, v69
	v_xor_b32_e32 v72, 32, v204
	v_cmp_lt_i32_e32 vcc, v72, v79
	s_waitcnt lgkmcnt(0)
	v_pk_add_f32 v[68:69], v[68:69], v[70:71]
	v_cndmask_b32_e32 v72, v204, v72, vcc
	v_lshlrev_b32_e32 v72, 2, v72
	ds_bpermute_b32 v70, v72, v68
	ds_bpermute_b32 v71, v72, v69
	s_and_saveexec_b64 s[8:9], s[40:41]
	s_cbranch_execz .Lwt_BB0_594
	v_lshl_add_u64 v[72:73], s[66:67], 0, v[2:3]
	s_waitcnt lgkmcnt(0)
	v_pk_add_f32 v[68:69], v[68:69], v[70:71]
	v_add_co_u32_e32 v70, vcc, 0x1000, v72
	s_nop 1
	v_addc_co_u32_e32 v71, vcc, 0, v73, vcc
	global_store_dwordx2 v[70:71], v[68:69], off offset:2048 sc0 sc1

.Lwt_BB0_595:
	v_mul_f32_e32 v69, v60, v60
	v_fmamk_f32 v69, v69, 0xbdd2d3e8, v201
	v_mul_f32_e32 v69, v60, v69
	v_exp_f32_e32 v69, v69
	v_mul_f32_e32 v68, v64, v64
	v_fmamk_f32 v68, v68, 0xbdd2d3e8, v201
	v_mul_f32_e32 v68, v64, v68
	v_add_f32_e32 v69, 1.0, v69
	v_rcp_f32_e32 v69, v69
	v_exp_f32_e32 v68, v68
	s_waitcnt lgkmcnt(0)
	v_add_u32_e32 v71, 0x40000, v146
	v_mul_f32_e32 v60, v60, v69
	v_mul_f32_e32 v69, v65, v65
	v_fmamk_f32 v69, v69, 0xbdd2d3e8, v201
	v_mul_f32_e32 v69, v65, v69
	v_exp_f32_e32 v69, v69
	v_add_f32_e32 v68, 1.0, v68
	v_rcp_f32_e32 v68, v68
	s_and_b64 vcc, exec, s[44:45]
	v_add_f32_e32 v69, 1.0, v69
	v_rcp_f32_e32 v69, v69
	s_nop 0
	v_pk_mul_f32 v[64:65], v[64:65], v[68:69]
	v_mul_f32_e32 v68, v61, v61
	v_fmamk_f32 v68, v68, 0xbdd2d3e8, v201
	v_mul_f32_e32 v68, v61, v68
	v_exp_f32_e32 v68, v68
	v_cvt_pk_bf16_f32 v74, v64, v65
	s_nop 0
	v_add_f32_e32 v68, 1.0, v68
	v_rcp_f32_e32 v68, v68
	s_nop 0
	v_mul_f32_e32 v68, v61, v68
	v_mul_f32_e32 v61, v66, v66
	v_fmamk_f32 v61, v61, 0xbdd2d3e8, v201
	v_mul_f32_e32 v61, v66, v61
	v_exp_f32_e32 v61, v61
	s_nop 0
	v_add_f32_e32 v61, 1.0, v61
	v_rcp_f32_e32 v61, v61
	s_nop 0
	v_mul_f32_e32 v66, v66, v61
	v_mul_f32_e32 v61, v62, v62
	v_fmamk_f32 v61, v61, 0xbdd2d3e8, v201
	v_mul_f32_e32 v61, v62, v61
	v_exp_f32_e32 v61, v61
	s_nop 0
	v_add_f32_e32 v61, 1.0, v61
	v_rcp_f32_e32 v61, v61
	s_nop 0
	v_mul_f32_e32 v62, v62, v61
	v_mul_f32_e32 v61, v67, v67
	v_fmamk_f32 v61, v61, 0xbdd2d3e8, v201
	v_mul_f32_e32 v61, v67, v61
	v_exp_f32_e32 v61, v61
	s_nop 0
	v_add_f32_e32 v61, 1.0, v61
	v_rcp_f32_e32 v61, v61
	s_nop 0
	v_mul_f32_e32 v70, v67, v61
	v_mul_f32_e32 v61, v63, v63
	v_fmamk_f32 v61, v61, 0xbdd2d3e8, v201
	v_mul_f32_e32 v61, v63, v61
	v_exp_f32_e32 v61, v61
	v_cvt_pk_bf16_f32 v75, v66, v70
	v_cvt_pk_bf16_f32 v76, v60, v68
	s_nop 0
	v_add_f32_e32 v61, 1.0, v61
	v_rcp_f32_e32 v61, v61
	s_nop 0
	v_mul_f32_e32 v72, v63, v61
	v_mul_f32_e32 v61, v56, v56
	v_fmamk_f32 v61, v61, 0xbdd2d3e8, v201
	v_mul_f32_e32 v61, v56, v61
	v_exp_f32_e32 v61, v61
	v_cvt_pk_bf16_f32 v77, v62, v72
	global_store_dwordx4 v71, v[74:77], s[6:7] sc0 sc1
	v_add_f32_e32 v61, 1.0, v61
	v_rcp_f32_e32 v61, v61
	s_nop 0
	v_mul_f32_e32 v56, v56, v61
	v_mul_f32_e32 v61, v52, v52
	v_fmamk_f32 v61, v61, 0xbdd2d3e8, v201
	v_mul_f32_e32 v61, v52, v61
	v_exp_f32_e32 v61, v61
	s_nop 0
	v_add_f32_e32 v61, 1.0, v61
	v_rcp_f32_e32 v61, v61
	s_nop 0
	v_mul_f32_e32 v52, v52, v61
	v_mul_f32_e32 v61, v57, v57
	v_fmamk_f32 v61, v61, 0xbdd2d3e8, v201
	v_mul_f32_e32 v61, v57, v61
	v_exp_f32_e32 v61, v61
	s_nop 0
	v_add_f32_e32 v61, 1.0, v61
	v_rcp_f32_e32 v61, v61
	s_nop 0
	v_mul_f32_e32 v74, v57, v61
	v_mul_f32_e32 v57, v53, v53
	v_fmamk_f32 v57, v57, 0xbdd2d3e8, v201
	v_mul_f32_e32 v57, v53, v57
	v_exp_f32_e32 v57, v57
	v_cvt_pk_bf16_f32 v82, v56, v74
	s_nop 0
	v_add_f32_e32 v57, 1.0, v57
	v_rcp_f32_e32 v57, v57
	s_nop 0
	v_mul_f32_e32 v76, v53, v57
	v_mul_f32_e32 v53, v58, v58
	v_fmamk_f32 v53, v53, 0xbdd2d3e8, v201
	v_mul_f32_e32 v53, v58, v53
	v_exp_f32_e32 v53, v53
	s_nop 0
	v_add_f32_e32 v53, 1.0, v53
	v_rcp_f32_e32 v53, v53
	s_nop 0
	v_mul_f32_e32 v58, v58, v53
	v_mul_f32_e32 v53, v54, v54
	v_fmamk_f32 v53, v53, 0xbdd2d3e8, v201
	v_mul_f32_e32 v53, v54, v53
	v_exp_f32_e32 v53, v53
	s_nop 0
	v_add_f32_e32 v53, 1.0, v53
	v_rcp_f32_e32 v53, v53
	s_nop 0
	v_mul_f32_e32 v54, v54, v53
	v_mul_f32_e32 v53, v59, v59
	v_fmamk_f32 v53, v53, 0xbdd2d3e8, v201
	v_mul_f32_e32 v53, v59, v53
	v_exp_f32_e32 v53, v53
	s_nop 0
	v_add_f32_e32 v53, 1.0, v53
	v_rcp_f32_e32 v53, v53
	s_nop 0
	v_mul_f32_e32 v78, v59, v53
	v_mul_f32_e32 v53, v55, v55
	v_fmamk_f32 v53, v53, 0xbdd2d3e8, v201
	v_mul_f32_e32 v53, v55, v53
	v_exp_f32_e32 v53, v53
	v_cvt_pk_bf16_f32 v83, v58, v78
	v_cvt_pk_bf16_f32 v84, v52, v76
	s_nop 0
	v_add_f32_e32 v53, 1.0, v53
	v_rcp_f32_e32 v53, v53
	s_nop 0
	v_mul_f32_e32 v80, v55, v53
	v_add_u32_e32 v53, 0x40100, v146
	v_cvt_pk_bf16_f32 v85, v54, v80
	global_store_dwordx4 v53, v[82:85], s[6:7] sc0 sc1
	s_cbranch_vccnz .Lwt_BB0_599
	s_nop 0
	v_mov_b32_e32 v84, v3
	v_mov_b32_e32 v85, v65
	v_pk_mul_f32 v[82:83], v[64:65], v[64:65]
	v_pk_add_f32 v[84:85], v[64:65], v[84:85]
	v_pk_mov_b32 v[64:65], v[64:65], v[82:83] op_sel:[1,0]
	v_mov_b32_e32 v85, v83
	v_mul_f32_e32 v67, v66, v66
	v_pk_add_f32 v[64:65], v[64:65], v[84:85]
	v_mul_f32_e32 v71, v70, v70
	v_pk_add_f32 v[64:65], v[66:67], v[64:65]
	v_mul_f32_e32 v61, v60, v60
	v_pk_add_f32 v[64:65], v[70:71], v[64:65]
	v_mul_f32_e32 v69, v68, v68
	v_pk_add_f32 v[60:61], v[60:61], v[64:65]
	v_mul_f32_e32 v63, v62, v62
	v_pk_add_f32 v[60:61], v[68:69], v[60:61]
	v_mul_f32_e32 v73, v72, v72
	v_pk_add_f32 v[60:61], v[62:63], v[60:61]
	v_mul_f32_e32 v57, v56, v56
	v_pk_add_f32 v[60:61], v[72:73], v[60:61]
	v_mul_f32_e32 v75, v74, v74
	v_pk_add_f32 v[56:57], v[56:57], v[60:61]
	v_mul_f32_e32 v59, v58, v58
	v_pk_add_f32 v[56:57], v[74:75], v[56:57]
	v_mul_f32_e32 v79, v78, v78
	v_pk_add_f32 v[56:57], v[58:59], v[56:57]
	v_mul_f32_e32 v53, v52, v52
	v_and_b32_e32 v63, 64, v204
	v_pk_add_f32 v[56:57], v[78:79], v[56:57]
	v_mul_f32_e32 v77, v76, v76
	v_xor_b32_e32 v62, 16, v204
	v_add_u32_e32 v63, 64, v63
	v_pk_add_f32 v[52:53], v[52:53], v[56:57]
	v_mul_f32_e32 v55, v54, v54
	v_cmp_lt_i32_e32 vcc, v62, v63
	v_pk_add_f32 v[52:53], v[76:77], v[52:53]
	v_mul_f32_e32 v81, v80, v80
	v_cndmask_b32_e32 v62, v204, v62, vcc
	v_pk_add_f32 v[52:53], v[54:55], v[52:53]
	v_lshlrev_b32_e32 v62, 2, v62
	v_pk_add_f32 v[52:53], v[80:81], v[52:53]
	ds_bpermute_b32 v54, v62, v52
	ds_bpermute_b32 v55, v62, v53
	v_xor_b32_e32 v56, 32, v204
	v_cmp_lt_i32_e32 vcc, v56, v63
	s_waitcnt lgkmcnt(0)
	v_pk_add_f32 v[52:53], v[52:53], v[54:55]
	v_cndmask_b32_e32 v56, v204, v56, vcc
	v_lshlrev_b32_e32 v56, 2, v56
	ds_bpermute_b32 v54, v56, v52
	ds_bpermute_b32 v55, v56, v53
	s_and_saveexec_b64 s[8:9], s[40:41]
	s_cbranch_execz .Lwt_BB0_598
	v_lshl_add_u64 v[56:57], s[66:67], 0, v[2:3]
	s_waitcnt lgkmcnt(0)
	v_pk_add_f32 v[52:53], v[52:53], v[54:55]
	v_add_co_u32_e32 v54, vcc, 0x4000, v56
	s_nop 1
	v_addc_co_u32_e32 v55, vcc, 0, v57, vcc
	global_store_dwordx2 v[54:55], v[52:53], off sc0 sc1

.Lwt_BB0_599:
	v_mul_f32_e32 v53, v44, v44
	v_fmamk_f32 v53, v53, 0xbdd2d3e8, v201
	v_mul_f32_e32 v53, v44, v53
	v_exp_f32_e32 v53, v53
	v_mul_f32_e32 v52, v48, v48
	v_fmamk_f32 v52, v52, 0xbdd2d3e8, v201
	v_mul_f32_e32 v52, v48, v52
	v_add_f32_e32 v53, 1.0, v53
	v_rcp_f32_e32 v53, v53
	v_exp_f32_e32 v52, v52
	s_waitcnt lgkmcnt(0)
	v_add_u32_e32 v55, 0x48000, v146
	v_mul_f32_e32 v44, v44, v53
	v_mul_f32_e32 v53, v49, v49
	v_fmamk_f32 v53, v53, 0xbdd2d3e8, v201
	v_mul_f32_e32 v53, v49, v53
	v_exp_f32_e32 v53, v53
	v_add_f32_e32 v52, 1.0, v52
	v_rcp_f32_e32 v52, v52
	s_and_b64 vcc, exec, s[44:45]
	v_add_f32_e32 v53, 1.0, v53
	v_rcp_f32_e32 v53, v53
	s_nop 0
	v_pk_mul_f32 v[48:49], v[48:49], v[52:53]
	v_mul_f32_e32 v52, v45, v45
	v_fmamk_f32 v52, v52, 0xbdd2d3e8, v201
	v_mul_f32_e32 v52, v45, v52
	v_exp_f32_e32 v52, v52
	v_cvt_pk_bf16_f32 v58, v48, v49
	s_nop 0
	v_add_f32_e32 v52, 1.0, v52
	v_rcp_f32_e32 v52, v52
	s_nop 0
	v_mul_f32_e32 v52, v45, v52
	v_mul_f32_e32 v45, v50, v50
	v_fmamk_f32 v45, v45, 0xbdd2d3e8, v201
	v_mul_f32_e32 v45, v50, v45
	v_exp_f32_e32 v45, v45
	s_nop 0
	v_add_f32_e32 v45, 1.0, v45
	v_rcp_f32_e32 v45, v45
	s_nop 0
	v_mul_f32_e32 v50, v50, v45
	v_mul_f32_e32 v45, v46, v46
	v_fmamk_f32 v45, v45, 0xbdd2d3e8, v201
	v_mul_f32_e32 v45, v46, v45
	v_exp_f32_e32 v45, v45
	s_nop 0
	v_add_f32_e32 v45, 1.0, v45
	v_rcp_f32_e32 v45, v45
	s_nop 0
	v_mul_f32_e32 v46, v46, v45
	v_mul_f32_e32 v45, v51, v51
	v_fmamk_f32 v45, v45, 0xbdd2d3e8, v201
	v_mul_f32_e32 v45, v51, v45
	v_exp_f32_e32 v45, v45
	s_nop 0
	v_add_f32_e32 v45, 1.0, v45
	v_rcp_f32_e32 v45, v45
	s_nop 0
	v_mul_f32_e32 v54, v51, v45
	v_mul_f32_e32 v45, v47, v47
	v_fmamk_f32 v45, v45, 0xbdd2d3e8, v201
	v_mul_f32_e32 v45, v47, v45
	v_exp_f32_e32 v45, v45
	v_cvt_pk_bf16_f32 v59, v50, v54
	v_cvt_pk_bf16_f32 v60, v44, v52
	s_nop 0
	v_add_f32_e32 v45, 1.0, v45
	v_rcp_f32_e32 v45, v45
	s_nop 0
	v_mul_f32_e32 v56, v47, v45
	v_mul_f32_e32 v45, v40, v40
	v_fmamk_f32 v45, v45, 0xbdd2d3e8, v201
	v_mul_f32_e32 v45, v40, v45
	v_exp_f32_e32 v45, v45
	v_cvt_pk_bf16_f32 v61, v46, v56
	global_store_dwordx4 v55, v[58:61], s[6:7] sc0 sc1
	v_add_f32_e32 v45, 1.0, v45
	v_rcp_f32_e32 v45, v45
	s_nop 0
	v_mul_f32_e32 v40, v40, v45
	v_mul_f32_e32 v45, v36, v36
	v_fmamk_f32 v45, v45, 0xbdd2d3e8, v201
	v_mul_f32_e32 v45, v36, v45
	v_exp_f32_e32 v45, v45
	s_nop 0
	v_add_f32_e32 v45, 1.0, v45
	v_rcp_f32_e32 v45, v45
	s_nop 0
	v_mul_f32_e32 v36, v36, v45
	v_mul_f32_e32 v45, v41, v41
	v_fmamk_f32 v45, v45, 0xbdd2d3e8, v201
	v_mul_f32_e32 v45, v41, v45
	v_exp_f32_e32 v45, v45
	s_nop 0
	v_add_f32_e32 v45, 1.0, v45
	v_rcp_f32_e32 v45, v45
	s_nop 0
	v_mul_f32_e32 v58, v41, v45
	v_mul_f32_e32 v41, v37, v37
	v_fmamk_f32 v41, v41, 0xbdd2d3e8, v201
	v_mul_f32_e32 v41, v37, v41
	v_exp_f32_e32 v41, v41
	v_cvt_pk_bf16_f32 v66, v40, v58
	s_nop 0
	v_add_f32_e32 v41, 1.0, v41
	v_rcp_f32_e32 v41, v41
	s_nop 0
	v_mul_f32_e32 v60, v37, v41
	v_mul_f32_e32 v37, v42, v42
	v_fmamk_f32 v37, v37, 0xbdd2d3e8, v201
	v_mul_f32_e32 v37, v42, v37
	v_exp_f32_e32 v37, v37
	s_nop 0
	v_add_f32_e32 v37, 1.0, v37
	v_rcp_f32_e32 v37, v37
	s_nop 0
	v_mul_f32_e32 v42, v42, v37
	v_mul_f32_e32 v37, v38, v38
	v_fmamk_f32 v37, v37, 0xbdd2d3e8, v201
	v_mul_f32_e32 v37, v38, v37
	v_exp_f32_e32 v37, v37
	s_nop 0
	v_add_f32_e32 v37, 1.0, v37
	v_rcp_f32_e32 v37, v37
	s_nop 0
	v_mul_f32_e32 v38, v38, v37
	v_mul_f32_e32 v37, v43, v43
	v_fmamk_f32 v37, v37, 0xbdd2d3e8, v201
	v_mul_f32_e32 v37, v43, v37
	v_exp_f32_e32 v37, v37
	s_nop 0
	v_add_f32_e32 v37, 1.0, v37
	v_rcp_f32_e32 v37, v37
	s_nop 0
	v_mul_f32_e32 v62, v43, v37
	v_mul_f32_e32 v37, v39, v39
	v_fmamk_f32 v37, v37, 0xbdd2d3e8, v201
	v_mul_f32_e32 v37, v39, v37
	v_exp_f32_e32 v37, v37
	v_cvt_pk_bf16_f32 v67, v42, v62
	v_cvt_pk_bf16_f32 v68, v36, v60
	s_nop 0
	v_add_f32_e32 v37, 1.0, v37
	v_rcp_f32_e32 v37, v37
	s_nop 0
	v_mul_f32_e32 v64, v39, v37
	v_add_u32_e32 v37, 0x48100, v146
	v_cvt_pk_bf16_f32 v69, v38, v64
	global_store_dwordx4 v37, v[66:69], s[6:7] sc0 sc1
	s_cbranch_vccnz .Lwt_BB0_603
	s_nop 0
	v_mov_b32_e32 v68, v3
	v_mov_b32_e32 v69, v49
	v_pk_mul_f32 v[66:67], v[48:49], v[48:49]
	v_pk_add_f32 v[68:69], v[48:49], v[68:69]
	v_pk_mov_b32 v[48:49], v[48:49], v[66:67] op_sel:[1,0]
	v_mov_b32_e32 v69, v67
	v_mul_f32_e32 v51, v50, v50
	v_pk_add_f32 v[48:49], v[48:49], v[68:69]
	v_mul_f32_e32 v55, v54, v54
	v_pk_add_f32 v[48:49], v[50:51], v[48:49]
	v_mul_f32_e32 v45, v44, v44
	v_pk_add_f32 v[48:49], v[54:55], v[48:49]
	v_mul_f32_e32 v53, v52, v52
	v_pk_add_f32 v[44:45], v[44:45], v[48:49]
	v_mul_f32_e32 v47, v46, v46
	v_pk_add_f32 v[44:45], v[52:53], v[44:45]
	v_mul_f32_e32 v57, v56, v56
	v_pk_add_f32 v[44:45], v[46:47], v[44:45]
	v_mul_f32_e32 v41, v40, v40
	v_pk_add_f32 v[44:45], v[56:57], v[44:45]
	v_mul_f32_e32 v59, v58, v58
	v_pk_add_f32 v[40:41], v[40:41], v[44:45]
	v_mul_f32_e32 v43, v42, v42
	v_pk_add_f32 v[40:41], v[58:59], v[40:41]
	v_mul_f32_e32 v63, v62, v62
	v_pk_add_f32 v[40:41], v[42:43], v[40:41]
	v_mul_f32_e32 v37, v36, v36
	v_and_b32_e32 v47, 64, v204
	v_pk_add_f32 v[40:41], v[62:63], v[40:41]
	v_mul_f32_e32 v61, v60, v60
	v_xor_b32_e32 v46, 16, v204
	v_add_u32_e32 v47, 64, v47
	v_pk_add_f32 v[36:37], v[36:37], v[40:41]
	v_mul_f32_e32 v39, v38, v38
	v_cmp_lt_i32_e32 vcc, v46, v47
	v_pk_add_f32 v[36:37], v[60:61], v[36:37]
	v_mul_f32_e32 v65, v64, v64
	v_cndmask_b32_e32 v46, v204, v46, vcc
	v_pk_add_f32 v[36:37], v[38:39], v[36:37]
	v_lshlrev_b32_e32 v46, 2, v46
	v_pk_add_f32 v[36:37], v[64:65], v[36:37]
	ds_bpermute_b32 v38, v46, v36
	ds_bpermute_b32 v39, v46, v37
	v_xor_b32_e32 v40, 32, v204
	v_cmp_lt_i32_e32 vcc, v40, v47
	s_waitcnt lgkmcnt(0)
	v_pk_add_f32 v[36:37], v[36:37], v[38:39]
	v_cndmask_b32_e32 v40, v204, v40, vcc
	v_lshlrev_b32_e32 v40, 2, v40
	ds_bpermute_b32 v38, v40, v36
	ds_bpermute_b32 v39, v40, v37
	s_and_saveexec_b64 s[8:9], s[40:41]
	s_cbranch_execz .Lwt_BB0_602
	v_lshl_add_u64 v[40:41], s[66:67], 0, v[2:3]
	s_waitcnt lgkmcnt(0)
	v_pk_add_f32 v[36:37], v[36:37], v[38:39]
	v_add_co_u32_e32 v38, vcc, 0x4000, v40
	s_nop 1
	v_addc_co_u32_e32 v39, vcc, 0, v41, vcc
	global_store_dwordx2 v[38:39], v[36:37], off offset:2048 sc0 sc1

.Lwt_BB0_603:
	v_mul_f32_e32 v37, v28, v28
	v_fmamk_f32 v37, v37, 0xbdd2d3e8, v201
	v_mul_f32_e32 v37, v28, v37
	v_exp_f32_e32 v37, v37
	v_mul_f32_e32 v36, v32, v32
	v_fmamk_f32 v36, v36, 0xbdd2d3e8, v201
	v_mul_f32_e32 v36, v32, v36
	v_add_f32_e32 v37, 1.0, v37
	v_rcp_f32_e32 v37, v37
	v_exp_f32_e32 v36, v36
	s_waitcnt lgkmcnt(0)
	v_add_u32_e32 v39, 0x50000, v146
	v_mul_f32_e32 v28, v28, v37
	v_mul_f32_e32 v37, v33, v33
	v_fmamk_f32 v37, v37, 0xbdd2d3e8, v201
	v_mul_f32_e32 v37, v33, v37
	v_exp_f32_e32 v37, v37
	v_add_f32_e32 v36, 1.0, v36
	v_rcp_f32_e32 v36, v36
	s_and_b64 vcc, exec, s[44:45]
	v_add_f32_e32 v37, 1.0, v37
	v_rcp_f32_e32 v37, v37
	s_nop 0
	v_pk_mul_f32 v[32:33], v[32:33], v[36:37]
	v_mul_f32_e32 v36, v29, v29
	v_fmamk_f32 v36, v36, 0xbdd2d3e8, v201
	v_mul_f32_e32 v36, v29, v36
	v_exp_f32_e32 v36, v36
	v_cvt_pk_bf16_f32 v42, v32, v33
	s_nop 0
	v_add_f32_e32 v36, 1.0, v36
	v_rcp_f32_e32 v36, v36
	s_nop 0
	v_mul_f32_e32 v36, v29, v36
	v_mul_f32_e32 v29, v34, v34
	v_fmamk_f32 v29, v29, 0xbdd2d3e8, v201
	v_mul_f32_e32 v29, v34, v29
	v_exp_f32_e32 v29, v29
	s_nop 0
	v_add_f32_e32 v29, 1.0, v29
	v_rcp_f32_e32 v29, v29
	s_nop 0
	v_mul_f32_e32 v34, v34, v29
	v_mul_f32_e32 v29, v30, v30
	v_fmamk_f32 v29, v29, 0xbdd2d3e8, v201
	v_mul_f32_e32 v29, v30, v29
	v_exp_f32_e32 v29, v29
	s_nop 0
	v_add_f32_e32 v29, 1.0, v29
	v_rcp_f32_e32 v29, v29
	s_nop 0
	v_mul_f32_e32 v30, v30, v29
	v_mul_f32_e32 v29, v35, v35
	v_fmamk_f32 v29, v29, 0xbdd2d3e8, v201
	v_mul_f32_e32 v29, v35, v29
	v_exp_f32_e32 v29, v29
	s_nop 0
	v_add_f32_e32 v29, 1.0, v29
	v_rcp_f32_e32 v29, v29
	s_nop 0
	v_mul_f32_e32 v38, v35, v29
	v_mul_f32_e32 v29, v31, v31
	v_fmamk_f32 v29, v29, 0xbdd2d3e8, v201
	v_mul_f32_e32 v29, v31, v29
	v_exp_f32_e32 v29, v29
	v_cvt_pk_bf16_f32 v43, v34, v38
	v_cvt_pk_bf16_f32 v44, v28, v36
	s_nop 0
	v_add_f32_e32 v29, 1.0, v29
	v_rcp_f32_e32 v29, v29
	s_nop 0
	v_mul_f32_e32 v40, v31, v29
	v_mul_f32_e32 v29, v24, v24
	v_fmamk_f32 v29, v29, 0xbdd2d3e8, v201
	v_mul_f32_e32 v29, v24, v29
	v_exp_f32_e32 v29, v29
	v_cvt_pk_bf16_f32 v45, v30, v40
	global_store_dwordx4 v39, v[42:45], s[6:7] sc0 sc1
	v_add_f32_e32 v29, 1.0, v29
	v_rcp_f32_e32 v29, v29
	s_nop 0
	v_mul_f32_e32 v24, v24, v29
	v_mul_f32_e32 v29, v20, v20
	v_fmamk_f32 v29, v29, 0xbdd2d3e8, v201
	v_mul_f32_e32 v29, v20, v29
	v_exp_f32_e32 v29, v29
	s_nop 0
	v_add_f32_e32 v29, 1.0, v29
	v_rcp_f32_e32 v29, v29
	s_nop 0
	v_mul_f32_e32 v20, v20, v29
	v_mul_f32_e32 v29, v25, v25
	v_fmamk_f32 v29, v29, 0xbdd2d3e8, v201
	v_mul_f32_e32 v29, v25, v29
	v_exp_f32_e32 v29, v29
	s_nop 0
	v_add_f32_e32 v29, 1.0, v29
	v_rcp_f32_e32 v29, v29
	s_nop 0
	v_mul_f32_e32 v42, v25, v29
	v_mul_f32_e32 v25, v21, v21
	v_fmamk_f32 v25, v25, 0xbdd2d3e8, v201
	v_mul_f32_e32 v25, v21, v25
	v_exp_f32_e32 v25, v25
	v_cvt_pk_bf16_f32 v50, v24, v42
	s_nop 0
	v_add_f32_e32 v25, 1.0, v25
	v_rcp_f32_e32 v25, v25
	s_nop 0
	v_mul_f32_e32 v44, v21, v25
	v_mul_f32_e32 v21, v26, v26
	v_fmamk_f32 v21, v21, 0xbdd2d3e8, v201
	v_mul_f32_e32 v21, v26, v21
	v_exp_f32_e32 v21, v21
	s_nop 0
	v_add_f32_e32 v21, 1.0, v21
	v_rcp_f32_e32 v21, v21
	s_nop 0
	v_mul_f32_e32 v26, v26, v21
	v_mul_f32_e32 v21, v22, v22
	v_fmamk_f32 v21, v21, 0xbdd2d3e8, v201
	v_mul_f32_e32 v21, v22, v21
	v_exp_f32_e32 v21, v21
	s_nop 0
	v_add_f32_e32 v21, 1.0, v21
	v_rcp_f32_e32 v21, v21
	s_nop 0
	v_mul_f32_e32 v22, v22, v21
	v_mul_f32_e32 v21, v27, v27
	v_fmamk_f32 v21, v21, 0xbdd2d3e8, v201
	v_mul_f32_e32 v21, v27, v21
	v_exp_f32_e32 v21, v21
	s_nop 0
	v_add_f32_e32 v21, 1.0, v21
	v_rcp_f32_e32 v21, v21
	s_nop 0
	v_mul_f32_e32 v46, v27, v21
	v_mul_f32_e32 v21, v23, v23
	v_fmamk_f32 v21, v21, 0xbdd2d3e8, v201
	v_mul_f32_e32 v21, v23, v21
	v_exp_f32_e32 v21, v21
	v_cvt_pk_bf16_f32 v51, v26, v46
	v_cvt_pk_bf16_f32 v52, v20, v44
	s_nop 0
	v_add_f32_e32 v21, 1.0, v21
	v_rcp_f32_e32 v21, v21
	s_nop 0
	v_mul_f32_e32 v48, v23, v21
	v_add_u32_e32 v21, 0x50100, v146
	v_cvt_pk_bf16_f32 v53, v22, v48
	global_store_dwordx4 v21, v[50:53], s[6:7] sc0 sc1
	s_cbranch_vccnz .Lwt_BB0_607
	s_nop 0
	v_mov_b32_e32 v52, v3
	v_mov_b32_e32 v53, v33
	v_pk_mul_f32 v[50:51], v[32:33], v[32:33]
	v_pk_add_f32 v[52:53], v[32:33], v[52:53]
	v_pk_mov_b32 v[32:33], v[32:33], v[50:51] op_sel:[1,0]
	v_mov_b32_e32 v53, v51
	v_mul_f32_e32 v35, v34, v34
	v_pk_add_f32 v[32:33], v[32:33], v[52:53]
	v_mul_f32_e32 v39, v38, v38
	v_pk_add_f32 v[32:33], v[34:35], v[32:33]
	v_mul_f32_e32 v29, v28, v28
	v_pk_add_f32 v[32:33], v[38:39], v[32:33]
	v_mul_f32_e32 v37, v36, v36
	v_pk_add_f32 v[28:29], v[28:29], v[32:33]
	v_mul_f32_e32 v31, v30, v30
	v_pk_add_f32 v[28:29], v[36:37], v[28:29]
	v_mul_f32_e32 v41, v40, v40
	v_pk_add_f32 v[28:29], v[30:31], v[28:29]
	v_mul_f32_e32 v25, v24, v24
	v_pk_add_f32 v[28:29], v[40:41], v[28:29]
	v_mul_f32_e32 v43, v42, v42
	v_pk_add_f32 v[24:25], v[24:25], v[28:29]
	v_mul_f32_e32 v27, v26, v26
	v_pk_add_f32 v[24:25], v[42:43], v[24:25]
	v_mul_f32_e32 v47, v46, v46
	v_pk_add_f32 v[24:25], v[26:27], v[24:25]
	v_mul_f32_e32 v21, v20, v20
	v_and_b32_e32 v31, 64, v204
	v_pk_add_f32 v[24:25], v[46:47], v[24:25]
	v_mul_f32_e32 v45, v44, v44
	v_xor_b32_e32 v30, 16, v204
	v_add_u32_e32 v31, 64, v31
	v_pk_add_f32 v[20:21], v[20:21], v[24:25]
	v_mul_f32_e32 v23, v22, v22
	v_cmp_lt_i32_e32 vcc, v30, v31
	v_pk_add_f32 v[20:21], v[44:45], v[20:21]
	v_mul_f32_e32 v49, v48, v48
	v_cndmask_b32_e32 v30, v204, v30, vcc
	v_pk_add_f32 v[20:21], v[22:23], v[20:21]
	v_lshlrev_b32_e32 v30, 2, v30
	v_pk_add_f32 v[20:21], v[48:49], v[20:21]
	ds_bpermute_b32 v22, v30, v20
	ds_bpermute_b32 v23, v30, v21
	v_xor_b32_e32 v24, 32, v204
	v_cmp_lt_i32_e32 vcc, v24, v31
	s_waitcnt lgkmcnt(0)
	v_pk_add_f32 v[20:21], v[20:21], v[22:23]
	v_cndmask_b32_e32 v24, v204, v24, vcc
	v_lshlrev_b32_e32 v24, 2, v24
	ds_bpermute_b32 v22, v24, v20
	ds_bpermute_b32 v23, v24, v21
	s_and_saveexec_b64 s[8:9], s[40:41]
	s_cbranch_execz .Lwt_BB0_606
	v_lshl_add_u64 v[24:25], s[66:67], 0, v[2:3]
	s_waitcnt lgkmcnt(0)
	v_pk_add_f32 v[20:21], v[20:21], v[22:23]
	v_add_co_u32_e32 v22, vcc, 0x5000, v24
	s_nop 1
	v_addc_co_u32_e32 v23, vcc, 0, v25, vcc
	global_store_dwordx2 v[22:23], v[20:21], off sc0 sc1

.Lwt_BB0_607:
	v_mul_f32_e32 v21, v12, v12
	v_fmamk_f32 v21, v21, 0xbdd2d3e8, v201
	v_mul_f32_e32 v21, v12, v21
	v_exp_f32_e32 v21, v21
	v_mul_f32_e32 v20, v16, v16
	v_fmamk_f32 v20, v20, 0xbdd2d3e8, v201
	v_mul_f32_e32 v20, v16, v20
	v_add_f32_e32 v21, 1.0, v21
	v_rcp_f32_e32 v21, v21
	v_exp_f32_e32 v20, v20
	s_waitcnt lgkmcnt(0)
	v_add_u32_e32 v23, 0x58000, v146
	v_mul_f32_e32 v12, v12, v21
	v_mul_f32_e32 v21, v17, v17
	v_fmamk_f32 v21, v21, 0xbdd2d3e8, v201
	v_mul_f32_e32 v21, v17, v21
	v_exp_f32_e32 v21, v21
	v_add_f32_e32 v20, 1.0, v20
	v_rcp_f32_e32 v20, v20
	s_and_b64 vcc, exec, s[44:45]
	v_add_f32_e32 v21, 1.0, v21
	v_rcp_f32_e32 v21, v21
	s_nop 0
	v_pk_mul_f32 v[16:17], v[16:17], v[20:21]
	v_mul_f32_e32 v20, v13, v13
	v_fmamk_f32 v20, v20, 0xbdd2d3e8, v201
	v_mul_f32_e32 v20, v13, v20
	v_exp_f32_e32 v20, v20
	v_cvt_pk_bf16_f32 v26, v16, v17
	s_nop 0
	v_add_f32_e32 v20, 1.0, v20
	v_rcp_f32_e32 v20, v20
	s_nop 0
	v_mul_f32_e32 v20, v13, v20
	v_mul_f32_e32 v13, v18, v18
	v_fmamk_f32 v13, v13, 0xbdd2d3e8, v201
	v_mul_f32_e32 v13, v18, v13
	v_exp_f32_e32 v13, v13
	s_nop 0
	v_add_f32_e32 v13, 1.0, v13
	v_rcp_f32_e32 v13, v13
	s_nop 0
	v_mul_f32_e32 v18, v18, v13
	v_mul_f32_e32 v13, v14, v14
	v_fmamk_f32 v13, v13, 0xbdd2d3e8, v201
	v_mul_f32_e32 v13, v14, v13
	v_exp_f32_e32 v13, v13
	s_nop 0
	v_add_f32_e32 v13, 1.0, v13
	v_rcp_f32_e32 v13, v13
	s_nop 0
	v_mul_f32_e32 v14, v14, v13
	v_mul_f32_e32 v13, v19, v19
	v_fmamk_f32 v13, v13, 0xbdd2d3e8, v201
	v_mul_f32_e32 v13, v19, v13
	v_exp_f32_e32 v13, v13
	s_nop 0
	v_add_f32_e32 v13, 1.0, v13
	v_rcp_f32_e32 v13, v13
	s_nop 0
	v_mul_f32_e32 v22, v19, v13
	v_mul_f32_e32 v13, v15, v15
	v_fmamk_f32 v13, v13, 0xbdd2d3e8, v201
	v_mul_f32_e32 v13, v15, v13
	v_exp_f32_e32 v13, v13
	v_cvt_pk_bf16_f32 v27, v18, v22
	v_cvt_pk_bf16_f32 v28, v12, v20
	s_nop 0
	v_add_f32_e32 v13, 1.0, v13
	v_rcp_f32_e32 v13, v13
	s_nop 0
	v_mul_f32_e32 v24, v15, v13
	v_mul_f32_e32 v13, v8, v8
	v_fmamk_f32 v13, v13, 0xbdd2d3e8, v201
	v_mul_f32_e32 v13, v8, v13
	v_exp_f32_e32 v13, v13
	v_cvt_pk_bf16_f32 v29, v14, v24
	global_store_dwordx4 v23, v[26:29], s[6:7] sc0 sc1
	v_add_f32_e32 v13, 1.0, v13
	v_rcp_f32_e32 v13, v13
	s_nop 0
	v_mul_f32_e32 v8, v8, v13
	v_mul_f32_e32 v13, v4, v4
	v_fmamk_f32 v13, v13, 0xbdd2d3e8, v201
	v_mul_f32_e32 v13, v4, v13
	v_exp_f32_e32 v13, v13
	s_nop 0
	v_add_f32_e32 v13, 1.0, v13
	v_rcp_f32_e32 v13, v13
	s_nop 0
	v_mul_f32_e32 v4, v4, v13
	v_mul_f32_e32 v13, v9, v9
	v_fmamk_f32 v13, v13, 0xbdd2d3e8, v201
	v_mul_f32_e32 v13, v9, v13
	v_exp_f32_e32 v13, v13
	s_nop 0
	v_add_f32_e32 v13, 1.0, v13
	v_rcp_f32_e32 v13, v13
	s_nop 0
	v_mul_f32_e32 v26, v9, v13
	v_mul_f32_e32 v9, v5, v5
	v_fmamk_f32 v9, v9, 0xbdd2d3e8, v201
	v_mul_f32_e32 v9, v5, v9
	v_exp_f32_e32 v9, v9
	v_cvt_pk_bf16_f32 v34, v8, v26
	s_nop 0
	v_add_f32_e32 v9, 1.0, v9
	v_rcp_f32_e32 v9, v9
	s_nop 0
	v_mul_f32_e32 v28, v5, v9
	v_mul_f32_e32 v5, v10, v10
	v_fmamk_f32 v5, v5, 0xbdd2d3e8, v201
	v_mul_f32_e32 v5, v10, v5
	v_exp_f32_e32 v5, v5
	s_nop 0
	v_add_f32_e32 v5, 1.0, v5
	v_rcp_f32_e32 v5, v5
	s_nop 0
	v_mul_f32_e32 v10, v10, v5
	v_mul_f32_e32 v5, v6, v6
	v_fmamk_f32 v5, v5, 0xbdd2d3e8, v201
	v_mul_f32_e32 v5, v6, v5
	v_exp_f32_e32 v5, v5
	s_nop 0
	v_add_f32_e32 v5, 1.0, v5
	v_rcp_f32_e32 v5, v5
	s_nop 0
	v_mul_f32_e32 v6, v6, v5
	v_mul_f32_e32 v5, v11, v11
	v_fmamk_f32 v5, v5, 0xbdd2d3e8, v201
	v_mul_f32_e32 v5, v11, v5
	v_exp_f32_e32 v5, v5
	s_nop 0
	v_add_f32_e32 v5, 1.0, v5
	v_rcp_f32_e32 v5, v5
	s_nop 0
	v_mul_f32_e32 v30, v11, v5
	v_mul_f32_e32 v5, v7, v7
	v_fmamk_f32 v5, v5, 0xbdd2d3e8, v201
	v_mul_f32_e32 v5, v7, v5
	v_exp_f32_e32 v5, v5
	v_cvt_pk_bf16_f32 v35, v10, v30
	v_cvt_pk_bf16_f32 v36, v4, v28
	s_nop 0
	v_add_f32_e32 v5, 1.0, v5
	v_rcp_f32_e32 v5, v5
	s_nop 0
	v_mul_f32_e32 v32, v7, v5
	v_add_u32_e32 v5, 0x58100, v146
	v_cvt_pk_bf16_f32 v37, v6, v32
	global_store_dwordx4 v5, v[34:37], s[6:7] sc0 sc1
	s_cbranch_vccnz .LBB0_611
	s_nop 0
	v_mov_b32_e32 v36, v3
	v_mov_b32_e32 v37, v17
	v_pk_mul_f32 v[34:35], v[16:17], v[16:17]
	v_pk_add_f32 v[36:37], v[16:17], v[36:37]
	v_pk_mov_b32 v[16:17], v[16:17], v[34:35] op_sel:[1,0]
	v_mov_b32_e32 v37, v35
	v_mul_f32_e32 v19, v18, v18
	v_pk_add_f32 v[16:17], v[16:17], v[36:37]
	v_mul_f32_e32 v23, v22, v22
	v_pk_add_f32 v[16:17], v[18:19], v[16:17]
	v_mul_f32_e32 v13, v12, v12
	v_pk_add_f32 v[16:17], v[22:23], v[16:17]
	v_mul_f32_e32 v21, v20, v20
	v_pk_add_f32 v[12:13], v[12:13], v[16:17]
	v_mul_f32_e32 v15, v14, v14
	v_pk_add_f32 v[12:13], v[20:21], v[12:13]
	v_mul_f32_e32 v25, v24, v24
	v_pk_add_f32 v[12:13], v[14:15], v[12:13]
	v_mul_f32_e32 v9, v8, v8
	v_pk_add_f32 v[12:13], v[24:25], v[12:13]
	v_mul_f32_e32 v27, v26, v26
	v_pk_add_f32 v[8:9], v[8:9], v[12:13]
	v_mul_f32_e32 v11, v10, v10
	v_pk_add_f32 v[8:9], v[26:27], v[8:9]
	v_mul_f32_e32 v31, v30, v30
	v_pk_add_f32 v[8:9], v[10:11], v[8:9]
	v_mul_f32_e32 v5, v4, v4
	v_and_b32_e32 v15, 64, v204
	v_pk_add_f32 v[8:9], v[30:31], v[8:9]
	v_mul_f32_e32 v29, v28, v28
	v_xor_b32_e32 v14, 16, v204
	v_add_u32_e32 v15, 64, v15
	v_pk_add_f32 v[4:5], v[4:5], v[8:9]
	v_mul_f32_e32 v7, v6, v6
	v_cmp_lt_i32_e32 vcc, v14, v15
	v_pk_add_f32 v[4:5], v[28:29], v[4:5]
	v_mul_f32_e32 v33, v32, v32
	v_cndmask_b32_e32 v14, v204, v14, vcc
	v_pk_add_f32 v[4:5], v[6:7], v[4:5]
	v_lshlrev_b32_e32 v14, 2, v14
	v_pk_add_f32 v[4:5], v[32:33], v[4:5]
	ds_bpermute_b32 v6, v14, v4
	ds_bpermute_b32 v7, v14, v5
	v_xor_b32_e32 v8, 32, v204
	v_cmp_lt_i32_e32 vcc, v8, v15
	s_waitcnt lgkmcnt(0)
	v_pk_add_f32 v[4:5], v[4:5], v[6:7]
	v_cndmask_b32_e32 v8, v204, v8, vcc
	v_lshlrev_b32_e32 v8, 2, v8
	ds_bpermute_b32 v6, v8, v4
	ds_bpermute_b32 v7, v8, v5
	s_and_saveexec_b64 s[6:7], s[40:41]
	s_cbranch_execz .Lwt_BB0_610
	v_lshl_add_u64 v[8:9], s[66:67], 0, v[2:3]
	s_waitcnt lgkmcnt(0)
	v_pk_add_f32 v[4:5], v[4:5], v[6:7]
	v_add_co_u32_e32 v6, vcc, 0x5000, v8
	s_nop 1
	v_addc_co_u32_e32 v7, vcc, 0, v9, vcc
	global_store_dwordx2 v[6:7], v[4:5], off offset:2048 sc0 sc1
.Lwt_BB0_610:
	s_or_b64 exec, exec, s[6:7]
	s_branch .LBB0_611
